# strategy 4: one static priority raise for the trailing half-workgroup across the P1/P3/P4/P5 K-loops, per-segment s_setprio toggles removed, priority 0 in epilogues
# speedup vs baseline: 1.0141x; 1.0141x over previous
; #define PG8_STAGE(bufoff, gbase, voff) do { _Pragma("unroll") for (int _i = 0; _i < 2; ++_i) \
;         __builtin_amdgcn_global_load_lds((const unsigned*)((const char*)(gbase) + (voff)[_i]), (PG8_LAS unsigned*)(lds + (bufoff) + ldsw + _i * 8192), 16, 0, 0); } while (0)
; #define PG8_WAIT_V(n) asm volatile("s_waitcnt vmcnt(" #n ")" ::: "memory")
;     __host__ __device__ bool next(int i, Unit& u) const {
;         const long L = (long)i * G + c; if (L >= nwg) return false;
;         int wgid = (int)L; { const int q = nwg / NXCD, r = nwg % NXCD, xcd = wgid % NXCD, off = wgid / NXCD; wgid = (xcd < r ? xcd * (q + 1) : r * (q + 1) + (xcd - r) * q) + off; }
;         const int nig = WGM * nN, gid = wgid / nig, fm = gid * WGM, gsz = (nM - fm) < WGM ? (nM - fm) : WGM;
;         u.pm = fm + ((wgid % nig) % gsz); u.pn = (wgid % nig) / gsz; return true;
; template <class Epi, class Sched, bool ALIGN_EPI = false, bool SP2 = false>
; __device__ __forceinline__ void gemm_phase(PG8_LAS unsigned char* lds, const Gemm g, const Sched& S, const Epi& E) {
;     ...
;     for (int i = 0; i < 2; ++i) { int R, C; stage_rc(tid * 16 + i * 8192, R, C); const int Rb = Epi::PERM ? ((R & ~31) + perm32(R & 31)) : R;
;         voffA[i] = (unsigned)(R * K + C) * 2u; voffB[i] = (unsigned)(Rb * K + C) * 2u; }
;     const size_t kstep = (size_t)(BK * 2);
;     const size_t hstep = (size_t)HALF * K * 2;
;     const size_t tstep = 2 * hstep;
;     const unsigned ldsw = (unsigned)wid * 1024u;
;     const int aoff = lds_byte(wr * 64 + fr, fq * 8), boff = lds_byte(wc * 32 + fr, fq * 8);
;     ...
;     Unit cur, nxt; int ui = 0;
;     if (!S.next(0, cur)) return;
;     f32x4 acc[2][2][4][2];
; #pragma unroll
;     for (int a = 0; a < 2; ++a)
; #pragma unroll
;         for (int b = 0; b < 2; ++b)
; #pragma unroll
;             for (int m = 0; m < 4; ++m)
; #pragma unroll
;                 for (int n = 0; n < 2; ++n) acc[a][b][m][n] = (f32x4){0.f, 0.f, 0.f, 0.f};
;     bf16x8 At[4][2], B0[2][2], B1[2][2];
;     const char* cA = (const char*)g.A + (size_t)cur.pm * tstep; const char* cB = (const char*)g.Bt + (size_t)cur.pn * tstep;
;     S.a_ready(cur);
;     if constexpr (SP2) {
;         PG8_STAGE(PG8_SB(0, 0), cB, voffB); PG8_STAGE(PG8_SB(0, 1), cB + hstep, voffB); PG8_STAGE(PG8_SA(0, 0), cA, voffA); PG8_STAGE(PG8_SA(0, 1), cA + hstep, voffA);
;         if (wr == 1) PG8_BAR;
;         PG8_WAIT_V(2); PG8_BAR;
.LBB0_416:
	s_andn2_b64 vcc, exec, s[24:25]
	s_lshr_b32 s61, s45, 1
	v_writelane_b32 v250, s46, 27
	v_writelane_b32 v250, s45, 28
	s_cbranch_vccnz .LBB0_487
	s_and_b64 s[0:1], s[22:23], exec
	s_movk_i32 s0, 0x400
	s_cselect_b32 s49, s0, 0xa00
	s_lshr_b32 s26, s49, 1
	v_mov_b32_e32 v10, v204
	v_readlane_b32 s0, v252, 0
	s_cmp_ge_i32 s0, s26
	v_readfirstlane_b32 s27, v10
	s_cbranch_scc1 .LBB0_433
	v_lshlrev_b32_e32 v0, 4, v10
	s_waitcnt lgkmcnt(0)
	v_add_u32_e32 v1, 0x2000, v0
	s_waitcnt lgkmcnt(0)
	v_ashrrev_i32_e32 v2, 31, v1
	v_lshrrev_b32_e32 v2, 22, v2
	v_add_u32_e32 v2, v1, v2
	v_ashrrev_i32_e32 v8, 10, v2
	v_mul_i32_i24_e32 v2, 0x400, v8
	v_sub_u32_e32 v1, v1, v2
	v_lshrrev_b32_e32 v2, 4, v1
	v_bitop3_b32 v1, v2, v1, 32 bitop3:0x6c
	v_ashrrev_i32_e32 v2, 31, v1
	s_lshl_b32 s1, s45, 20
	v_lshrrev_b32_e32 v2, 26, v2
	s_mul_i32 s0, s61, 0x380000
	s_and_b32 s1, s1, 0x100000
	v_add_u32_e32 v2, v1, v2
	v_lshlrev_b32_e32 v3, 3, v8
	s_add_i32 s30, s0, s1
	v_ashrrev_i32_e32 v9, 6, v2
	v_and_b32_e32 v3, -16, v3
	s_lshl_b64 s[0:1], s[30:31], 1
	v_add_u32_e32 v3, v9, v3
	s_add_u32 s30, s64, s0
	v_and_b32_e32 v4, 3, v9
	s_mov_b32 s0, 0x1fffe0
	v_lshrrev_b32_e32 v5, 2, v3
	v_lshlrev_b32_e32 v6, 1, v3
	v_and_b32_e32 v2, 0xc0, v2
	v_and_or_b32 v4, v3, s0, v4
	v_and_b32_e32 v5, 4, v5
	v_and_b32_e32 v6, 24, v6
	v_sub_u32_e32 v1, v1, v2
	v_or3_b32 v4, v4, v5, v6
	v_lshlrev_b32_e32 v5, 5, v8
	v_ashrrev_i16_sdwa v1, v205, sext(v1) dst_sel:DWORD dst_unused:UNUSED_PAD src0_sel:DWORD src1_sel:BYTE_0
	v_and_b32_e32 v5, 32, v5
	v_bfe_i32 v11, v1, 0, 16
	v_add_lshl_u32 v1, v5, v11, 1
	v_lshl_add_u32 v128, v4, 11, v1
	v_lshl_add_u32 v130, v3, 11, v1
	v_bfe_i32 v1, v10, 27, 1
	v_lshrrev_b32_e32 v1, 22, v1
	v_add_u32_e32 v1, v0, v1
	v_and_b32_e32 v1, 0xfffffc00, v1
	v_sub_u32_e32 v0, v0, v1
	v_lshrrev_b32_e32 v1, 4, v0
	v_ashrrev_i32_e32 v2, 31, v10
	v_bitop3_b32 v0, v1, v0, 32 bitop3:0x6c
	v_lshrrev_b32_e32 v2, 26, v2
	v_ashrrev_i32_e32 v1, 31, v0
	v_add_u32_e32 v2, v10, v2
	v_lshrrev_b32_e32 v1, 26, v1
	v_ashrrev_i32_e32 v13, 6, v2
	v_add_u32_e32 v1, v0, v1
	v_lshlrev_b32_e32 v2, 3, v13
	v_ashrrev_i32_e32 v12, 6, v1
	v_and_b32_e32 v2, -16, v2
	v_writelane_b32 v250, s52, 29
	v_add_u32_e32 v2, v12, v2
	v_and_b32_e32 v3, 3, v12
	v_writelane_b32 v250, s53, 30
	s_addc_u32 s52, s65, s1
	s_ashr_i32 s23, s27, 6
	v_and_or_b32 v3, v2, s0, v3
	s_lshr_b32 s55, s49, 4
	v_readlane_b32 s0, v251, 34
	s_lshr_b32 s53, s49, 6
	s_ashr_i32 s29, s27, 8
	s_lshl_b32 s54, s23, 10
	s_or_b32 s22, s55, 1
	v_readlane_b32 s1, v251, 35
	s_and_b64 s[0:1], s[0:1], exec
	v_lshrrev_b32_e32 v4, 2, v2
	v_lshlrev_b32_e32 v5, 1, v2
	v_and_b32_e32 v1, 0xc0, v1
	s_cselect_b32 s0, s22, s55
	s_abs_i32 s59, s53
	v_and_b32_e32 v4, 4, v4
	v_and_b32_e32 v5, 24, v5
	v_sub_u32_e32 v0, v0, v1
	v_cvt_f32_u32_e32 v1, s59
	v_or3_b32 v3, v3, v4, v5
	v_lshlrev_b32_e32 v4, 5, v13
	v_ashrrev_i16_sdwa v0, v205, sext(v0) dst_sel:DWORD dst_unused:UNUSED_PAD src0_sel:DWORD src1_sel:BYTE_0
	v_and_b32_e32 v4, 32, v4
	v_bfe_i32 v14, v0, 0, 16
	v_add_lshl_u32 v0, v4, v14, 1
	v_lshl_add_u32 v138, v3, 11, v0
	v_lshl_add_u32 v132, v2, 11, v0
	v_rcp_iflag_f32_e32 v0, v1
	v_readlane_b32 s1, v251, 36
	s_mul_i32 s0, s0, s1
	v_readlane_b32 s1, v251, 37
	v_mul_f32_e32 v0, 0x4f7ffffe, v0
	v_cvt_u32_f32_e32 v0, v0
	s_sub_i32 s24, 0, s59
	v_writelane_b32 v250, s61, 31
	s_add_i32 s0, s0, s1
	v_readfirstlane_b32 s89, v0
	s_mul_i32 s24, s24, s89
	v_writelane_b32 v250, s22, 32
	s_ashr_i32 s1, s0, 31
	s_ashr_i32 s22, s53, 31
	s_mul_hi_u32 s24, s89, s24
	s_mov_b32 s45, s22
	s_xor_b32 s1, s1, s22
	s_abs_i32 s22, s0
	s_add_i32 s89, s89, s24
	s_mul_hi_u32 s24, s22, s89
	s_mul_i32 s25, s24, s59
	s_sub_i32 s22, s22, s25
	s_add_i32 s25, s24, 1
	s_sub_i32 s28, s22, s59
	s_cmp_ge_u32 s22, s59
	s_cselect_b32 s24, s25, s24
	s_cselect_b32 s22, s28, s22
	s_add_i32 s25, s24, 1
	s_cmp_ge_u32 s22, s59
	s_cselect_b32 s22, s25, s24
	s_xor_b32 s22, s22, s1
	s_sub_i32 s1, s22, s1
	s_lshl_b32 s22, s1, 2
	s_sub_i32 s24, 0x80, s22
	s_min_i32 s24, s24, 4
	s_sext_i32_i16 s25, s24
	v_cvt_f32_i32_e32 v0, s25
	s_mul_i32 s1, s1, s53
	s_sub_i32 s36, s0, s1
	v_cvt_f32_i32_e32 v1, s36
	v_rcp_iflag_f32_e32 v2, v0
	s_xor_b32 s0, s36, s25
	s_ashr_i32 s0, s0, 30
	s_or_b32 s25, s0, 1
	v_mul_f32_e32 v2, v1, v2
	v_trunc_f32_e32 v2, v2
	v_fma_f32 v1, -v2, v0, v1
	v_cvt_i32_f32_e32 v2, v2
	v_cmp_ge_f32_e64 s[0:1], |v1|, |v0|
	s_and_b64 s[0:1], s[0:1], exec
	s_cselect_b32 s0, s25, 0
	v_readfirstlane_b32 s1, v2
	s_add_i32 s28, s1, s0
	s_mul_i32 s0, s28, s24
	s_sub_i32 s0, s36, s0
	s_sext_i32_i16 s0, s0
	s_add_i32 s24, s22, s0
	s_ashr_i32 s25, s24, 31
	s_bfe_i64 s[36:37], s[28:29], 0x100000
	s_lshl_b64 s[0:1], s[24:25], 19
	s_lshl_b64 s[36:37], s[36:37], 19
	s_add_u32 s42, s30, s36
	s_addc_u32 s43, s52, s37
	s_add_i32 s48, s54, 0
	s_add_i32 m0, s48, 0x10000
	v_mov_b32_e32 v129, v139
	global_load_lds_dwordx4 v138, s[42:43]
	s_add_i32 m0, s48, 0x12000
	s_add_u32 s36, s42, 0x40000
	global_load_lds_dwordx4 v128, s[42:43]
	s_addc_u32 s37, s43, 0
	s_add_i32 m0, s48, 0x14000
	v_mov_b32_e32 v133, v139
	global_load_lds_dwordx4 v138, s[36:37]
	s_add_i32 m0, s48, 0x16000
	s_add_u32 s46, s72, s0
	s_addc_u32 s47, s73, s1
	s_add_i32 s0, s48, 0x2000
	global_load_lds_dwordx4 v128, s[36:37]
	s_mov_b32 m0, s48
	s_add_u32 s36, s46, 0x40000
	global_load_lds_dwordx4 v132, s[46:47]
	s_mov_b32 m0, s0
	s_addc_u32 s37, s47, 0
	s_add_i32 s1, s48, 0x4000
	global_load_lds_dwordx4 v130, s[46:47]
	s_mov_b32 m0, s1
	s_add_i32 s22, s48, 0x6000
	global_load_lds_dwordx4 v132, s[36:37]
	s_mov_b32 m0, s22
	s_cmp_eq_u32 s29, 1
	global_load_lds_dwordx4 v130, s[36:37]
	v_mov_b32_e32 v131, v139
	s_cselect_b64 s[36:37], -1, 0
	v_lshl_add_u64 v[4:5], s[42:43], 0, v[138:139]
	v_lshl_add_u64 v[2:3], s[42:43], 0, v[128:129]
	v_lshl_add_u64 v[0:1], s[46:47], 0, v[132:133]
	v_writelane_b32 v250, s36, 34
	s_cmp_lg_u32 s29, 1
	v_lshl_add_u64 v[6:7], s[46:47], 0, v[130:131]
	v_writelane_b32 v250, s37, 35
	s_cbranch_scc1 .LBB0_420
	s_setprio 1
	s_barrier

; #define PG8_STAGE(bufoff, gbase, voff) do { _Pragma("unroll") for (int _i = 0; _i < 2; ++_i) \
;         __builtin_amdgcn_global_load_lds((const unsigned*)((const char*)(gbase) + (voff)[_i]), (PG8_LAS unsigned*)(lds + (bufoff) + ldsw + _i * 8192), 16, 0, 0); } while (0)
; #define PG8_LDA(dst, b, h) do { _Pragma("unroll") for (int m = 0; m < 4; ++m) _Pragma("unroll") for (int k = 0; k < 2; ++k) dst[m][k] = *(const PG8_LAS bf16x8*)(lds + PG8_SA(b, h) + aoff + m * 2048 + k * 1024); } while (0)
; #define PG8_LDB(dst, b, h) do { _Pragma("unroll") for (int n = 0; n < 2; ++n) _Pragma("unroll") for (int k = 0; k < 2; ++k) dst[n][k] = *(const PG8_LAS bf16x8*)(lds + PG8_SB(b, h) + boff + n * 2048 + k * 1024); } while (0)
; #define PG8_MMA(ai, bj, At, Bt) do { __builtin_amdgcn_s_setprio(1); _Pragma("unroll") for (int m = 0; m < 4; ++m) _Pragma("unroll") for (int n = 0; n < 2; ++n) _Pragma("unroll") for (int k = 0; k < 2; ++k) \
;         acc[ai][bj][m][n] = __builtin_amdgcn_mfma_f32_16x16x32_bf16(Bt[n][k], At[m][k], acc[ai][bj][m][n], 0, 0, 0); __builtin_amdgcn_s_setprio(0); } while (0)
; #define PG8_WAIT_V(n) asm volatile("s_waitcnt vmcnt(" #n ")" ::: "memory")
; #define PG8_WAIT_L(n) asm volatile("s_waitcnt lgkmcnt(" #n ")" ::: "memory")
; #define PG8_BAR __builtin_amdgcn_s_barrier()
; #define PG8_SCHED __builtin_amdgcn_sched_barrier(0)
; template <class Epi, class Sched, bool ALIGN_EPI = false, bool SP2 = false>
; __device__ __forceinline__ void gemm_phase(PG8_LAS unsigned char* lds, const Gemm g, const Sched& S, const Epi& E) {
;     ...
;         for (int t = 0; t < nt; t += 2) {
;             const bool last = (t == nt - 2);
;             const char* a1 = cA + (size_t)(t + 1) * kstep;
;             const char* a2 = last ? nA : cA + (size_t)(t + 2) * kstep; const char* b2 = last ? nB : cB + (size_t)(t + 2) * kstep;
;             const char* a3 = a2 + kstep; const char* b3 = b2 + kstep;
;             if (last && has_next) S.a_ready(nxt);
;             if constexpr (SP2) {
;             PG8_LDB(B0, 0, 0); PG8_LDB(B1, 0, 1); PG8_SCHED; PG8_LDA(At, 0, 0); PG8_STAGE(PG8_SA(1, 1), a1 + hstep, voffA);
;             PG8_WAIT_V(8); PG8_WAIT_L(0); PG8_BAR; PG8_MMA(0, 0, At, B0); PG8_MMA(0, 1, At, B1); PG8_BAR; PG8_SCHED;
.LBB0_426:
	s_add_u32 s42, s26, 0xfffc0080
	s_addc_u32 s43, s27, -1
	s_add_i32 s76, 0, 0x10000
	s_cmp_eq_u32 s95, 12
	s_cselect_b32 s47, s41, s43
	s_cselect_b32 s46, s92, s42
	s_cselect_b32 s43, s39, s94
	s_cselect_b32 s42, s93, vcc_lo
	s_add_i32 s77, 0, 0x14000
	v_add_u32_e32 v168, s76, v157
	v_add_u32_e32 v184, s77, v157
	ds_read_b128 v[152:155], v168
	ds_read_b128 v[160:163], v168 offset:1024
	ds_read_b128 v[164:167], v168 offset:2048
	ds_read_b128 v[168:171], v168 offset:3072
	ds_read_b128 v[172:175], v184
	ds_read_b128 v[176:179], v184 offset:1024
	ds_read_b128 v[180:183], v184 offset:2048
	ds_read_b128 v[184:187], v184 offset:3072
	v_lshl_add_u64 v[224:225], s[26:27], 0, v[134:135]
	s_add_i32 m0, s48, 0xc000
	ds_read_b128 v[188:191], v159
	ds_read_b128 v[192:195], v159 offset:1024
	ds_read_b128 v[196:199], v159 offset:2048
	ds_read_b128 v[200:203], v159 offset:3072
	ds_read_b128 v[208:211], v159 offset:4096
	ds_read_b128 v[212:215], v159 offset:5120
	ds_read_b128 v[216:219], v159 offset:6144
	ds_read_b128 v[220:223], v159 offset:7168
	global_load_lds_dwordx4 v[224:225], off
	v_lshl_add_u64 v[224:225], s[26:27], 0, v[148:149]
	s_add_i32 m0, s48, 0xe000
	s_nop 0
	global_load_lds_dwordx4 v[224:225], off
	s_waitcnt vmcnt(8)
	s_waitcnt lgkmcnt(0)
	s_barrier
	s_waitcnt lgkmcnt(0)
	v_mfma_f32_16x16x32_bf16 v[124:127], v[152:155], v[188:191], v[124:127]
	v_mfma_f32_16x16x32_bf16 v[120:123], v[164:167], v[188:191], v[120:123]
	v_mfma_f32_16x16x32_bf16 v[108:111], v[152:155], v[196:199], v[108:111]
	v_mfma_f32_16x16x32_bf16 v[104:107], v[164:167], v[196:199], v[104:107]
	v_mfma_f32_16x16x32_bf16 v[92:95], v[152:155], v[208:211], v[92:95]
	v_mfma_f32_16x16x32_bf16 v[88:91], v[164:167], v[208:211], v[88:91]
	v_mfma_f32_16x16x32_bf16 v[76:79], v[152:155], v[216:219], v[76:79]
	v_mfma_f32_16x16x32_bf16 v[72:75], v[164:167], v[216:219], v[72:75]
	v_mfma_f32_16x16x32_bf16 v[124:127], v[160:163], v[192:195], v[124:127]
	v_mfma_f32_16x16x32_bf16 v[120:123], v[168:171], v[192:195], v[120:123]
	v_mfma_f32_16x16x32_bf16 v[108:111], v[160:163], v[200:203], v[108:111]
	v_mfma_f32_16x16x32_bf16 v[104:107], v[168:171], v[200:203], v[104:107]
	v_mfma_f32_16x16x32_bf16 v[92:95], v[160:163], v[212:215], v[92:95]
	v_mfma_f32_16x16x32_bf16 v[88:91], v[168:171], v[212:215], v[88:91]
	v_mfma_f32_16x16x32_bf16 v[76:79], v[160:163], v[220:223], v[76:79]
	v_mfma_f32_16x16x32_bf16 v[72:75], v[168:171], v[220:223], v[72:75]
	v_mfma_f32_16x16x32_bf16 v[116:119], v[172:175], v[188:191], v[116:119]
	v_mfma_f32_16x16x32_bf16 v[112:115], v[180:183], v[188:191], v[112:115]
	v_mfma_f32_16x16x32_bf16 v[100:103], v[172:175], v[196:199], v[100:103]
	v_mfma_f32_16x16x32_bf16 v[96:99], v[180:183], v[196:199], v[96:99]
	v_mfma_f32_16x16x32_bf16 v[84:87], v[172:175], v[208:211], v[84:87]
	v_mfma_f32_16x16x32_bf16 v[80:83], v[180:183], v[208:211], v[80:83]
	v_mfma_f32_16x16x32_bf16 v[68:71], v[172:175], v[216:219], v[68:71]
	v_mfma_f32_16x16x32_bf16 v[64:67], v[180:183], v[216:219], v[64:67]
	v_mfma_f32_16x16x32_bf16 v[116:119], v[176:179], v[192:195], v[116:119]
	v_mfma_f32_16x16x32_bf16 v[112:115], v[184:187], v[192:195], v[112:115]
	v_mfma_f32_16x16x32_bf16 v[100:103], v[176:179], v[200:203], v[100:103]
	v_mfma_f32_16x16x32_bf16 v[96:99], v[184:187], v[200:203], v[96:99]
	v_mfma_f32_16x16x32_bf16 v[84:87], v[176:179], v[212:215], v[84:87]
	v_mfma_f32_16x16x32_bf16 v[80:83], v[184:187], v[212:215], v[80:83]
	v_mfma_f32_16x16x32_bf16 v[68:71], v[176:179], v[220:223], v[68:71]
	v_mfma_f32_16x16x32_bf16 v[64:67], v[184:187], v[220:223], v[64:67]
	s_barrier
	s_add_i32 s76, s76, s54
	v_lshl_add_u64 v[224:225], s[42:43], 0, v[138:139]
	s_mov_b32 m0, s76
	ds_read_b128 v[188:191], v159 offset:16384
	ds_read_b128 v[192:195], v159 offset:17408
	ds_read_b128 v[196:199], v159 offset:18432
	ds_read_b128 v[200:203], v159 offset:19456
	ds_read_b128 v[208:211], v159 offset:20480
	ds_read_b128 v[212:215], v159 offset:21504
	ds_read_b128 v[216:219], v159 offset:22528
	ds_read_b128 v[220:223], v159 offset:23552
	global_load_lds_dwordx4 v[224:225], off
	s_add_i32 m0, s76, 0x2000
	s_add_u32 s96, s42, 0x40000
	v_lshl_add_u64 v[226:227], s[42:43], 0, v[128:129]
	s_addc_u32 s97, s43, 0
	s_add_i32 s76, s77, s54
	global_load_lds_dwordx4 v[226:227], off
	v_lshl_add_u64 v[228:229], s[96:97], 0, v[138:139]
	s_mov_b32 m0, s76
	v_lshl_add_u64 v[230:231], s[46:47], 0, v[130:131]
	global_load_lds_dwordx4 v[228:229], off
	v_lshl_add_u64 v[228:229], s[96:97], 0, v[128:129]
	s_add_i32 m0, s76, 0x2000
	s_nop 0
	global_load_lds_dwordx4 v[228:229], off
	v_lshl_add_u64 v[228:229], s[46:47], 0, v[132:133]
	s_mov_b32 m0, s48
	s_nop 0
	global_load_lds_dwordx4 v[228:229], off
	s_mov_b32 m0, s0
	s_nop 0
	global_load_lds_dwordx4 v[230:231], off
	s_waitcnt vmcnt(8)
	s_waitcnt lgkmcnt(0)
	s_barrier
; #define PG8_STAGE(bufoff, gbase, voff) do { _Pragma("unroll") for (int _i = 0; _i < 2; ++_i) \
;         __builtin_amdgcn_global_load_lds((const unsigned*)((const char*)(gbase) + (voff)[_i]), (PG8_LAS unsigned*)(lds + (bufoff) + ldsw + _i * 8192), 16, 0, 0); } while (0)
; #define PG8_LDA(dst, b, h) do { _Pragma("unroll") for (int m = 0; m < 4; ++m) _Pragma("unroll") for (int k = 0; k < 2; ++k) dst[m][k] = *(const PG8_LAS bf16x8*)(lds + PG8_SA(b, h) + aoff + m * 2048 + k * 1024); } while (0)
; #define PG8_LDB(dst, b, h) do { _Pragma("unroll") for (int n = 0; n < 2; ++n) _Pragma("unroll") for (int k = 0; k < 2; ++k) dst[n][k] = *(const PG8_LAS bf16x8*)(lds + PG8_SB(b, h) + boff + n * 2048 + k * 1024); } while (0)
; #define PG8_MMA(ai, bj, At, Bt) do { __builtin_amdgcn_s_setprio(1); _Pragma("unroll") for (int m = 0; m < 4; ++m) _Pragma("unroll") for (int n = 0; n < 2; ++n) _Pragma("unroll") for (int k = 0; k < 2; ++k) \
;         acc[ai][bj][m][n] = __builtin_amdgcn_mfma_f32_16x16x32_bf16(Bt[n][k], At[m][k], acc[ai][bj][m][n], 0, 0, 0); __builtin_amdgcn_s_setprio(0); } while (0)
; #define PG8_WAIT_V(n) asm volatile("s_waitcnt vmcnt(" #n ")" ::: "memory")
; #define PG8_WAIT_L(n) asm volatile("s_waitcnt lgkmcnt(" #n ")" ::: "memory")
; #define PG8_BAR __builtin_amdgcn_s_barrier()
; #define PG8_SCHED __builtin_amdgcn_sched_barrier(0)
; template <class Epi, class Sched, bool ALIGN_EPI = false, bool SP2 = false>
; __device__ __forceinline__ void gemm_phase(PG8_LAS unsigned char* lds, const Gemm g, const Sched& S, const Epi& E) {
;     ...
;             PG8_WAIT_V(8); PG8_WAIT_L(0); PG8_BAR; PG8_MMA(0, 0, At, B0); PG8_MMA(0, 1, At, B1); PG8_BAR; PG8_SCHED;
;             PG8_LDA(At, 0, 1); PG8_STAGE(PG8_SB(0, 0), b2, voffB); PG8_STAGE(PG8_SB(0, 1), b2 + hstep, voffB); PG8_STAGE(PG8_SA(0, 0), a2, voffA);
;             PG8_WAIT_V(8); PG8_WAIT_L(0); PG8_BAR; PG8_MMA(1, 0, At, B0); PG8_MMA(1, 1, At, B1); PG8_BAR; PG8_SCHED;
;             PG8_LDB(B0, 1, 0); PG8_LDB(B1, 1, 1); PG8_SCHED; PG8_LDA(At, 1, 0); PG8_STAGE(PG8_SA(0, 1), a2 + hstep, voffA);
;             PG8_WAIT_V(8); PG8_WAIT_L(0); PG8_BAR; PG8_MMA(0, 0, At, B0); PG8_MMA(0, 1, At, B1); PG8_BAR; PG8_SCHED;
	s_waitcnt lgkmcnt(0)
	v_mfma_f32_16x16x32_bf16 v[60:63], v[152:155], v[188:191], v[60:63]
	v_mfma_f32_16x16x32_bf16 v[56:59], v[164:167], v[188:191], v[56:59]
	v_mfma_f32_16x16x32_bf16 v[44:47], v[152:155], v[196:199], v[44:47]
	v_mfma_f32_16x16x32_bf16 v[40:43], v[164:167], v[196:199], v[40:43]
	v_mfma_f32_16x16x32_bf16 v[28:31], v[152:155], v[208:211], v[28:31]
	v_mfma_f32_16x16x32_bf16 v[24:27], v[164:167], v[208:211], v[24:27]
	v_mfma_f32_16x16x32_bf16 v[12:15], v[152:155], v[216:219], v[12:15]
	v_mfma_f32_16x16x32_bf16 v[8:11], v[164:167], v[216:219], v[8:11]
	v_mfma_f32_16x16x32_bf16 v[60:63], v[160:163], v[192:195], v[60:63]
	v_mfma_f32_16x16x32_bf16 v[56:59], v[168:171], v[192:195], v[56:59]
	v_mfma_f32_16x16x32_bf16 v[44:47], v[160:163], v[200:203], v[44:47]
	v_mfma_f32_16x16x32_bf16 v[40:43], v[168:171], v[200:203], v[40:43]
	v_mfma_f32_16x16x32_bf16 v[28:31], v[160:163], v[212:215], v[28:31]
	v_mfma_f32_16x16x32_bf16 v[24:27], v[168:171], v[212:215], v[24:27]
	v_mfma_f32_16x16x32_bf16 v[12:15], v[160:163], v[220:223], v[12:15]
	v_mfma_f32_16x16x32_bf16 v[8:11], v[168:171], v[220:223], v[8:11]
	v_mfma_f32_16x16x32_bf16 v[52:55], v[172:175], v[188:191], v[52:55]
	v_mfma_f32_16x16x32_bf16 v[48:51], v[180:183], v[188:191], v[48:51]
	v_mfma_f32_16x16x32_bf16 v[36:39], v[172:175], v[196:199], v[36:39]
	v_mfma_f32_16x16x32_bf16 v[32:35], v[180:183], v[196:199], v[32:35]
	v_mfma_f32_16x16x32_bf16 v[20:23], v[172:175], v[208:211], v[20:23]
	v_mfma_f32_16x16x32_bf16 v[16:19], v[180:183], v[208:211], v[16:19]
	v_mfma_f32_16x16x32_bf16 v[4:7], v[172:175], v[216:219], v[4:7]
	v_mfma_f32_16x16x32_bf16 v[0:3], v[180:183], v[216:219], v[0:3]
	v_mfma_f32_16x16x32_bf16 v[52:55], v[176:179], v[192:195], v[52:55]
	v_mfma_f32_16x16x32_bf16 v[48:51], v[184:187], v[192:195], v[48:51]
	v_mfma_f32_16x16x32_bf16 v[36:39], v[176:179], v[200:203], v[36:39]
	v_mfma_f32_16x16x32_bf16 v[32:35], v[184:187], v[200:203], v[32:35]
	v_mfma_f32_16x16x32_bf16 v[20:23], v[176:179], v[212:215], v[20:23]
	v_mfma_f32_16x16x32_bf16 v[16:19], v[184:187], v[212:215], v[16:19]
	v_mfma_f32_16x16x32_bf16 v[4:7], v[176:179], v[220:223], v[4:7]
	v_mfma_f32_16x16x32_bf16 v[0:3], v[184:187], v[220:223], v[0:3]
	s_barrier
	s_add_i32 s76, 0, 0x18000
	s_add_i32 s77, 0, 0x1c000
	v_add_u32_e32 v168, s76, v157
	v_add_u32_e32 v184, s77, v157
	ds_read_b128 v[152:155], v168
	ds_read_b128 v[160:163], v168 offset:1024
	ds_read_b128 v[164:167], v168 offset:2048
	ds_read_b128 v[168:171], v168 offset:3072
	ds_read_b128 v[172:175], v184
	ds_read_b128 v[176:179], v184 offset:1024
	ds_read_b128 v[180:183], v184 offset:2048
	ds_read_b128 v[184:187], v184 offset:3072
	s_add_u32 s46, s46, 0x40000
	s_addc_u32 s47, s47, 0
	s_mov_b32 m0, s1
	v_lshl_add_u64 v[232:233], s[46:47], 0, v[132:133]
	ds_read_b128 v[188:191], v159 offset:32768
	ds_read_b128 v[192:195], v159 offset:33792
	ds_read_b128 v[196:199], v159 offset:34816
	ds_read_b128 v[200:203], v159 offset:35840
	ds_read_b128 v[208:211], v159 offset:36864
	ds_read_b128 v[212:215], v159 offset:37888
	ds_read_b128 v[216:219], v159 offset:38912
	ds_read_b128 v[220:223], v159 offset:39936
	global_load_lds_dwordx4 v[232:233], off
	v_lshl_add_u64 v[232:233], s[46:47], 0, v[130:131]
	s_mov_b32 m0, s22
	s_nop 0
	global_load_lds_dwordx4 v[232:233], off
	s_waitcnt vmcnt(8)
	s_waitcnt lgkmcnt(0)
	s_barrier
	s_waitcnt lgkmcnt(0)
	v_mfma_f32_16x16x32_bf16 v[124:127], v[152:155], v[188:191], v[124:127]
	v_mfma_f32_16x16x32_bf16 v[120:123], v[164:167], v[188:191], v[120:123]
	v_mfma_f32_16x16x32_bf16 v[108:111], v[152:155], v[196:199], v[108:111]
	v_mfma_f32_16x16x32_bf16 v[104:107], v[164:167], v[196:199], v[104:107]
	v_mfma_f32_16x16x32_bf16 v[92:95], v[152:155], v[208:211], v[92:95]
	v_mfma_f32_16x16x32_bf16 v[88:91], v[164:167], v[208:211], v[88:91]
	v_mfma_f32_16x16x32_bf16 v[76:79], v[152:155], v[216:219], v[76:79]
	v_mfma_f32_16x16x32_bf16 v[72:75], v[164:167], v[216:219], v[72:75]
	v_mfma_f32_16x16x32_bf16 v[124:127], v[160:163], v[192:195], v[124:127]
	v_mfma_f32_16x16x32_bf16 v[120:123], v[168:171], v[192:195], v[120:123]
	v_mfma_f32_16x16x32_bf16 v[108:111], v[160:163], v[200:203], v[108:111]
	v_mfma_f32_16x16x32_bf16 v[104:107], v[168:171], v[200:203], v[104:107]
	v_mfma_f32_16x16x32_bf16 v[92:95], v[160:163], v[212:215], v[92:95]
	v_mfma_f32_16x16x32_bf16 v[88:91], v[168:171], v[212:215], v[88:91]
	v_mfma_f32_16x16x32_bf16 v[76:79], v[160:163], v[220:223], v[76:79]
	v_mfma_f32_16x16x32_bf16 v[72:75], v[168:171], v[220:223], v[72:75]
	v_mfma_f32_16x16x32_bf16 v[116:119], v[172:175], v[188:191], v[116:119]
	v_mfma_f32_16x16x32_bf16 v[112:115], v[180:183], v[188:191], v[112:115]
	v_mfma_f32_16x16x32_bf16 v[100:103], v[172:175], v[196:199], v[100:103]
	v_mfma_f32_16x16x32_bf16 v[96:99], v[180:183], v[196:199], v[96:99]
	v_mfma_f32_16x16x32_bf16 v[84:87], v[172:175], v[208:211], v[84:87]
	v_mfma_f32_16x16x32_bf16 v[80:83], v[180:183], v[208:211], v[80:83]
	v_mfma_f32_16x16x32_bf16 v[68:71], v[172:175], v[216:219], v[68:71]
	v_mfma_f32_16x16x32_bf16 v[64:67], v[180:183], v[216:219], v[64:67]
	v_mfma_f32_16x16x32_bf16 v[116:119], v[176:179], v[192:195], v[116:119]
	v_mfma_f32_16x16x32_bf16 v[112:115], v[184:187], v[192:195], v[112:115]
	v_mfma_f32_16x16x32_bf16 v[100:103], v[176:179], v[200:203], v[100:103]
	v_mfma_f32_16x16x32_bf16 v[96:99], v[184:187], v[200:203], v[96:99]
	v_mfma_f32_16x16x32_bf16 v[84:87], v[176:179], v[212:215], v[84:87]
	v_mfma_f32_16x16x32_bf16 v[80:83], v[184:187], v[212:215], v[80:83]
	v_mfma_f32_16x16x32_bf16 v[68:71], v[176:179], v[220:223], v[68:71]
	v_mfma_f32_16x16x32_bf16 v[64:67], v[184:187], v[220:223], v[64:67]
	s_barrier
;     __device__ __forceinline__ void operator()(const f32x4 (&acc)[2][2][4][2], const Unit& u, int wr, int wc, int fr, int fq) const {
;         const int row0 = u.pm * BM + wr * 64 + fr, col0 = u.pn * BM + wc * 32 + 8 * fq;
; #pragma unroll
;         for (int ai = 0; ai < 2; ++ai)
; #pragma unroll
;             for (int m = 0; m < 4; ++m) {
; template <class Epi, class Sched, bool ALIGN_EPI = false, bool SP2 = false>
; __device__ __forceinline__ void gemm_phase(PG8_LAS unsigned char* lds, const Gemm g, const Sched& S, const Epi& E) {
;     ...
;             PG8_WAIT_V(8); PG8_WAIT_L(0); PG8_BAR; PG8_MMA(0, 0, At, B0); PG8_MMA(0, 1, At, B1); PG8_BAR; PG8_SCHED;
;             PG8_LDA(At, 1, 1); PG8_STAGE(PG8_SB(1, 0), b3, voffB); PG8_STAGE(PG8_SB(1, 1), b3 + hstep, voffB); PG8_STAGE(PG8_SA(1, 0), a3, voffA);
;             PG8_WAIT_V(8); PG8_WAIT_L(0); PG8_BAR; PG8_MMA(1, 0, At, B0); PG8_MMA(1, 1, At, B1); PG8_BAR; PG8_SCHED;
;             } else {
;             PG8_LDB(B0, 0, 0); PG8_SCHED; PG8_LDA(At, 0, 0); PG8_STAGE(PG8_SA(1, 1), a1 + hstep, voffA);
;             PG8_WAIT_L(8); PG8_BAR; PG8_WAIT_L(0); PG8_MMA(0, 0, At, B0); PG8_BAR; PG8_SCHED;
;             PG8_LDB(B1, 0, 1); PG8_STAGE(PG8_SB(0, 0), b2, voffB);
;             PG8_BAR; PG8_WAIT_L(0); PG8_MMA(0, 1, At, B1); PG8_BAR;
;             PG8_LDA(At, 0, 1); PG8_STAGE(PG8_SA(0, 0), a2, voffA);
;             PG8_BAR; PG8_WAIT_L(0); PG8_MMA(1, 0, At, B0); PG8_BAR; PG8_SCHED;
;             PG8_STAGE(PG8_SB(0, 1), b2 + hstep, voffB);
;             PG8_WAIT_V(6); PG8_BAR; PG8_MMA(1, 1, At, B1); PG8_BAR;
;             PG8_LDB(B0, 1, 0); PG8_SCHED; PG8_LDA(At, 1, 0); PG8_STAGE(PG8_SA(0, 1), a2 + hstep, voffA);
;             PG8_WAIT_L(8); PG8_BAR; PG8_WAIT_L(0); PG8_MMA(0, 0, At, B0); PG8_BAR; PG8_SCHED;
;             PG8_LDB(B1, 1, 1); PG8_STAGE(PG8_SB(1, 0), b3, voffB);
;             PG8_BAR; PG8_WAIT_L(0); PG8_MMA(0, 1, At, B1); PG8_BAR;
;             PG8_LDA(At, 1, 1); PG8_STAGE(PG8_SA(1, 0), a3, voffA);
;             PG8_BAR; PG8_WAIT_L(0); PG8_MMA(1, 0, At, B0); PG8_BAR; PG8_SCHED;
;             PG8_STAGE(PG8_SB(1, 1), b3 + hstep, voffB);
;             PG8_WAIT_V(6); PG8_BAR; PG8_MMA(1, 1, At, B1); PG8_BAR;
;             }
;         }
;         if constexpr (ALIGN_EPI) { if (wr == 0) PG8_BAR; }
;         if constexpr (!Epi::AFTER_DRAIN) { E(acc, cur, wr, wc, fr, fq); S.done(cur); }
	s_add_i32 s46, s76, s54
	v_lshl_add_u64 v[224:225], v[224:225], 0, s[34:35]
	s_mov_b32 m0, s46
	ds_read_b128 v[188:191], v159 offset:49152
	ds_read_b128 v[192:195], v159 offset:50176
	ds_read_b128 v[196:199], v159 offset:51200
	ds_read_b128 v[200:203], v159 offset:52224
	ds_read_b128 v[208:211], v159 offset:53248
	ds_read_b128 v[212:215], v159 offset:54272
	ds_read_b128 v[216:219], v159 offset:55296
	ds_read_b128 v[220:223], v159 offset:56320
	global_load_lds_dwordx4 v[224:225], off
	s_add_i32 m0, s46, 0x2000
	s_add_u32 s42, s42, 0x40080
	v_lshl_add_u64 v[224:225], v[226:227], 0, s[34:35]
	s_addc_u32 s43, s43, 0
	s_add_i32 s46, s77, s54
	global_load_lds_dwordx4 v[224:225], off
	v_lshl_add_u64 v[224:225], s[42:43], 0, v[138:139]
	s_mov_b32 m0, s46
	s_nop 0
	global_load_lds_dwordx4 v[224:225], off
	v_lshl_add_u64 v[224:225], s[42:43], 0, v[128:129]
	s_add_i32 m0, s46, 0x2000
	s_nop 0
	global_load_lds_dwordx4 v[224:225], off
	v_lshl_add_u64 v[224:225], v[228:229], 0, s[34:35]
	s_mov_b32 m0, s23
	s_nop 0
	global_load_lds_dwordx4 v[224:225], off
	v_lshl_add_u64 v[224:225], v[230:231], 0, s[34:35]
	s_mov_b32 m0, s58
	s_nop 0
	global_load_lds_dwordx4 v[224:225], off
	s_waitcnt vmcnt(8)
	s_waitcnt lgkmcnt(0)
	s_barrier
	s_waitcnt lgkmcnt(0)
	v_mfma_f32_16x16x32_bf16 v[60:63], v[152:155], v[188:191], v[60:63]
	v_mfma_f32_16x16x32_bf16 v[56:59], v[164:167], v[188:191], v[56:59]
	v_mfma_f32_16x16x32_bf16 v[44:47], v[152:155], v[196:199], v[44:47]
	v_mfma_f32_16x16x32_bf16 v[40:43], v[164:167], v[196:199], v[40:43]
	v_mfma_f32_16x16x32_bf16 v[28:31], v[152:155], v[208:211], v[28:31]
	v_mfma_f32_16x16x32_bf16 v[24:27], v[164:167], v[208:211], v[24:27]
	v_mfma_f32_16x16x32_bf16 v[12:15], v[152:155], v[216:219], v[12:15]
	v_mfma_f32_16x16x32_bf16 v[8:11], v[164:167], v[216:219], v[8:11]
	v_mfma_f32_16x16x32_bf16 v[60:63], v[160:163], v[192:195], v[60:63]
	v_mfma_f32_16x16x32_bf16 v[56:59], v[168:171], v[192:195], v[56:59]
	v_mfma_f32_16x16x32_bf16 v[44:47], v[160:163], v[200:203], v[44:47]
	v_mfma_f32_16x16x32_bf16 v[40:43], v[168:171], v[200:203], v[40:43]
	v_mfma_f32_16x16x32_bf16 v[28:31], v[160:163], v[212:215], v[28:31]
	v_mfma_f32_16x16x32_bf16 v[24:27], v[168:171], v[212:215], v[24:27]
	v_mfma_f32_16x16x32_bf16 v[12:15], v[160:163], v[220:223], v[12:15]
	v_mfma_f32_16x16x32_bf16 v[8:11], v[168:171], v[220:223], v[8:11]
	v_mfma_f32_16x16x32_bf16 v[52:55], v[172:175], v[188:191], v[52:55]
	v_mfma_f32_16x16x32_bf16 v[48:51], v[180:183], v[188:191], v[48:51]
	v_mfma_f32_16x16x32_bf16 v[36:39], v[172:175], v[196:199], v[36:39]
	v_mfma_f32_16x16x32_bf16 v[32:35], v[180:183], v[196:199], v[32:35]
	v_mfma_f32_16x16x32_bf16 v[20:23], v[172:175], v[208:211], v[20:23]
	v_mfma_f32_16x16x32_bf16 v[16:19], v[180:183], v[208:211], v[16:19]
	v_mfma_f32_16x16x32_bf16 v[4:7], v[172:175], v[216:219], v[4:7]
	v_mfma_f32_16x16x32_bf16 v[0:3], v[180:183], v[216:219], v[0:3]
	v_mfma_f32_16x16x32_bf16 v[52:55], v[176:179], v[192:195], v[52:55]
	v_mfma_f32_16x16x32_bf16 v[48:51], v[184:187], v[192:195], v[48:51]
	v_mfma_f32_16x16x32_bf16 v[36:39], v[176:179], v[200:203], v[36:39]
	v_mfma_f32_16x16x32_bf16 v[32:35], v[184:187], v[200:203], v[32:35]
	v_mfma_f32_16x16x32_bf16 v[20:23], v[176:179], v[212:215], v[20:23]
	v_mfma_f32_16x16x32_bf16 v[16:19], v[184:187], v[212:215], v[16:19]
	v_mfma_f32_16x16x32_bf16 v[4:7], v[176:179], v[220:223], v[4:7]
	v_mfma_f32_16x16x32_bf16 v[0:3], v[184:187], v[220:223], v[0:3]
	s_barrier
	s_add_i32 s95, s95, 2
	s_add_u32 s26, s26, 0x100
	s_addc_u32 s27, s27, 0
	s_add_u32 vcc_lo, vcc_lo, 0x100
	s_addc_u32 s94, s94, 0
	s_cmp_gt_u32 s95, 13
	s_cbranch_scc0 .LBB0_426
	s_and_b64 vcc, exec, s[28:29]
	s_cbranch_vccz .LBB0_429
	s_barrier
.LBB0_429:
	s_setprio 0
	v_lshl_add_u32 v154, s24, 8, v156
	v_ashrrev_i32_e32 v155, 31, v154
	v_lshlrev_b64 v[234:235], 6, v[154:155]
	v_and_or_b32 v234, v204, 48, v234
	v_lshl_add_u64 v[234:235], s[90:91], 0, v[234:235]
	v_mov_b32_e32 v236, 0x2000
	v_mov_b32_e32 v237, 0
	v_lshl_add_u64 v[236:237], v[234:235], 0, v[236:237]
	global_load_dwordx4 v[180:183], v[234:235], off
	global_load_dwordx4 v[184:187], v[234:235], off offset:1024
	global_load_dwordx4 v[188:191], v[234:235], off offset:2048
	global_load_dwordx4 v[192:195], v[234:235], off offset:3072
	global_load_dwordx4 v[196:199], v[236:237], off
	global_load_dwordx4 v[200:203], v[236:237], off offset:1024
	global_load_dwordx4 v[216:219], v[236:237], off offset:2048
	global_load_dwordx4 v[220:223], v[236:237], off offset:3072
	v_lshl_or_b32 v152, s25, 8, v158
	v_ashrrev_i32_e32 v153, 31, v152
	v_lshlrev_b64 v[152:153], 1, v[152:153]
	v_bfe_u32 v228, v204, 2, 4
	v_and_b32_e32 v229, 15, v204
	v_sub_u32_e32 v229, v228, v229
	v_mul_i32_i24_e32 v229, s49, v229
	v_and_b32_e32 v231, 3, v204
	v_bfe_u32 v232, v204, 4, 2
	v_sub_u32_e32 v232, v231, v232
	v_lshl_add_u32 v229, v232, 3, v229
	v_lshlrev_b32_e32 v232, 1, v229
	v_ashrrev_i32_e32 v233, 31, v232
	v_lshl_add_u64 v[152:153], v[152:153], 0, v[232:233]
	v_lshl_add_u32 v230, v231, 4, v228
	v_lshlrev_b32_e32 v230, 2, v230
	v_readlane_b32 s76, v250, 21
	v_readlane_b32 s92, v250, 23
	v_readlane_b32 s96, v250, 25
	v_readlane_b32 s77, v250, 22
	v_readlane_b32 s93, v250, 24
	v_readlane_b32 s97, v250, 26
	v_mad_i64_i32 v[162:163], s[24:25], v154, s49, 0
	v_lshl_add_u64 v[162:163], v[162:163], 1, s[78:79]
	v_lshl_add_u64 v[162:163], v[162:163], 0, v[152:153]
	s_waitcnt vmcnt(0)
; __device__ __forceinline__ unsigned cvt_pk_bf16(float lo, float hi) { unsigned r; asm volatile("v_cvt_pk_bf16_f32 %0, %1, %2" : "=v"(r) : "v"(lo), "v"(hi)); return r; }
;     __device__ __forceinline__ void operator()(const f32x4 (&acc)[2][2][4][2], const Unit& u, int wr, int wc, int fr, int fq) const {
;     ...
;                 const int row = row0 + ai * HALF + m * 16;
;                 const f32x4* sp = (const f32x4*)(ss + (size_t)row * 16);
;                 const f32x4 a0 = sp[0], a1 = sp[1], a2 = sp[2], a3 = sp[3];
;                 const float tot = ((a0.x + a0.y) + (a0.z + a0.w)) + ((a1.x + a1.y) + (a1.z + a1.w)) + ((a2.x + a2.y) + (a2.z + a2.w)) + ((a3.x + a3.y) + (a3.z + a3.w));
;                 const float rs = rsqrtf(tot * (1.0f / 1024.0f) + 1e-6f);
;                 bf16_t* rowp = O + (size_t)row * ldc + col0;
; #pragma unroll
;                 for (int bj = 0; bj < 2; ++bj) {
;                     f32x4 v0 = acc[ai][bj][m][0] * rs, v1 = acc[ai][bj][m][1] * rs;
;                     if (ACT == 1) {
; #pragma unroll
;                         for (int e = 0; e < 4; ++e) { float a = fmaxf(v0[e], 0.f); v0[e] = a * a; float b = fmaxf(v1[e], 0.f); v1[e] = b * b; }
;                     }
;                     u32x4 w; w.x = cvt_pk_bf16(v0[0], v0[1]); w.y = cvt_pk_bf16(v0[2], v0[3]); w.z = cvt_pk_bf16(v1[0], v1[1]); w.w = cvt_pk_bf16(v1[2], v1[3]);
;                     *(u32x4*)(rowp + bj * HALF) = w;
	v_add_f32_e32 v180, v180, v181
	v_add_f32_e32 v182, v182, v183
	v_add_f32_e32 v184, v184, v185
	v_add_f32_e32 v186, v186, v187
	v_add_f32_e32 v188, v188, v189
	v_add_f32_e32 v190, v190, v191
	v_add_f32_e32 v192, v192, v193
	v_add_f32_e32 v194, v194, v195
	v_add_f32_e32 v196, v196, v197
	v_add_f32_e32 v198, v198, v199
	v_add_f32_e32 v200, v200, v201
	v_add_f32_e32 v202, v202, v203
	v_add_f32_e32 v216, v216, v217
	v_add_f32_e32 v218, v218, v219
	v_add_f32_e32 v220, v220, v221
	v_add_f32_e32 v222, v222, v223
	v_add_f32_e32 v180, v180, v182
	v_add_f32_e32 v184, v184, v186
	v_add_f32_e32 v188, v188, v190
	v_add_f32_e32 v192, v192, v194
	v_add_f32_e32 v196, v196, v198
	v_add_f32_e32 v200, v200, v202
	v_add_f32_e32 v216, v216, v218
	v_add_f32_e32 v220, v220, v222
	v_mov_b32_e32 v181, v180
	v_mov_b32_e32 v185, v184
	v_mov_b32_e32 v189, v188
	v_mov_b32_e32 v193, v192
	v_mov_b32_e32 v197, v196
	v_mov_b32_e32 v201, v200
	v_mov_b32_e32 v217, v216
	v_mov_b32_e32 v221, v220
	s_nop 1
	v_permlane16_swap_b32_e32 v180, v181
	v_permlane16_swap_b32_e32 v184, v185
	v_permlane16_swap_b32_e32 v188, v189
	v_permlane16_swap_b32_e32 v192, v193
	v_permlane16_swap_b32_e32 v196, v197
	v_permlane16_swap_b32_e32 v200, v201
	v_permlane16_swap_b32_e32 v216, v217
	v_permlane16_swap_b32_e32 v220, v221
	v_add_f32_e32 v180, v180, v181
	v_add_f32_e32 v184, v184, v185
	v_add_f32_e32 v188, v188, v189
	v_add_f32_e32 v192, v192, v193
	v_add_f32_e32 v196, v196, v197
	v_add_f32_e32 v200, v200, v201
	v_add_f32_e32 v216, v216, v217
	v_add_f32_e32 v220, v220, v221
	v_mov_b32_e32 v181, v180
	v_mov_b32_e32 v185, v184
	v_mov_b32_e32 v189, v188
	v_mov_b32_e32 v193, v192
	v_mov_b32_e32 v197, v196
	v_mov_b32_e32 v201, v200
	v_mov_b32_e32 v217, v216
	v_mov_b32_e32 v221, v220
	s_nop 1
	v_permlane32_swap_b32_e32 v180, v181
	v_permlane32_swap_b32_e32 v184, v185
	v_permlane32_swap_b32_e32 v188, v189
	v_permlane32_swap_b32_e32 v192, v193
	v_permlane32_swap_b32_e32 v196, v197
	v_permlane32_swap_b32_e32 v200, v201
	v_permlane32_swap_b32_e32 v216, v217
	v_permlane32_swap_b32_e32 v220, v221
	v_add_f32_e32 v180, v180, v181
	v_add_f32_e32 v184, v184, v185
	v_add_f32_e32 v188, v188, v189
	v_add_f32_e32 v192, v192, v193
	v_add_f32_e32 v196, v196, v197
	v_add_f32_e32 v200, v200, v201
	v_add_f32_e32 v216, v216, v217
	v_add_f32_e32 v220, v220, v221
	v_fmamk_f32 v180, v180, 0x3a800000, v137
	v_cmp_gt_f32_e32 vcc, s4, v180
	v_mul_f32_e32 v181, 0x4b800000, v180
	s_nop 0
	v_cndmask_b32_e32 v180, v180, v181, vcc
	v_rsq_f32_e32 v180, v180
	s_nop 0
	v_mul_f32_e32 v181, 0x45800000, v180
	v_cndmask_b32_e32 v180, v180, v181, vcc
	v_fmamk_f32 v184, v184, 0x3a800000, v137
	v_cmp_gt_f32_e32 vcc, s4, v184
	v_mul_f32_e32 v185, 0x4b800000, v184
	s_nop 0
	v_cndmask_b32_e32 v184, v184, v185, vcc
	v_rsq_f32_e32 v184, v184
	s_nop 0
	v_mul_f32_e32 v185, 0x45800000, v184
	v_cndmask_b32_e32 v184, v184, v185, vcc
	v_fmamk_f32 v188, v188, 0x3a800000, v137
	v_cmp_gt_f32_e32 vcc, s4, v188
	v_mul_f32_e32 v189, 0x4b800000, v188
	s_nop 0
	v_cndmask_b32_e32 v188, v188, v189, vcc
	v_rsq_f32_e32 v188, v188
	s_nop 0
	v_mul_f32_e32 v189, 0x45800000, v188
	v_cndmask_b32_e32 v188, v188, v189, vcc
	v_fmamk_f32 v192, v192, 0x3a800000, v137
	v_cmp_gt_f32_e32 vcc, s4, v192
	v_mul_f32_e32 v193, 0x4b800000, v192
	s_nop 0
	v_cndmask_b32_e32 v192, v192, v193, vcc
	v_rsq_f32_e32 v192, v192
	s_nop 0
	v_mul_f32_e32 v193, 0x45800000, v192
	v_cndmask_b32_e32 v192, v192, v193, vcc
	v_fmamk_f32 v196, v196, 0x3a800000, v137
	v_cmp_gt_f32_e32 vcc, s4, v196
	v_mul_f32_e32 v197, 0x4b800000, v196
	s_nop 0
	v_cndmask_b32_e32 v196, v196, v197, vcc
	v_rsq_f32_e32 v196, v196
	s_nop 0
	v_mul_f32_e32 v197, 0x45800000, v196
	v_cndmask_b32_e32 v196, v196, v197, vcc
	v_fmamk_f32 v200, v200, 0x3a800000, v137
	v_cmp_gt_f32_e32 vcc, s4, v200
	v_mul_f32_e32 v201, 0x4b800000, v200
	s_nop 0
	v_cndmask_b32_e32 v200, v200, v201, vcc
	v_rsq_f32_e32 v200, v200
	s_nop 0
	v_mul_f32_e32 v201, 0x45800000, v200
	v_cndmask_b32_e32 v200, v200, v201, vcc
	v_fmamk_f32 v216, v216, 0x3a800000, v137
	v_cmp_gt_f32_e32 vcc, s4, v216
	v_mul_f32_e32 v217, 0x4b800000, v216
	s_nop 0
	v_cndmask_b32_e32 v216, v216, v217, vcc
	v_rsq_f32_e32 v216, v216
	s_nop 0
	v_mul_f32_e32 v217, 0x45800000, v216
	v_cndmask_b32_e32 v216, v216, v217, vcc
	v_fmamk_f32 v220, v220, 0x3a800000, v137
	v_cmp_gt_f32_e32 vcc, s4, v220
	v_mul_f32_e32 v221, 0x4b800000, v220
	s_nop 0
	v_cndmask_b32_e32 v220, v220, v221, vcc
	v_rsq_f32_e32 v220, v220
	s_nop 0
	v_mul_f32_e32 v221, 0x45800000, v220
	v_cndmask_b32_e32 v220, v220, v221, vcc
	v_mov_b32_e32 v160, v180
	v_pk_mul_f32 v[126:127], v[126:127], v[160:161] op_sel_hi:[1,0]
	v_pk_mul_f32 v[124:125], v[124:125], v[160:161] op_sel_hi:[1,0]
	v_pk_mul_f32 v[164:165], v[122:123], v[160:161] op_sel_hi:[1,0]
	v_pk_mul_f32 v[122:123], v[120:121], v[160:161] op_sel_hi:[1,0]
	v_cvt_pk_bf16_f32 v120, v124, v125
	v_cvt_pk_bf16_f32 v121, v126, v127
	v_pk_mul_f32 v[118:119], v[118:119], v[160:161] op_sel_hi:[1,0]
	v_cvt_pk_bf16_f32 v122, v122, v123
	v_cvt_pk_bf16_f32 v123, v164, v165
	ds_bpermute_b32 v208, v230, v120
	ds_bpermute_b32 v209, v230, v121
	ds_bpermute_b32 v210, v230, v122
	ds_bpermute_b32 v211, v230, v123
	v_pk_mul_f32 v[116:117], v[116:117], v[160:161] op_sel_hi:[1,0]
	s_nop 0
	v_pk_mul_f32 v[120:121], v[114:115], v[160:161] op_sel_hi:[1,0]
	v_pk_mul_f32 v[114:115], v[112:113], v[160:161] op_sel_hi:[1,0]
	v_or_b32_e32 v160, 16, v154
	v_cvt_pk_bf16_f32 v112, v116, v117
	v_cvt_pk_bf16_f32 v113, v118, v119
	v_ashrrev_i32_e32 v161, 31, v160
	v_cvt_pk_bf16_f32 v114, v114, v115
	v_cvt_pk_bf16_f32 v115, v120, v121
	ds_bpermute_b32 v212, v230, v112
	ds_bpermute_b32 v213, v230, v113
	ds_bpermute_b32 v214, v230, v114
	ds_bpermute_b32 v215, v230, v115
	s_waitcnt lgkmcnt(4)
; __device__ __forceinline__ unsigned cvt_pk_bf16(float lo, float hi) { unsigned r; asm volatile("v_cvt_pk_bf16_f32 %0, %1, %2" : "=v"(r) : "v"(lo), "v"(hi)); return r; }
;     __device__ __forceinline__ void operator()(const f32x4 (&acc)[2][2][4][2], const Unit& u, int wr, int wc, int fr, int fq) const {
;     ...
;                 const int row = row0 + ai * HALF + m * 16;
;                 const f32x4* sp = (const f32x4*)(ss + (size_t)row * 16);
;                 const f32x4 a0 = sp[0], a1 = sp[1], a2 = sp[2], a3 = sp[3];
;                 const float tot = ((a0.x + a0.y) + (a0.z + a0.w)) + ((a1.x + a1.y) + (a1.z + a1.w)) + ((a2.x + a2.y) + (a2.z + a2.w)) + ((a3.x + a3.y) + (a3.z + a3.w));
;                 const float rs = rsqrtf(tot * (1.0f / 1024.0f) + 1e-6f);
;                 bf16_t* rowp = O + (size_t)row * ldc + col0;
; #pragma unroll
;                 for (int bj = 0; bj < 2; ++bj) {
;                     f32x4 v0 = acc[ai][bj][m][0] * rs, v1 = acc[ai][bj][m][1] * rs;
;                     if (ACT == 1) {
; #pragma unroll
;                         for (int e = 0; e < 4; ++e) { float a = fmaxf(v0[e], 0.f); v0[e] = a * a; float b = fmaxf(v1[e], 0.f); v1[e] = b * b; }
;                     }
;                     u32x4 w; w.x = cvt_pk_bf16(v0[0], v0[1]); w.y = cvt_pk_bf16(v0[2], v0[3]); w.z = cvt_pk_bf16(v1[0], v1[1]); w.w = cvt_pk_bf16(v1[2], v1[3]);
;                     *(u32x4*)(rowp + bj * HALF) = w;
	global_store_dwordx4 v[162:163], v[208:211], off
	s_waitcnt lgkmcnt(0)
	global_store_dwordx4 v[162:163], v[212:215], off offset:256
	s_nop 1
	v_mad_i64_i32 v[114:115], s[24:25], v160, s49, 0
	v_lshl_add_u64 v[114:115], v[114:115], 1, s[78:79]
	v_lshl_add_u64 v[114:115], v[114:115], 0, v[152:153]
	v_mov_b32_e32 v112, v184
	v_pk_mul_f32 v[110:111], v[110:111], v[112:113] op_sel_hi:[1,0]
	v_pk_mul_f32 v[108:109], v[108:109], v[112:113] op_sel_hi:[1,0]
	v_pk_mul_f32 v[116:117], v[106:107], v[112:113] op_sel_hi:[1,0]
	v_pk_mul_f32 v[106:107], v[104:105], v[112:113] op_sel_hi:[1,0]
	v_cvt_pk_bf16_f32 v104, v108, v109
	v_cvt_pk_bf16_f32 v105, v110, v111
	v_pk_mul_f32 v[102:103], v[102:103], v[112:113] op_sel_hi:[1,0]
	v_cvt_pk_bf16_f32 v106, v106, v107
	v_cvt_pk_bf16_f32 v107, v116, v117
	ds_bpermute_b32 v208, v230, v104
	ds_bpermute_b32 v209, v230, v105
	ds_bpermute_b32 v210, v230, v106
	ds_bpermute_b32 v211, v230, v107
	v_pk_mul_f32 v[100:101], v[100:101], v[112:113] op_sel_hi:[1,0]
	s_nop 0
	v_pk_mul_f32 v[104:105], v[98:99], v[112:113] op_sel_hi:[1,0]
	v_pk_mul_f32 v[98:99], v[96:97], v[112:113] op_sel_hi:[1,0]
	v_or_b32_e32 v112, 32, v154
	v_cvt_pk_bf16_f32 v96, v100, v101
	v_cvt_pk_bf16_f32 v97, v102, v103
	v_ashrrev_i32_e32 v113, 31, v112
	v_cvt_pk_bf16_f32 v98, v98, v99
	v_cvt_pk_bf16_f32 v99, v104, v105
	ds_bpermute_b32 v212, v230, v96
	ds_bpermute_b32 v213, v230, v97
	ds_bpermute_b32 v214, v230, v98
	ds_bpermute_b32 v215, v230, v99
	s_waitcnt lgkmcnt(4)
	global_store_dwordx4 v[114:115], v[208:211], off
	s_waitcnt lgkmcnt(0)
	global_store_dwordx4 v[114:115], v[212:215], off offset:256
	s_nop 1
	v_mad_i64_i32 v[98:99], s[24:25], v112, s49, 0
	v_lshl_add_u64 v[98:99], v[98:99], 1, s[78:79]
	v_lshl_add_u64 v[98:99], v[98:99], 0, v[152:153]
	v_mov_b32_e32 v96, v188
	v_pk_mul_f32 v[94:95], v[94:95], v[96:97] op_sel_hi:[1,0]
	v_pk_mul_f32 v[92:93], v[92:93], v[96:97] op_sel_hi:[1,0]
	v_pk_mul_f32 v[100:101], v[90:91], v[96:97] op_sel_hi:[1,0]
	v_pk_mul_f32 v[90:91], v[88:89], v[96:97] op_sel_hi:[1,0]
	v_cvt_pk_bf16_f32 v88, v92, v93
	v_cvt_pk_bf16_f32 v89, v94, v95
	v_pk_mul_f32 v[86:87], v[86:87], v[96:97] op_sel_hi:[1,0]
	v_cvt_pk_bf16_f32 v90, v90, v91
	v_cvt_pk_bf16_f32 v91, v100, v101
	ds_bpermute_b32 v208, v230, v88
	ds_bpermute_b32 v209, v230, v89
	ds_bpermute_b32 v210, v230, v90
	ds_bpermute_b32 v211, v230, v91
	v_pk_mul_f32 v[84:85], v[84:85], v[96:97] op_sel_hi:[1,0]
	s_nop 0
	v_pk_mul_f32 v[88:89], v[82:83], v[96:97] op_sel_hi:[1,0]
	v_pk_mul_f32 v[82:83], v[80:81], v[96:97] op_sel_hi:[1,0]
	v_or_b32_e32 v96, 48, v154
	v_cvt_pk_bf16_f32 v80, v84, v85
	v_cvt_pk_bf16_f32 v81, v86, v87
	v_ashrrev_i32_e32 v97, 31, v96
	v_cvt_pk_bf16_f32 v82, v82, v83
	v_cvt_pk_bf16_f32 v83, v88, v89
	ds_bpermute_b32 v212, v230, v80
	ds_bpermute_b32 v213, v230, v81
	ds_bpermute_b32 v214, v230, v82
	ds_bpermute_b32 v215, v230, v83
	s_waitcnt lgkmcnt(4)
	global_store_dwordx4 v[98:99], v[208:211], off
	s_waitcnt lgkmcnt(0)
	global_store_dwordx4 v[98:99], v[212:215], off offset:256
	s_nop 1
	v_mad_i64_i32 v[82:83], s[24:25], v96, s49, 0
	v_lshl_add_u64 v[82:83], v[82:83], 1, s[78:79]
	v_lshl_add_u64 v[82:83], v[82:83], 0, v[152:153]
	v_mov_b32_e32 v80, v192
	v_pk_mul_f32 v[78:79], v[78:79], v[80:81] op_sel_hi:[1,0]
	v_pk_mul_f32 v[76:77], v[76:77], v[80:81] op_sel_hi:[1,0]
	v_pk_mul_f32 v[84:85], v[74:75], v[80:81] op_sel_hi:[1,0]
	v_pk_mul_f32 v[74:75], v[72:73], v[80:81] op_sel_hi:[1,0]
	v_cvt_pk_bf16_f32 v72, v76, v77
	v_cvt_pk_bf16_f32 v73, v78, v79
	v_pk_mul_f32 v[70:71], v[70:71], v[80:81] op_sel_hi:[1,0]
	v_cvt_pk_bf16_f32 v74, v74, v75
	v_cvt_pk_bf16_f32 v75, v84, v85
	ds_bpermute_b32 v208, v230, v72
	ds_bpermute_b32 v209, v230, v73
	ds_bpermute_b32 v210, v230, v74
	ds_bpermute_b32 v211, v230, v75
	v_pk_mul_f32 v[68:69], v[68:69], v[80:81] op_sel_hi:[1,0]
	s_nop 0
	v_pk_mul_f32 v[72:73], v[66:67], v[80:81] op_sel_hi:[1,0]
	v_pk_mul_f32 v[66:67], v[64:65], v[80:81] op_sel_hi:[1,0]
	v_add_u32_e32 v80, 0x80, v154
	v_cvt_pk_bf16_f32 v64, v68, v69
	v_cvt_pk_bf16_f32 v65, v70, v71
	v_ashrrev_i32_e32 v81, 31, v80
	v_cvt_pk_bf16_f32 v66, v66, v67
	v_cvt_pk_bf16_f32 v67, v72, v73
	ds_bpermute_b32 v212, v230, v64
	ds_bpermute_b32 v213, v230, v65
	ds_bpermute_b32 v214, v230, v66
	ds_bpermute_b32 v215, v230, v67
	s_waitcnt lgkmcnt(4)
	global_store_dwordx4 v[82:83], v[208:211], off
	s_waitcnt lgkmcnt(0)
	global_store_dwordx4 v[82:83], v[212:215], off offset:256
	s_nop 1
	v_mad_i64_i32 v[66:67], s[24:25], v80, s49, 0
	v_lshl_add_u64 v[66:67], v[66:67], 1, s[78:79]
	v_lshl_add_u64 v[66:67], v[66:67], 0, v[152:153]
	v_mov_b32_e32 v64, v196
	v_pk_mul_f32 v[62:63], v[62:63], v[64:65] op_sel_hi:[1,0]
	v_pk_mul_f32 v[60:61], v[60:61], v[64:65] op_sel_hi:[1,0]
	v_pk_mul_f32 v[68:69], v[58:59], v[64:65] op_sel_hi:[1,0]
	v_pk_mul_f32 v[58:59], v[56:57], v[64:65] op_sel_hi:[1,0]
	v_cvt_pk_bf16_f32 v56, v60, v61
	v_cvt_pk_bf16_f32 v57, v62, v63
	v_pk_mul_f32 v[54:55], v[54:55], v[64:65] op_sel_hi:[1,0]
	v_cvt_pk_bf16_f32 v58, v58, v59
	v_cvt_pk_bf16_f32 v59, v68, v69
	ds_bpermute_b32 v208, v230, v56
	ds_bpermute_b32 v209, v230, v57
	ds_bpermute_b32 v210, v230, v58
	ds_bpermute_b32 v211, v230, v59
	v_pk_mul_f32 v[52:53], v[52:53], v[64:65] op_sel_hi:[1,0]
	s_nop 0
	v_pk_mul_f32 v[56:57], v[50:51], v[64:65] op_sel_hi:[1,0]
	v_pk_mul_f32 v[50:51], v[48:49], v[64:65] op_sel_hi:[1,0]
	v_add_u32_e32 v64, 0x90, v154
	v_cvt_pk_bf16_f32 v48, v52, v53
	v_cvt_pk_bf16_f32 v49, v54, v55
	v_ashrrev_i32_e32 v65, 31, v64
	v_cvt_pk_bf16_f32 v50, v50, v51
	v_cvt_pk_bf16_f32 v51, v56, v57
	ds_bpermute_b32 v212, v230, v48
	ds_bpermute_b32 v213, v230, v49
	ds_bpermute_b32 v214, v230, v50
	ds_bpermute_b32 v215, v230, v51
	s_waitcnt lgkmcnt(4)
; __device__ __forceinline__ unsigned cvt_pk_bf16(float lo, float hi) { unsigned r; asm volatile("v_cvt_pk_bf16_f32 %0, %1, %2" : "=v"(r) : "v"(lo), "v"(hi)); return r; }
; #define PG8_BAR __builtin_amdgcn_s_barrier()
;     __device__ __forceinline__ void operator()(const f32x4 (&acc)[2][2][4][2], const Unit& u, int wr, int wc, int fr, int fq) const {
;     ...
;                 bf16_t* rowp = O + (size_t)row * ldc + col0;
; #pragma unroll
;                 for (int bj = 0; bj < 2; ++bj) {
;                     f32x4 v0 = acc[ai][bj][m][0] * rs, v1 = acc[ai][bj][m][1] * rs;
;                     if (ACT == 1) {
; #pragma unroll
;                         for (int e = 0; e < 4; ++e) { float a = fmaxf(v0[e], 0.f); v0[e] = a * a; float b = fmaxf(v1[e], 0.f); v1[e] = b * b; }
;                     }
;                     u32x4 w; w.x = cvt_pk_bf16(v0[0], v0[1]); w.y = cvt_pk_bf16(v0[2], v0[3]); w.z = cvt_pk_bf16(v1[0], v1[1]); w.w = cvt_pk_bf16(v1[2], v1[3]);
;                     *(u32x4*)(rowp + bj * HALF) = w;
; template <class Epi, class Sched, bool ALIGN_EPI = false, bool SP2 = false>
; __device__ __forceinline__ void gemm_phase(PG8_LAS unsigned char* lds, const Gemm g, const Sched& S, const Epi& E) {
;     ...
;         if (!has_next) break;
; #pragma unroll
;         for (int a = 0; a < 2; ++a)
; #pragma unroll
;             for (int b = 0; b < 2; ++b)
; #pragma unroll
;                 for (int m = 0; m < 4; ++m)
; #pragma unroll
;                     for (int n = 0; n < 2; ++n) acc[a][b][m][n] = (f32x4){0.f, 0.f, 0.f, 0.f};
;         cur = nxt; cA = nA; cB = nB; ++ui;
;         if constexpr (ALIGN_EPI) { if (wr == 1) PG8_BAR; }
	global_store_dwordx4 v[66:67], v[208:211], off
	s_waitcnt lgkmcnt(0)
	global_store_dwordx4 v[66:67], v[212:215], off offset:256
	s_nop 1
	v_mad_i64_i32 v[50:51], s[24:25], v64, s49, 0
	v_lshl_add_u64 v[50:51], v[50:51], 1, s[78:79]
	v_lshl_add_u64 v[50:51], v[50:51], 0, v[152:153]
	v_mov_b32_e32 v48, v200
	v_pk_mul_f32 v[46:47], v[46:47], v[48:49] op_sel_hi:[1,0]
	v_pk_mul_f32 v[44:45], v[44:45], v[48:49] op_sel_hi:[1,0]
	v_pk_mul_f32 v[52:53], v[42:43], v[48:49] op_sel_hi:[1,0]
	v_pk_mul_f32 v[42:43], v[40:41], v[48:49] op_sel_hi:[1,0]
	v_cvt_pk_bf16_f32 v40, v44, v45
	v_cvt_pk_bf16_f32 v41, v46, v47
	v_pk_mul_f32 v[38:39], v[38:39], v[48:49] op_sel_hi:[1,0]
	v_cvt_pk_bf16_f32 v42, v42, v43
	v_cvt_pk_bf16_f32 v43, v52, v53
	ds_bpermute_b32 v208, v230, v40
	ds_bpermute_b32 v209, v230, v41
	ds_bpermute_b32 v210, v230, v42
	ds_bpermute_b32 v211, v230, v43
	v_pk_mul_f32 v[36:37], v[36:37], v[48:49] op_sel_hi:[1,0]
	s_nop 0
	v_pk_mul_f32 v[40:41], v[34:35], v[48:49] op_sel_hi:[1,0]
	v_pk_mul_f32 v[34:35], v[32:33], v[48:49] op_sel_hi:[1,0]
	v_add_u32_e32 v48, 0xa0, v154
	v_cvt_pk_bf16_f32 v32, v36, v37
	v_cvt_pk_bf16_f32 v33, v38, v39
	v_ashrrev_i32_e32 v49, 31, v48
	v_cvt_pk_bf16_f32 v34, v34, v35
	v_cvt_pk_bf16_f32 v35, v40, v41
	ds_bpermute_b32 v212, v230, v32
	ds_bpermute_b32 v213, v230, v33
	ds_bpermute_b32 v214, v230, v34
	ds_bpermute_b32 v215, v230, v35
	s_waitcnt lgkmcnt(4)
	global_store_dwordx4 v[50:51], v[208:211], off
	s_waitcnt lgkmcnt(0)
	global_store_dwordx4 v[50:51], v[212:215], off offset:256
	s_nop 1
	v_mad_i64_i32 v[34:35], s[24:25], v48, s49, 0
	v_lshl_add_u64 v[34:35], v[34:35], 1, s[78:79]
	v_lshl_add_u64 v[34:35], v[34:35], 0, v[152:153]
	v_mov_b32_e32 v32, v216
	v_pk_mul_f32 v[30:31], v[30:31], v[32:33] op_sel_hi:[1,0]
	v_pk_mul_f32 v[28:29], v[28:29], v[32:33] op_sel_hi:[1,0]
	v_pk_mul_f32 v[36:37], v[26:27], v[32:33] op_sel_hi:[1,0]
	v_pk_mul_f32 v[26:27], v[24:25], v[32:33] op_sel_hi:[1,0]
	v_cvt_pk_bf16_f32 v24, v28, v29
	v_cvt_pk_bf16_f32 v25, v30, v31
	v_pk_mul_f32 v[22:23], v[22:23], v[32:33] op_sel_hi:[1,0]
	v_cvt_pk_bf16_f32 v26, v26, v27
	v_cvt_pk_bf16_f32 v27, v36, v37
	ds_bpermute_b32 v208, v230, v24
	ds_bpermute_b32 v209, v230, v25
	ds_bpermute_b32 v210, v230, v26
	ds_bpermute_b32 v211, v230, v27
	v_pk_mul_f32 v[20:21], v[20:21], v[32:33] op_sel_hi:[1,0]
	s_nop 0
	v_pk_mul_f32 v[24:25], v[18:19], v[32:33] op_sel_hi:[1,0]
	v_pk_mul_f32 v[18:19], v[16:17], v[32:33] op_sel_hi:[1,0]
	v_add_u32_e32 v32, 0xb0, v154
	v_cvt_pk_bf16_f32 v16, v20, v21
	v_cvt_pk_bf16_f32 v17, v22, v23
	v_ashrrev_i32_e32 v33, 31, v32
	v_cvt_pk_bf16_f32 v18, v18, v19
	v_cvt_pk_bf16_f32 v19, v24, v25
	ds_bpermute_b32 v212, v230, v16
	ds_bpermute_b32 v213, v230, v17
	ds_bpermute_b32 v214, v230, v18
	ds_bpermute_b32 v215, v230, v19
	s_waitcnt lgkmcnt(4)
	global_store_dwordx4 v[34:35], v[208:211], off
	s_waitcnt lgkmcnt(0)
	global_store_dwordx4 v[34:35], v[212:215], off offset:256
	s_nop 1
	v_mad_i64_i32 v[18:19], s[24:25], v32, s49, 0
	v_lshl_add_u64 v[18:19], v[18:19], 1, s[78:79]
	v_lshl_add_u64 v[18:19], v[18:19], 0, v[152:153]
	s_mov_b64 s[24:25], -1
	v_mov_b32_e32 v16, v220
	v_pk_mul_f32 v[14:15], v[14:15], v[16:17] op_sel_hi:[1,0]
	v_pk_mul_f32 v[12:13], v[12:13], v[16:17] op_sel_hi:[1,0]
	v_pk_mul_f32 v[20:21], v[10:11], v[16:17] op_sel_hi:[1,0]
	v_pk_mul_f32 v[10:11], v[8:9], v[16:17] op_sel_hi:[1,0]
	v_cvt_pk_bf16_f32 v8, v12, v13
	v_cvt_pk_bf16_f32 v9, v14, v15
	s_andn2_b64 vcc, exec, s[36:37]
	v_cvt_pk_bf16_f32 v10, v10, v11
	v_cvt_pk_bf16_f32 v11, v20, v21
	ds_bpermute_b32 v208, v230, v8
	ds_bpermute_b32 v209, v230, v9
	ds_bpermute_b32 v210, v230, v10
	ds_bpermute_b32 v211, v230, v11
	v_pk_mul_f32 v[6:7], v[6:7], v[16:17] op_sel_hi:[1,0]
	v_pk_mul_f32 v[4:5], v[4:5], v[16:17] op_sel_hi:[1,0]
	v_pk_mul_f32 v[8:9], v[2:3], v[16:17] op_sel_hi:[1,0]
	v_pk_mul_f32 v[2:3], v[0:1], v[16:17] op_sel_hi:[1,0]
	v_cvt_pk_bf16_f32 v0, v4, v5
	v_cvt_pk_bf16_f32 v1, v6, v7
	s_nop 0
	v_cvt_pk_bf16_f32 v2, v2, v3
	v_cvt_pk_bf16_f32 v3, v8, v9
	ds_bpermute_b32 v212, v230, v0
	ds_bpermute_b32 v213, v230, v1
	ds_bpermute_b32 v214, v230, v2
	ds_bpermute_b32 v215, v230, v3
	s_waitcnt lgkmcnt(4)
	global_store_dwordx4 v[18:19], v[208:211], off
	s_waitcnt lgkmcnt(0)
	global_store_dwordx4 v[18:19], v[212:215], off offset:256
	s_cbranch_vccnz .LBB0_422
	v_readlane_b32 s24, v250, 34
	v_readlane_b32 s25, v250, 35
	s_andn2_b64 vcc, exec, s[24:25]
	s_cbranch_vccnz .LBB0_421
	s_setprio 1
	s_barrier
	s_branch .LBB0_421

; #define PG8_STAGE(bufoff, gbase, voff) do { _Pragma("unroll") for (int _i = 0; _i < 2; ++_i) \
;         __builtin_amdgcn_global_load_lds((const unsigned*)((const char*)(gbase) + (voff)[_i]), (PG8_LAS unsigned*)(lds + (bufoff) + ldsw + _i * 8192), 16, 0, 0); } while (0)
; #define PG8_BAR __builtin_amdgcn_s_barrier()
; template <class Epi, class Sched, bool ALIGN_EPI = false, bool SP2 = false>
; __device__ __forceinline__ void gemm_phase(PG8_LAS unsigned char* lds, const Gemm g, const Sched& S, const Epi& E) {
;     ...
;     for (int i = 0; i < 2; ++i) { int R, C; stage_rc(tid * 16 + i * 8192, R, C); const int Rb = Epi::PERM ? ((R & ~31) + perm32(R & 31)) : R;
;         voffA[i] = (unsigned)(R * K + C) * 2u; voffB[i] = (unsigned)(Rb * K + C) * 2u; }
;     const size_t kstep = (size_t)(BK * 2);
;     const size_t hstep = (size_t)HALF * K * 2;
;     const size_t tstep = 2 * hstep;
;     const unsigned ldsw = (unsigned)wid * 1024u;
;     const int aoff = lds_byte(wr * 64 + fr, fq * 8), boff = lds_byte(wc * 32 + fr, fq * 8);
;     ...
;     const char* cA = (const char*)g.A + (size_t)cur.pm * tstep; const char* cB = (const char*)g.Bt + (size_t)cur.pn * tstep;
;     S.a_ready(cur);
;     if constexpr (SP2) {
;         PG8_STAGE(PG8_SB(0, 0), cB, voffB); PG8_STAGE(PG8_SB(0, 1), cB + hstep, voffB); PG8_STAGE(PG8_SA(0, 0), cA, voffA); PG8_STAGE(PG8_SA(0, 1), cA + hstep, voffA);
;         if (wr == 1) PG8_BAR;
.LBB0_1045:
	s_andn2_b64 vcc, exec, s[0:1]
	v_readlane_b32 s0, v251, 26
	v_readlane_b32 s1, v251, 27
	s_nop 1
	v_cndmask_b32_e64 v0, 0, 1, s[0:1]
	v_cmp_ne_u32_e64 s[48:49], 1, v0
	s_cbranch_vccnz .LBB0_1136
	v_mov_b32_e32 v6, v204
	s_waitcnt lgkmcnt(0)
	s_barrier
	s_and_b64 vcc, exec, s[48:49]
	v_readfirstlane_b32 s22, v6
	s_cbranch_vccnz .LBB0_1082
	v_lshlrev_b32_e32 v3, 4, v6
	v_add_u32_e32 v1, 0x2000, v3
	v_ashrrev_i32_e32 v0, 31, v1
	v_lshrrev_b32_e32 v0, 22, v0
	v_add_u32_e32 v0, v1, v0
	v_ashrrev_i32_e32 v0, 10, v0
	v_mul_i32_i24_e32 v2, 0x400, v0
	v_sub_u32_e32 v1, v1, v2
	v_lshrrev_b32_e32 v2, 4, v1
	v_bitop3_b32 v2, v2, v1, 32 bitop3:0x6c
	v_ashrrev_i32_e32 v1, 31, v2
	v_lshrrev_b32_e32 v1, 26, v1
	v_add_u32_e32 v4, v2, v1
	v_lshlrev_b32_e32 v5, 3, v0
	s_lshl_b32 s0, s45, 21
	v_readlane_b32 s1, v251, 24
	v_ashrrev_i32_e32 v1, 6, v4
	v_and_b32_e32 v5, -16, v5
	s_add_u32 s58, s1, s0
	v_readlane_b32 s0, v251, 25
	v_add_u32_e32 v5, v1, v5
	s_addc_u32 s59, s0, 0
	v_and_b32_e32 v7, 3, v1
	s_mov_b32 s0, 0x1fffe0
	v_lshrrev_b32_e32 v8, 2, v5
	v_lshlrev_b32_e32 v9, 1, v5
	v_and_b32_e32 v4, 0xc0, v4
	v_and_or_b32 v7, v5, s0, v7
	v_and_b32_e32 v8, 4, v8
	v_and_b32_e32 v9, 24, v9
	v_sub_u32_e32 v2, v2, v4
	v_or3_b32 v7, v7, v8, v9
	v_lshlrev_b32_e32 v8, 5, v0
	v_ashrrev_i16_sdwa v2, v205, sext(v2) dst_sel:DWORD dst_unused:UNUSED_PAD src0_sel:DWORD src1_sel:BYTE_0
	v_and_b32_e32 v8, 32, v8
	v_bfe_i32 v2, v2, 0, 16
	v_add_lshl_u32 v4, v8, v2, 1
	v_lshl_add_u32 v128, v7, 11, v4
	v_lshl_add_u32 v130, v5, 11, v4
	v_bfe_i32 v4, v6, 27, 1
	v_lshrrev_b32_e32 v4, 22, v4
	v_add_u32_e32 v4, v3, v4
	v_and_b32_e32 v4, 0xfffffc00, v4
	v_sub_u32_e32 v3, v3, v4
	v_lshrrev_b32_e32 v4, 4, v3
	v_bitop3_b32 v5, v4, v3, 32 bitop3:0x6c
	v_ashrrev_i32_e32 v4, 31, v6
	v_lshrrev_b32_e32 v4, 26, v4
	v_ashrrev_i32_e32 v3, 31, v5
	v_add_u32_e32 v4, v6, v4
	v_lshrrev_b32_e32 v3, 26, v3
	v_ashrrev_i32_e32 v4, 6, v4
	v_add_u32_e32 v7, v5, v3
	v_lshlrev_b32_e32 v8, 3, v4
	v_ashrrev_i32_e32 v3, 6, v7
	v_and_b32_e32 v8, -16, v8
	v_add_u32_e32 v8, v3, v8
	v_and_b32_e32 v9, 3, v3
	v_lshrrev_b32_e32 v10, 2, v8
	v_lshlrev_b32_e32 v11, 1, v8
	v_and_b32_e32 v7, 0xc0, v7
	s_ashr_i32 s24, s22, 6
	v_and_or_b32 v9, v8, s0, v9
	v_and_b32_e32 v10, 4, v10
	v_and_b32_e32 v11, 24, v11
	v_sub_u32_e32 v5, v5, v7
	s_ashr_i32 s23, s22, 8
	s_lshl_b32 s60, s24, 10
	v_or3_b32 v9, v9, v10, v11
	v_lshlrev_b32_e32 v10, 5, v4
	v_ashrrev_i16_sdwa v5, v205, sext(v5) dst_sel:DWORD dst_unused:UNUSED_PAD src0_sel:DWORD src1_sel:BYTE_0
	v_readlane_b32 s0, v251, 48
	v_and_b32_e32 v10, 32, v10
	v_bfe_i32 v5, v5, 0, 16
	v_readlane_b32 s1, v251, 49
	s_add_u32 s26, s58, s0
	v_add_lshl_u32 v7, v10, v5, 1
	s_addc_u32 s27, s59, s1
	s_add_i32 s30, s60, 0
	v_lshl_add_u32 v138, v9, 11, v7
	s_add_i32 m0, s30, 0x10000
	v_lshl_add_u32 v132, v8, 11, v7
	global_load_lds_dwordx4 v138, s[26:27]
	s_add_i32 m0, s30, 0x12000
	s_add_u32 s0, s26, 0x40000
	global_load_lds_dwordx4 v128, s[26:27]
	s_addc_u32 s1, s27, 0
	s_add_i32 m0, s30, 0x14000
	s_add_i32 s61, s30, 0x2000
	global_load_lds_dwordx4 v138, s[0:1]
	s_add_i32 m0, s30, 0x16000
	s_add_i32 s74, s30, 0x4000
	global_load_lds_dwordx4 v128, s[0:1]
	v_readlane_b32 s0, v251, 50
	s_mov_b32 m0, s30
	v_readlane_b32 s1, v251, 51
	s_add_i32 s75, s30, 0x6000
	s_cmp_eq_u32 s23, 1
	v_writelane_b32 v250, s48, 32
	s_nop 1
	global_load_lds_dwordx4 v132, s[0:1]
	s_mov_b32 m0, s61
	v_writelane_b32 v250, s49, 33
	global_load_lds_dwordx4 v130, s[0:1]
	v_readlane_b32 s0, v251, 52
	s_mov_b32 m0, s74
	v_readlane_b32 s1, v251, 53
	s_nop 4
	global_load_lds_dwordx4 v132, s[0:1]
	s_mov_b32 m0, s75
	s_nop 0
	global_load_lds_dwordx4 v130, s[0:1]
	s_cselect_b64 s[0:1], -1, 0
	s_cmp_lg_u32 s23, 1
	s_cbranch_scc1 .LBB0_1049
	s_setprio 1
	s_barrier

; #define PG8_STAGE(bufoff, gbase, voff) do { _Pragma("unroll") for (int _i = 0; _i < 2; ++_i) \
;         __builtin_amdgcn_global_load_lds((const unsigned*)((const char*)(gbase) + (voff)[_i]), (PG8_LAS unsigned*)(lds + (bufoff) + ldsw + _i * 8192), 16, 0, 0); } while (0)
; #define PG8_LDA(dst, b, h) do { _Pragma("unroll") for (int m = 0; m < 4; ++m) _Pragma("unroll") for (int k = 0; k < 2; ++k) dst[m][k] = *(const PG8_LAS bf16x8*)(lds + PG8_SA(b, h) + aoff + m * 2048 + k * 1024); } while (0)
; #define PG8_LDB(dst, b, h) do { _Pragma("unroll") for (int n = 0; n < 2; ++n) _Pragma("unroll") for (int k = 0; k < 2; ++k) dst[n][k] = *(const PG8_LAS bf16x8*)(lds + PG8_SB(b, h) + boff + n * 2048 + k * 1024); } while (0)
; #define PG8_MMA(ai, bj, At, Bt) do { __builtin_amdgcn_s_setprio(1); _Pragma("unroll") for (int m = 0; m < 4; ++m) _Pragma("unroll") for (int n = 0; n < 2; ++n) _Pragma("unroll") for (int k = 0; k < 2; ++k) \
;         acc[ai][bj][m][n] = __builtin_amdgcn_mfma_f32_16x16x32_bf16(Bt[n][k], At[m][k], acc[ai][bj][m][n], 0, 0, 0); __builtin_amdgcn_s_setprio(0); } while (0)
; #define PG8_WAIT_V(n) asm volatile("s_waitcnt vmcnt(" #n ")" ::: "memory")
; #define PG8_BAR __builtin_amdgcn_s_barrier()
; template <class Epi, class Sched, bool ALIGN_EPI = false, bool SP2 = false>
; __device__ __forceinline__ void gemm_phase(PG8_LAS unsigned char* lds, const Gemm g, const Sched& S, const Epi& E) {
;     ...
;         for (int t = 0; t < nt; t += 2) {
;             const bool last = (t == nt - 2);
;             const char* a1 = cA + (size_t)(t + 1) * kstep;
;             const char* a2 = last ? nA : cA + (size_t)(t + 2) * kstep; const char* b2 = last ? nB : cB + (size_t)(t + 2) * kstep;
;             const char* a3 = a2 + kstep; const char* b3 = b2 + kstep;
;             if (last && has_next) S.a_ready(nxt);
;             if constexpr (SP2) {
;             PG8_LDB(B0, 0, 0); PG8_LDB(B1, 0, 1); PG8_SCHED; PG8_LDA(At, 0, 0); PG8_STAGE(PG8_SA(1, 1), a1 + hstep, voffA);
;             PG8_WAIT_V(8); PG8_WAIT_L(0); PG8_BAR; PG8_MMA(0, 0, At, B0); PG8_MMA(0, 1, At, B1); PG8_BAR; PG8_SCHED;
;             PG8_LDA(At, 0, 1); PG8_STAGE(PG8_SB(0, 0), b2, voffB); PG8_STAGE(PG8_SB(0, 1), b2 + hstep, voffB); PG8_STAGE(PG8_SA(0, 0), a2, voffA);
;             PG8_WAIT_V(8); PG8_WAIT_L(0); PG8_BAR; PG8_MMA(1, 0, At, B0); PG8_MMA(1, 1, At, B1); PG8_BAR; PG8_SCHED;
.LBB0_1059:
	s_add_u32 s26, s24, 0xfffc0080
	s_addc_u32 s27, s25, -1
	s_add_i32 s76, 0, 0x10000
	s_cmp_eq_u32 s94, 12
	s_cselect_b32 s43, s47, s27
	s_cselect_b32 s42, vcc_lo, s26
	s_cselect_b32 s27, s29, s37
	s_cselect_b32 s26, vcc_hi, s36
	s_add_i32 s77, 0, 0x14000
	v_add_u32_e32 v166, s76, v151
	v_add_u32_e32 v182, s77, v151
	ds_read_b128 v[154:157], v166
	ds_read_b128 v[158:161], v166 offset:1024
	ds_read_b128 v[162:165], v166 offset:2048
	ds_read_b128 v[166:169], v166 offset:3072
	ds_read_b128 v[170:173], v182
	ds_read_b128 v[174:177], v182 offset:1024
	ds_read_b128 v[178:181], v182 offset:2048
	ds_read_b128 v[182:185], v182 offset:3072
	v_lshl_add_u64 v[202:203], s[24:25], 0, v[134:135]
	s_add_i32 m0, s30, 0xc000
	ds_read_b128 v[186:189], v153
	ds_read_b128 v[190:193], v153 offset:1024
	ds_read_b128 v[194:197], v153 offset:2048
	ds_read_b128 v[198:201], v153 offset:3072
	ds_read_b128 v[208:211], v153 offset:4096
	ds_read_b128 v[212:215], v153 offset:5120
	ds_read_b128 v[216:219], v153 offset:6144
	ds_read_b128 v[220:223], v153 offset:7168
	global_load_lds_dwordx4 v[202:203], off
	v_lshl_add_u64 v[202:203], s[24:25], 0, v[148:149]
	s_add_i32 m0, s30, 0xe000
	s_nop 0
	global_load_lds_dwordx4 v[202:203], off
	s_waitcnt vmcnt(8)
	s_waitcnt lgkmcnt(0)
	s_barrier
	s_waitcnt lgkmcnt(0)
	v_mfma_f32_16x16x32_bf16 v[124:127], v[154:157], v[186:189], v[124:127]
	v_mfma_f32_16x16x32_bf16 v[120:123], v[162:165], v[186:189], v[120:123]
	v_mfma_f32_16x16x32_bf16 v[108:111], v[154:157], v[194:197], v[108:111]
	v_mfma_f32_16x16x32_bf16 v[104:107], v[162:165], v[194:197], v[104:107]
	v_mfma_f32_16x16x32_bf16 v[92:95], v[154:157], v[208:211], v[92:95]
	v_mfma_f32_16x16x32_bf16 v[88:91], v[162:165], v[208:211], v[88:91]
	v_mfma_f32_16x16x32_bf16 v[76:79], v[154:157], v[216:219], v[76:79]
	v_mfma_f32_16x16x32_bf16 v[72:75], v[162:165], v[216:219], v[72:75]
	v_mfma_f32_16x16x32_bf16 v[124:127], v[158:161], v[190:193], v[124:127]
	v_mfma_f32_16x16x32_bf16 v[120:123], v[166:169], v[190:193], v[120:123]
	v_mfma_f32_16x16x32_bf16 v[108:111], v[158:161], v[198:201], v[108:111]
	v_mfma_f32_16x16x32_bf16 v[104:107], v[166:169], v[198:201], v[104:107]
	v_mfma_f32_16x16x32_bf16 v[92:95], v[158:161], v[212:215], v[92:95]
	v_mfma_f32_16x16x32_bf16 v[88:91], v[166:169], v[212:215], v[88:91]
	v_mfma_f32_16x16x32_bf16 v[76:79], v[158:161], v[220:223], v[76:79]
	v_mfma_f32_16x16x32_bf16 v[72:75], v[166:169], v[220:223], v[72:75]
	v_mfma_f32_16x16x32_bf16 v[116:119], v[170:173], v[186:189], v[116:119]
	v_mfma_f32_16x16x32_bf16 v[112:115], v[178:181], v[186:189], v[112:115]
	v_mfma_f32_16x16x32_bf16 v[100:103], v[170:173], v[194:197], v[100:103]
	v_mfma_f32_16x16x32_bf16 v[96:99], v[178:181], v[194:197], v[96:99]
	v_mfma_f32_16x16x32_bf16 v[84:87], v[170:173], v[208:211], v[84:87]
	v_mfma_f32_16x16x32_bf16 v[80:83], v[178:181], v[208:211], v[80:83]
	v_mfma_f32_16x16x32_bf16 v[68:71], v[170:173], v[216:219], v[68:71]
	v_mfma_f32_16x16x32_bf16 v[64:67], v[178:181], v[216:219], v[64:67]
	v_mfma_f32_16x16x32_bf16 v[116:119], v[174:177], v[190:193], v[116:119]
	v_mfma_f32_16x16x32_bf16 v[112:115], v[182:185], v[190:193], v[112:115]
	v_mfma_f32_16x16x32_bf16 v[100:103], v[174:177], v[198:201], v[100:103]
	v_mfma_f32_16x16x32_bf16 v[96:99], v[182:185], v[198:201], v[96:99]
	v_mfma_f32_16x16x32_bf16 v[84:87], v[174:177], v[212:215], v[84:87]
	v_mfma_f32_16x16x32_bf16 v[80:83], v[182:185], v[212:215], v[80:83]
	v_mfma_f32_16x16x32_bf16 v[68:71], v[174:177], v[220:223], v[68:71]
	v_mfma_f32_16x16x32_bf16 v[64:67], v[182:185], v[220:223], v[64:67]
	s_barrier
	s_add_i32 s76, s76, s60
	v_lshl_add_u64 v[202:203], s[26:27], 0, v[138:139]
	s_mov_b32 m0, s76
	ds_read_b128 v[186:189], v153 offset:16384
	ds_read_b128 v[190:193], v153 offset:17408
	ds_read_b128 v[194:197], v153 offset:18432
	ds_read_b128 v[198:201], v153 offset:19456
	ds_read_b128 v[208:211], v153 offset:20480
	ds_read_b128 v[212:215], v153 offset:21504
	ds_read_b128 v[216:219], v153 offset:22528
	ds_read_b128 v[220:223], v153 offset:23552
	global_load_lds_dwordx4 v[202:203], off
	s_add_i32 m0, s76, 0x2000
	s_add_u32 s96, s26, 0x40000
	v_lshl_add_u64 v[224:225], s[26:27], 0, v[128:129]
	s_addc_u32 s97, s27, 0
	s_add_i32 s76, s77, s60
	global_load_lds_dwordx4 v[224:225], off
	v_lshl_add_u64 v[226:227], s[96:97], 0, v[138:139]
	s_mov_b32 m0, s76
	v_lshl_add_u64 v[228:229], s[42:43], 0, v[130:131]
	global_load_lds_dwordx4 v[226:227], off
	v_lshl_add_u64 v[226:227], s[96:97], 0, v[128:129]
	s_add_i32 m0, s76, 0x2000
	s_nop 0
	global_load_lds_dwordx4 v[226:227], off
	v_lshl_add_u64 v[226:227], s[42:43], 0, v[132:133]
	s_mov_b32 m0, s30
	s_nop 0
	global_load_lds_dwordx4 v[226:227], off
	s_mov_b32 m0, s61
	s_nop 0
	global_load_lds_dwordx4 v[228:229], off
	s_waitcnt vmcnt(8)
	s_waitcnt lgkmcnt(0)
	s_barrier
; #define PG8_STAGE(bufoff, gbase, voff) do { _Pragma("unroll") for (int _i = 0; _i < 2; ++_i) \
;         __builtin_amdgcn_global_load_lds((const unsigned*)((const char*)(gbase) + (voff)[_i]), (PG8_LAS unsigned*)(lds + (bufoff) + ldsw + _i * 8192), 16, 0, 0); } while (0)
; #define PG8_LDA(dst, b, h) do { _Pragma("unroll") for (int m = 0; m < 4; ++m) _Pragma("unroll") for (int k = 0; k < 2; ++k) dst[m][k] = *(const PG8_LAS bf16x8*)(lds + PG8_SA(b, h) + aoff + m * 2048 + k * 1024); } while (0)
; #define PG8_LDB(dst, b, h) do { _Pragma("unroll") for (int n = 0; n < 2; ++n) _Pragma("unroll") for (int k = 0; k < 2; ++k) dst[n][k] = *(const PG8_LAS bf16x8*)(lds + PG8_SB(b, h) + boff + n * 2048 + k * 1024); } while (0)
; #define PG8_MMA(ai, bj, At, Bt) do { __builtin_amdgcn_s_setprio(1); _Pragma("unroll") for (int m = 0; m < 4; ++m) _Pragma("unroll") for (int n = 0; n < 2; ++n) _Pragma("unroll") for (int k = 0; k < 2; ++k) \
;         acc[ai][bj][m][n] = __builtin_amdgcn_mfma_f32_16x16x32_bf16(Bt[n][k], At[m][k], acc[ai][bj][m][n], 0, 0, 0); __builtin_amdgcn_s_setprio(0); } while (0)
; #define PG8_WAIT_V(n) asm volatile("s_waitcnt vmcnt(" #n ")" ::: "memory")
; #define PG8_WAIT_L(n) asm volatile("s_waitcnt lgkmcnt(" #n ")" ::: "memory")
; #define PG8_BAR __builtin_amdgcn_s_barrier()
; #define PG8_SCHED __builtin_amdgcn_sched_barrier(0)
; template <class Epi, class Sched, bool ALIGN_EPI = false, bool SP2 = false>
; __device__ __forceinline__ void gemm_phase(PG8_LAS unsigned char* lds, const Gemm g, const Sched& S, const Epi& E) {
;     ...
;             PG8_WAIT_V(8); PG8_WAIT_L(0); PG8_BAR; PG8_MMA(1, 0, At, B0); PG8_MMA(1, 1, At, B1); PG8_BAR; PG8_SCHED;
;             PG8_LDB(B0, 1, 0); PG8_LDB(B1, 1, 1); PG8_SCHED; PG8_LDA(At, 1, 0); PG8_STAGE(PG8_SA(0, 1), a2 + hstep, voffA);
;             PG8_WAIT_V(8); PG8_WAIT_L(0); PG8_BAR; PG8_MMA(0, 0, At, B0); PG8_MMA(0, 1, At, B1); PG8_BAR; PG8_SCHED;
	s_waitcnt lgkmcnt(0)
	v_mfma_f32_16x16x32_bf16 v[60:63], v[154:157], v[186:189], v[60:63]
	v_mfma_f32_16x16x32_bf16 v[56:59], v[162:165], v[186:189], v[56:59]
	v_mfma_f32_16x16x32_bf16 v[44:47], v[154:157], v[194:197], v[44:47]
	v_mfma_f32_16x16x32_bf16 v[40:43], v[162:165], v[194:197], v[40:43]
	v_mfma_f32_16x16x32_bf16 v[28:31], v[154:157], v[208:211], v[28:31]
	v_mfma_f32_16x16x32_bf16 v[24:27], v[162:165], v[208:211], v[24:27]
	v_mfma_f32_16x16x32_bf16 v[12:15], v[154:157], v[216:219], v[12:15]
	v_mfma_f32_16x16x32_bf16 v[8:11], v[162:165], v[216:219], v[8:11]
	v_mfma_f32_16x16x32_bf16 v[60:63], v[158:161], v[190:193], v[60:63]
	v_mfma_f32_16x16x32_bf16 v[56:59], v[166:169], v[190:193], v[56:59]
	v_mfma_f32_16x16x32_bf16 v[44:47], v[158:161], v[198:201], v[44:47]
	v_mfma_f32_16x16x32_bf16 v[40:43], v[166:169], v[198:201], v[40:43]
	v_mfma_f32_16x16x32_bf16 v[28:31], v[158:161], v[212:215], v[28:31]
	v_mfma_f32_16x16x32_bf16 v[24:27], v[166:169], v[212:215], v[24:27]
	v_mfma_f32_16x16x32_bf16 v[12:15], v[158:161], v[220:223], v[12:15]
	v_mfma_f32_16x16x32_bf16 v[8:11], v[166:169], v[220:223], v[8:11]
	v_mfma_f32_16x16x32_bf16 v[52:55], v[170:173], v[186:189], v[52:55]
	v_mfma_f32_16x16x32_bf16 v[48:51], v[178:181], v[186:189], v[48:51]
	v_mfma_f32_16x16x32_bf16 v[36:39], v[170:173], v[194:197], v[36:39]
	v_mfma_f32_16x16x32_bf16 v[32:35], v[178:181], v[194:197], v[32:35]
	v_mfma_f32_16x16x32_bf16 v[20:23], v[170:173], v[208:211], v[20:23]
	v_mfma_f32_16x16x32_bf16 v[16:19], v[178:181], v[208:211], v[16:19]
	v_mfma_f32_16x16x32_bf16 v[4:7], v[170:173], v[216:219], v[4:7]
	v_mfma_f32_16x16x32_bf16 v[0:3], v[178:181], v[216:219], v[0:3]
	v_mfma_f32_16x16x32_bf16 v[52:55], v[174:177], v[190:193], v[52:55]
	v_mfma_f32_16x16x32_bf16 v[48:51], v[182:185], v[190:193], v[48:51]
	v_mfma_f32_16x16x32_bf16 v[36:39], v[174:177], v[198:201], v[36:39]
	v_mfma_f32_16x16x32_bf16 v[32:35], v[182:185], v[198:201], v[32:35]
	v_mfma_f32_16x16x32_bf16 v[20:23], v[174:177], v[212:215], v[20:23]
	v_mfma_f32_16x16x32_bf16 v[16:19], v[182:185], v[212:215], v[16:19]
	v_mfma_f32_16x16x32_bf16 v[4:7], v[174:177], v[220:223], v[4:7]
	v_mfma_f32_16x16x32_bf16 v[0:3], v[182:185], v[220:223], v[0:3]
	s_barrier
	s_add_i32 s76, 0, 0x18000
	s_add_i32 s77, 0, 0x1c000
	v_add_u32_e32 v166, s76, v151
	v_add_u32_e32 v182, s77, v151
	ds_read_b128 v[154:157], v166
	ds_read_b128 v[158:161], v166 offset:1024
	ds_read_b128 v[162:165], v166 offset:2048
	ds_read_b128 v[166:169], v166 offset:3072
	ds_read_b128 v[170:173], v182
	ds_read_b128 v[174:177], v182 offset:1024
	ds_read_b128 v[178:181], v182 offset:2048
	ds_read_b128 v[182:185], v182 offset:3072
	s_add_u32 s42, s42, 0x40000
	s_addc_u32 s43, s43, 0
	s_mov_b32 m0, s74
	v_lshl_add_u64 v[230:231], s[42:43], 0, v[132:133]
	ds_read_b128 v[186:189], v153 offset:32768
	ds_read_b128 v[190:193], v153 offset:33792
	ds_read_b128 v[194:197], v153 offset:34816
	ds_read_b128 v[198:201], v153 offset:35840
	ds_read_b128 v[208:211], v153 offset:36864
	ds_read_b128 v[212:215], v153 offset:37888
	ds_read_b128 v[216:219], v153 offset:38912
	ds_read_b128 v[220:223], v153 offset:39936
	global_load_lds_dwordx4 v[230:231], off
	v_lshl_add_u64 v[230:231], s[42:43], 0, v[130:131]
	s_mov_b32 m0, s75
	s_nop 0
	global_load_lds_dwordx4 v[230:231], off
	s_waitcnt vmcnt(8)
	s_waitcnt lgkmcnt(0)
	s_barrier
	s_waitcnt lgkmcnt(0)
	v_mfma_f32_16x16x32_bf16 v[124:127], v[154:157], v[186:189], v[124:127]
	v_mfma_f32_16x16x32_bf16 v[120:123], v[162:165], v[186:189], v[120:123]
	v_mfma_f32_16x16x32_bf16 v[108:111], v[154:157], v[194:197], v[108:111]
	v_mfma_f32_16x16x32_bf16 v[104:107], v[162:165], v[194:197], v[104:107]
	v_mfma_f32_16x16x32_bf16 v[92:95], v[154:157], v[208:211], v[92:95]
	v_mfma_f32_16x16x32_bf16 v[88:91], v[162:165], v[208:211], v[88:91]
	v_mfma_f32_16x16x32_bf16 v[76:79], v[154:157], v[216:219], v[76:79]
	v_mfma_f32_16x16x32_bf16 v[72:75], v[162:165], v[216:219], v[72:75]
	v_mfma_f32_16x16x32_bf16 v[124:127], v[158:161], v[190:193], v[124:127]
	v_mfma_f32_16x16x32_bf16 v[120:123], v[166:169], v[190:193], v[120:123]
	v_mfma_f32_16x16x32_bf16 v[108:111], v[158:161], v[198:201], v[108:111]
	v_mfma_f32_16x16x32_bf16 v[104:107], v[166:169], v[198:201], v[104:107]
	v_mfma_f32_16x16x32_bf16 v[92:95], v[158:161], v[212:215], v[92:95]
	v_mfma_f32_16x16x32_bf16 v[88:91], v[166:169], v[212:215], v[88:91]
	v_mfma_f32_16x16x32_bf16 v[76:79], v[158:161], v[220:223], v[76:79]
	v_mfma_f32_16x16x32_bf16 v[72:75], v[166:169], v[220:223], v[72:75]
	v_mfma_f32_16x16x32_bf16 v[116:119], v[170:173], v[186:189], v[116:119]
	v_mfma_f32_16x16x32_bf16 v[112:115], v[178:181], v[186:189], v[112:115]
	v_mfma_f32_16x16x32_bf16 v[100:103], v[170:173], v[194:197], v[100:103]
	v_mfma_f32_16x16x32_bf16 v[96:99], v[178:181], v[194:197], v[96:99]
	v_mfma_f32_16x16x32_bf16 v[84:87], v[170:173], v[208:211], v[84:87]
	v_mfma_f32_16x16x32_bf16 v[80:83], v[178:181], v[208:211], v[80:83]
	v_mfma_f32_16x16x32_bf16 v[68:71], v[170:173], v[216:219], v[68:71]
	v_mfma_f32_16x16x32_bf16 v[64:67], v[178:181], v[216:219], v[64:67]
	v_mfma_f32_16x16x32_bf16 v[116:119], v[174:177], v[190:193], v[116:119]
	v_mfma_f32_16x16x32_bf16 v[112:115], v[182:185], v[190:193], v[112:115]
	v_mfma_f32_16x16x32_bf16 v[100:103], v[174:177], v[198:201], v[100:103]
	v_mfma_f32_16x16x32_bf16 v[96:99], v[182:185], v[198:201], v[96:99]
	v_mfma_f32_16x16x32_bf16 v[84:87], v[174:177], v[212:215], v[84:87]
	v_mfma_f32_16x16x32_bf16 v[80:83], v[182:185], v[212:215], v[80:83]
	v_mfma_f32_16x16x32_bf16 v[68:71], v[174:177], v[220:223], v[68:71]
	v_mfma_f32_16x16x32_bf16 v[64:67], v[182:185], v[220:223], v[64:67]
	s_barrier
; #define PG8_STAGE(bufoff, gbase, voff) do { _Pragma("unroll") for (int _i = 0; _i < 2; ++_i) \
;         __builtin_amdgcn_global_load_lds((const unsigned*)((const char*)(gbase) + (voff)[_i]), (PG8_LAS unsigned*)(lds + (bufoff) + ldsw + _i * 8192), 16, 0, 0); } while (0)
; #define PG8_LDA(dst, b, h) do { _Pragma("unroll") for (int m = 0; m < 4; ++m) _Pragma("unroll") for (int k = 0; k < 2; ++k) dst[m][k] = *(const PG8_LAS bf16x8*)(lds + PG8_SA(b, h) + aoff + m * 2048 + k * 1024); } while (0)
; #define PG8_MMA(ai, bj, At, Bt) do { __builtin_amdgcn_s_setprio(1); _Pragma("unroll") for (int m = 0; m < 4; ++m) _Pragma("unroll") for (int n = 0; n < 2; ++n) _Pragma("unroll") for (int k = 0; k < 2; ++k) \
;         acc[ai][bj][m][n] = __builtin_amdgcn_mfma_f32_16x16x32_bf16(Bt[n][k], At[m][k], acc[ai][bj][m][n], 0, 0, 0); __builtin_amdgcn_s_setprio(0); } while (0)
; #define PG8_WAIT_V(n) asm volatile("s_waitcnt vmcnt(" #n ")" ::: "memory")
; #define PG8_WAIT_L(n) asm volatile("s_waitcnt lgkmcnt(" #n ")" ::: "memory")
; #define PG8_BAR __builtin_amdgcn_s_barrier()
; #define PG8_SCHED __builtin_amdgcn_sched_barrier(0)
; template <class Epi, class Sched, bool ALIGN_EPI = false, bool SP2 = false>
; __device__ __forceinline__ void gemm_phase(PG8_LAS unsigned char* lds, const Gemm g, const Sched& S, const Epi& E) {
;     ...
;             PG8_LDA(At, 1, 1); PG8_STAGE(PG8_SB(1, 0), b3, voffB); PG8_STAGE(PG8_SB(1, 1), b3 + hstep, voffB); PG8_STAGE(PG8_SA(1, 0), a3, voffA);
;             PG8_WAIT_V(8); PG8_WAIT_L(0); PG8_BAR; PG8_MMA(1, 0, At, B0); PG8_MMA(1, 1, At, B1); PG8_BAR; PG8_SCHED;
;     ...
;         if constexpr (ALIGN_EPI) { if (wr == 0) PG8_BAR; }
	s_add_i32 s42, s76, s60
	v_lshl_add_u64 v[202:203], v[202:203], 0, s[34:35]
	s_mov_b32 m0, s42
	ds_read_b128 v[186:189], v153 offset:49152
	ds_read_b128 v[190:193], v153 offset:50176
	ds_read_b128 v[194:197], v153 offset:51200
	ds_read_b128 v[198:201], v153 offset:52224
	ds_read_b128 v[208:211], v153 offset:53248
	ds_read_b128 v[212:215], v153 offset:54272
	ds_read_b128 v[216:219], v153 offset:55296
	ds_read_b128 v[220:223], v153 offset:56320
	global_load_lds_dwordx4 v[202:203], off
	s_add_i32 m0, s42, 0x2000
	s_add_u32 s26, s26, 0x40080
	v_lshl_add_u64 v[202:203], v[224:225], 0, s[34:35]
	s_addc_u32 s27, s27, 0
	s_add_i32 s42, s77, s60
	global_load_lds_dwordx4 v[202:203], off
	v_lshl_add_u64 v[202:203], s[26:27], 0, v[138:139]
	s_mov_b32 m0, s42
	s_nop 0
	global_load_lds_dwordx4 v[202:203], off
	v_lshl_add_u64 v[202:203], s[26:27], 0, v[128:129]
	s_add_i32 m0, s42, 0x2000
	s_nop 0
	global_load_lds_dwordx4 v[202:203], off
	v_lshl_add_u64 v[202:203], v[226:227], 0, s[34:35]
	s_mov_b32 m0, s88
	s_nop 0
	global_load_lds_dwordx4 v[202:203], off
	v_lshl_add_u64 v[202:203], v[228:229], 0, s[34:35]
	s_mov_b32 m0, s89
	s_nop 0
	global_load_lds_dwordx4 v[202:203], off
	s_waitcnt vmcnt(8)
	s_waitcnt lgkmcnt(0)
	s_barrier
	s_waitcnt lgkmcnt(0)
	v_mfma_f32_16x16x32_bf16 v[60:63], v[154:157], v[186:189], v[60:63]
	v_mfma_f32_16x16x32_bf16 v[56:59], v[162:165], v[186:189], v[56:59]
	v_mfma_f32_16x16x32_bf16 v[44:47], v[154:157], v[194:197], v[44:47]
	v_mfma_f32_16x16x32_bf16 v[40:43], v[162:165], v[194:197], v[40:43]
	v_mfma_f32_16x16x32_bf16 v[28:31], v[154:157], v[208:211], v[28:31]
	v_mfma_f32_16x16x32_bf16 v[24:27], v[162:165], v[208:211], v[24:27]
	v_mfma_f32_16x16x32_bf16 v[12:15], v[154:157], v[216:219], v[12:15]
	v_mfma_f32_16x16x32_bf16 v[8:11], v[162:165], v[216:219], v[8:11]
	v_mfma_f32_16x16x32_bf16 v[60:63], v[158:161], v[190:193], v[60:63]
	v_mfma_f32_16x16x32_bf16 v[56:59], v[166:169], v[190:193], v[56:59]
	v_mfma_f32_16x16x32_bf16 v[44:47], v[158:161], v[198:201], v[44:47]
	v_mfma_f32_16x16x32_bf16 v[40:43], v[166:169], v[198:201], v[40:43]
	v_mfma_f32_16x16x32_bf16 v[28:31], v[158:161], v[212:215], v[28:31]
	v_mfma_f32_16x16x32_bf16 v[24:27], v[166:169], v[212:215], v[24:27]
	v_mfma_f32_16x16x32_bf16 v[12:15], v[158:161], v[220:223], v[12:15]
	v_mfma_f32_16x16x32_bf16 v[8:11], v[166:169], v[220:223], v[8:11]
	v_mfma_f32_16x16x32_bf16 v[52:55], v[170:173], v[186:189], v[52:55]
	v_mfma_f32_16x16x32_bf16 v[48:51], v[178:181], v[186:189], v[48:51]
	v_mfma_f32_16x16x32_bf16 v[36:39], v[170:173], v[194:197], v[36:39]
	v_mfma_f32_16x16x32_bf16 v[32:35], v[178:181], v[194:197], v[32:35]
	v_mfma_f32_16x16x32_bf16 v[20:23], v[170:173], v[208:211], v[20:23]
	v_mfma_f32_16x16x32_bf16 v[16:19], v[178:181], v[208:211], v[16:19]
	v_mfma_f32_16x16x32_bf16 v[4:7], v[170:173], v[216:219], v[4:7]
	v_mfma_f32_16x16x32_bf16 v[0:3], v[178:181], v[216:219], v[0:3]
	v_mfma_f32_16x16x32_bf16 v[52:55], v[174:177], v[190:193], v[52:55]
	v_mfma_f32_16x16x32_bf16 v[48:51], v[182:185], v[190:193], v[48:51]
	v_mfma_f32_16x16x32_bf16 v[36:39], v[174:177], v[198:201], v[36:39]
	v_mfma_f32_16x16x32_bf16 v[32:35], v[182:185], v[198:201], v[32:35]
	v_mfma_f32_16x16x32_bf16 v[20:23], v[174:177], v[212:215], v[20:23]
	v_mfma_f32_16x16x32_bf16 v[16:19], v[182:185], v[212:215], v[16:19]
	v_mfma_f32_16x16x32_bf16 v[4:7], v[174:177], v[220:223], v[4:7]
	v_mfma_f32_16x16x32_bf16 v[0:3], v[182:185], v[220:223], v[0:3]
	s_barrier
	s_add_i32 s94, s94, 2
	s_add_u32 s24, s24, 0x100
	s_addc_u32 s25, s25, 0
	s_add_u32 s36, s36, 0x100
	s_addc_u32 s37, s37, 0
	s_cmp_gt_u32 s94, 13
	s_cbranch_scc0 .LBB0_1059
	s_and_b64 vcc, exec, s[22:23]
	s_cbranch_vccz .LBB0_1062
	s_barrier
; __device__ __forceinline__ unsigned cvt_pk_bf16(float lo, float hi) { unsigned r; asm volatile("v_cvt_pk_bf16_f32 %0, %1, %2" : "=v"(r) : "v"(lo), "v"(hi)); return r; }
;     __device__ __forceinline__ void operator()(const f32x4 (&acc)[2][2][4][2], const Unit& u, int wr, int wc, int fr, int fq) const {
;         const unsigned row0 = u.pm * BM + wr * 64 + fr, col0 = u.pn * BM + wc * 32 + 8 * fq;
;         char* xo = (char*)xout; char* xbp = (char*)xb; char* ssp = (char*)ss;
;         const unsigned ssoff = (unsigned)(u.pn * 4 + wc) * 4u;
; #pragma unroll
;         for (int ai = 0; ai < 2; ++ai)
; #pragma unroll
;             for (int m = 0; m < 4; ++m) {
;                 const unsigned row = row0 + ai * HALF + m * 16;
;                 const unsigned hoff = (row * 1024u + col0) * 2u;
;                 float sq = 0.f;
; #pragma unroll
;                 for (int bj = 0; bj < 2; ++bj) {
;                     const u32x4 xw = *(const u32x4*)(xbp + hoff + bj * (HALF * 2));
;                     f32x4 v0, v1;
;                     v0[0] = __uint_as_float(xw.x << 16) + acc[ai][bj][m][0][0]; v0[1] = __uint_as_float(xw.x & 0xffff0000u) + acc[ai][bj][m][0][1];
;                     v0[2] = __uint_as_float(xw.y << 16) + acc[ai][bj][m][0][2]; v0[3] = __uint_as_float(xw.y & 0xffff0000u) + acc[ai][bj][m][0][3];
;                     v1[0] = __uint_as_float(xw.z << 16) + acc[ai][bj][m][1][0]; v1[1] = __uint_as_float(xw.z & 0xffff0000u) + acc[ai][bj][m][1][1];
;                     v1[2] = __uint_as_float(xw.w << 16) + acc[ai][bj][m][1][2]; v1[3] = __uint_as_float(xw.w & 0xffff0000u) + acc[ai][bj][m][1][3];
;                     if (xout) { *(f32x4*)(xo + 2u * hoff + bj * (HALF * 4)) = v0; *(f32x4*)(xo + 2u * hoff + bj * (HALF * 4) + 16) = v1; }
;                     u32x4 w; w.x = cvt_pk_bf16(v0[0], v0[1]); w.y = cvt_pk_bf16(v0[2], v0[3]); w.z = cvt_pk_bf16(v1[0], v1[1]); w.w = cvt_pk_bf16(v1[2], v1[3]);
;                     *(u32x4*)(xbp + hoff + bj * (HALF * 2)) = w;
;                     sq += (v0[0] * v0[0] + v0[1] * v0[1]) + (v0[2] * v0[2] + v0[3] * v0[3]) + (v1[0] * v1[0] + v1[1] * v1[1]) + (v1[2] * v1[2] + v1[3] * v1[3]);
;                 }
;                 sq += __shfl_xor(sq, 16); sq += __shfl_xor(sq, 32);
;                 if (fq == 0) *(float*)(ssp + row * 64u + ssoff) = sq;
.LBB0_1062:
	s_setprio 0
	v_lshl_add_u32 v154, s55, 8, v150
	v_lshl_or_b32 v155, s54, 9, v152
	v_lshl_add_u32 v160, v154, 11, v155
	v_add_u32_e32 v240, 0x8000, v160
	v_add_u32_e32 v241, 0x10000, v160
	v_add_u32_e32 v242, 0x18000, v160
	v_add_u32_e32 v243, 0x40000, v160
	v_add_u32_e32 v244, 0x48000, v160
	v_add_u32_e32 v245, 0x50000, v160
	v_add_u32_e32 v246, 0x58000, v160
	global_load_dwordx4 v[172:175], v160, s[72:73]
	global_load_dwordx4 v[176:179], v160, s[72:73] offset:256
	global_load_dwordx4 v[180:183], v240, s[72:73]
	global_load_dwordx4 v[184:187], v240, s[72:73] offset:256
	global_load_dwordx4 v[188:191], v241, s[72:73]
	global_load_dwordx4 v[192:195], v241, s[72:73] offset:256
	global_load_dwordx4 v[196:199], v242, s[72:73]
	global_load_dwordx4 v[200:203], v242, s[72:73] offset:256
	global_load_dwordx4 v[208:211], v243, s[72:73]
	global_load_dwordx4 v[212:215], v243, s[72:73] offset:256
	global_load_dwordx4 v[216:219], v244, s[72:73]
	global_load_dwordx4 v[220:223], v244, s[72:73] offset:256
	global_load_dwordx4 v[224:227], v245, s[72:73]
	global_load_dwordx4 v[228:231], v245, s[72:73] offset:256
	global_load_dwordx4 v[232:235], v246, s[72:73]
	global_load_dwordx4 v[236:239], v246, s[72:73] offset:256
	s_lshl_b32 s24, s54, 4
	s_or_b32 s24, s24, s92
	s_add_u32 s54, s90, s24
	s_addc_u32 s55, s91, 0
	s_waitcnt vmcnt(15)
	v_mov_b32_e32 v156, v172
	v_mov_b32_e32 v157, v173
	v_mov_b32_e32 v158, v174
	v_mov_b32_e32 v159, v175
	v_lshlrev_b32_e32 v161, 16, v156
	v_and_b32_e32 v156, 0xffff0000, v156
	v_add_f32_e32 v125, v125, v156
	v_lshlrev_b32_e32 v156, 16, v157
	v_add_f32_e32 v126, v126, v156
	v_and_b32_e32 v156, 0xffff0000, v157
	v_add_f32_e32 v127, v127, v156
	v_lshlrev_b32_e32 v156, 16, v158
	v_add_f32_e32 v156, v120, v156
	v_and_b32_e32 v120, 0xffff0000, v158
	v_add_f32_e32 v157, v121, v120
	v_lshlrev_b32_e32 v120, 16, v159
	v_add_f32_e32 v158, v122, v120
	v_and_b32_e32 v120, 0xffff0000, v159
	v_add_f32_e32 v124, v124, v161
	v_add_f32_e32 v159, v123, v120
	v_cvt_pk_bf16_f32 v120, v124, v125
	v_cvt_pk_bf16_f32 v121, v126, v127
	v_cvt_pk_bf16_f32 v122, v156, v157
	v_cvt_pk_bf16_f32 v123, v158, v159
	global_store_dwordx4 v160, v[120:123], s[72:73]
	s_nop 1
	v_mul_f32_e32 v120, v125, v125
	v_mul_f32_e32 v121, v127, v127
	v_fmac_f32_e32 v120, v124, v124
	v_fmac_f32_e32 v121, v126, v126
	v_add_f32_e32 v120, v120, v121
	v_mul_f32_e32 v121, v157, v157
	v_fmac_f32_e32 v121, v156, v156
	v_add_f32_e32 v120, v121, v120
	v_mul_f32_e32 v121, v159, v159
	v_fmac_f32_e32 v121, v158, v158
	v_add_f32_e32 v124, v121, v120
	s_waitcnt vmcnt(15)
	v_mov_b32_e32 v120, v176
	v_mov_b32_e32 v121, v177
	v_mov_b32_e32 v122, v178
	v_mov_b32_e32 v123, v179
	v_lshlrev_b32_e32 v125, 16, v120
	v_and_b32_e32 v120, 0xffff0000, v120
	v_add_f32_e32 v117, v117, v120
	v_lshlrev_b32_e32 v120, 16, v121
	v_add_f32_e32 v118, v118, v120
	v_and_b32_e32 v120, 0xffff0000, v121
	v_add_f32_e32 v119, v119, v120
	v_lshlrev_b32_e32 v120, 16, v122
	v_add_f32_e32 v120, v112, v120
	v_and_b32_e32 v112, 0xffff0000, v122
	v_add_f32_e32 v121, v113, v112
	v_lshlrev_b32_e32 v112, 16, v123
	v_add_f32_e32 v122, v114, v112
	v_and_b32_e32 v112, 0xffff0000, v123
	v_add_f32_e32 v116, v116, v125
	v_add_f32_e32 v123, v115, v112
	v_cvt_pk_bf16_f32 v112, v116, v117
	v_cvt_pk_bf16_f32 v113, v118, v119
	v_cvt_pk_bf16_f32 v114, v120, v121
	v_cvt_pk_bf16_f32 v115, v122, v123
	global_store_dwordx4 v160, v[112:115], s[72:73] offset:256
	s_nop 1
	v_mul_f32_e32 v112, v117, v117
	v_mul_f32_e32 v113, v119, v119
	v_fmac_f32_e32 v112, v116, v116
	v_fmac_f32_e32 v113, v118, v118
	v_add_f32_e32 v112, v112, v113
	v_mul_f32_e32 v113, v121, v121
	v_fmac_f32_e32 v113, v120, v120
	v_add_f32_e32 v112, v113, v112
	v_mul_f32_e32 v113, v123, v123
	v_fmac_f32_e32 v113, v122, v122
	v_add_f32_e32 v112, v113, v112
	v_and_b32_e32 v114, 64, v206
	v_add_f32_e32 v113, v124, v112
	v_xor_b32_e32 v112, 16, v206
	v_add_u32_e32 v115, 64, v114
	v_cmp_lt_i32_e32 vcc, v112, v115
	s_nop 1
	v_cndmask_b32_e32 v112, v206, v112, vcc
	v_lshlrev_b32_e32 v112, 2, v112
	ds_bpermute_b32 v114, v112, v113
	s_waitcnt lgkmcnt(0)
	v_add_f32_e32 v114, v113, v114
	v_xor_b32_e32 v113, 32, v206
	v_cmp_lt_i32_e32 vcc, v113, v115
	s_nop 1
	v_cndmask_b32_e32 v113, v206, v113, vcc
	v_lshlrev_b32_e32 v113, 2, v113
	ds_bpermute_b32 v115, v113, v114
	s_and_saveexec_b64 s[24:25], s[38:39]
	s_cbranch_execz .LBB0_1064
	v_lshlrev_b32_e32 v116, 6, v154
	s_waitcnt lgkmcnt(0)
	v_add_f32_e32 v114, v114, v115
	global_store_dword v116, v114, s[54:55]

; #define PG8_BAR __builtin_amdgcn_s_barrier()
; template <class Epi, class Sched, bool ALIGN_EPI = false, bool SP2 = false>
; __device__ __forceinline__ void gemm_phase(PG8_LAS unsigned char* lds, const Gemm g, const Sched& S, const Epi& E) {
;     ...
;         if (!has_next) break;
; #pragma unroll
;         for (int a = 0; a < 2; ++a)
; #pragma unroll
;             for (int b = 0; b < 2; ++b)
; #pragma unroll
;                 for (int m = 0; m < 4; ++m)
; #pragma unroll
;                     for (int n = 0; n < 2; ++n) acc[a][b][m][n] = (f32x4){0.f, 0.f, 0.f, 0.f};
;         cur = nxt; cA = nA; cB = nB; ++ui;
;         if constexpr (ALIGN_EPI) { if (wr == 1) PG8_BAR; }
.LBB0_1078:
	s_or_b64 exec, exec, s[24:25]
	s_andn2_b64 vcc, exec, s[40:41]
	s_mov_b64 s[24:25], -1
	s_cbranch_vccnz .LBB0_1051
	s_andn2_b64 vcc, exec, s[0:1]
	s_cbranch_vccnz .LBB0_1050
	s_setprio 1
	s_barrier
	s_branch .LBB0_1050

; #define PG8_STAGE(bufoff, gbase, voff) do { _Pragma("unroll") for (int _i = 0; _i < 2; ++_i) \
;         __builtin_amdgcn_global_load_lds((const unsigned*)((const char*)(gbase) + (voff)[_i]), (PG8_LAS unsigned*)(lds + (bufoff) + ldsw + _i * 8192), 16, 0, 0); } while (0)
; #define PG8_BAR __builtin_amdgcn_s_barrier()
; template <class Epi, class Sched, bool ALIGN_EPI = false, bool SP2 = false>
; __device__ __forceinline__ void gemm_phase(PG8_LAS unsigned char* lds, const Gemm g, const Sched& S, const Epi& E) {
;     ...
;     for (int i = 0; i < 2; ++i) { int R, C; stage_rc(tid * 16 + i * 8192, R, C); const int Rb = Epi::PERM ? ((R & ~31) + perm32(R & 31)) : R;
;         voffA[i] = (unsigned)(R * K + C) * 2u; voffB[i] = (unsigned)(Rb * K + C) * 2u; }
;     const size_t kstep = (size_t)(BK * 2);
;     const size_t hstep = (size_t)HALF * K * 2;
;     const size_t tstep = 2 * hstep;
;     const unsigned ldsw = (unsigned)wid * 1024u;
;     const int aoff = lds_byte(wr * 64 + fr, fq * 8), boff = lds_byte(wc * 32 + fr, fq * 8);
;     ...
;     const char* cA = (const char*)g.A + (size_t)cur.pm * tstep; const char* cB = (const char*)g.Bt + (size_t)cur.pn * tstep;
;     S.a_ready(cur);
;     if constexpr (SP2) {
;         PG8_STAGE(PG8_SB(0, 0), cB, voffB); PG8_STAGE(PG8_SB(0, 1), cB + hstep, voffB); PG8_STAGE(PG8_SA(0, 0), cA, voffA); PG8_STAGE(PG8_SA(0, 1), cA + hstep, voffA);
;         if (wr == 1) PG8_BAR;
.LBB0_1138:
	s_andn2_b64 vcc, exec, s[0:1]
	s_cbranch_vccnz .LBB0_1213
	v_readlane_b32 s0, v251, 30
	v_mov_b32_e32 v6, v204
	v_readlane_b32 s1, v251, 31
	s_andn2_b64 vcc, exec, s[0:1]
	v_readfirstlane_b32 s22, v6
	s_cbranch_vccnz .LBB0_1159
	s_waitcnt lgkmcnt(1)
	v_lshlrev_b32_e32 v3, 4, v6
	s_waitcnt lgkmcnt(0)
	v_add_u32_e32 v1, 0x2000, v3
	v_ashrrev_i32_e32 v0, 31, v1
	v_lshrrev_b32_e32 v0, 22, v0
	v_add_u32_e32 v0, v1, v0
	v_ashrrev_i32_e32 v0, 10, v0
	v_mul_i32_i24_e32 v2, 0x400, v0
	v_sub_u32_e32 v1, v1, v2
	v_lshrrev_b32_e32 v2, 4, v1
	v_bitop3_b32 v2, v2, v1, 32 bitop3:0x6c
	v_ashrrev_i32_e32 v1, 31, v2
	v_lshrrev_b32_e32 v1, 26, v1
	v_add_u32_e32 v4, v2, v1
	v_lshlrev_b32_e32 v5, 3, v0
	s_lshl_b32 s0, s45, 23
	v_readlane_b32 s1, v251, 28
	v_ashrrev_i32_e32 v1, 6, v4
	v_and_b32_e32 v5, -16, v5
	s_add_u32 s46, s1, s0
	v_readlane_b32 s0, v251, 29
	v_add_u32_e32 v5, v1, v5
	s_addc_u32 s47, s0, 0
	v_and_b32_e32 v7, 3, v1
	s_mov_b32 s0, 0x1fffe0
	v_lshrrev_b32_e32 v8, 2, v5
	v_lshlrev_b32_e32 v9, 1, v5
	v_and_b32_e32 v4, 0xc0, v4
	v_and_or_b32 v7, v5, s0, v7
	v_and_b32_e32 v8, 4, v8
	v_and_b32_e32 v9, 24, v9
	v_sub_u32_e32 v2, v2, v4
	v_or3_b32 v7, v7, v8, v9
	v_lshlrev_b32_e32 v8, 5, v0
	v_ashrrev_i16_sdwa v2, v205, sext(v2) dst_sel:DWORD dst_unused:UNUSED_PAD src0_sel:DWORD src1_sel:BYTE_0
	v_and_b32_e32 v8, 32, v8
	v_bfe_i32 v2, v2, 0, 16
	v_add_lshl_u32 v4, v8, v2, 1
	v_lshl_add_u32 v128, v7, 11, v4
	v_lshl_add_u32 v130, v5, 11, v4
	v_bfe_i32 v4, v6, 27, 1
	v_lshrrev_b32_e32 v4, 22, v4
	v_add_u32_e32 v4, v3, v4
	v_and_b32_e32 v4, 0xfffffc00, v4
	v_sub_u32_e32 v3, v3, v4
	v_lshrrev_b32_e32 v4, 4, v3
	v_bitop3_b32 v5, v4, v3, 32 bitop3:0x6c
	v_ashrrev_i32_e32 v4, 31, v6
	v_lshrrev_b32_e32 v4, 26, v4
	v_ashrrev_i32_e32 v3, 31, v5
	v_add_u32_e32 v4, v6, v4
	v_lshrrev_b32_e32 v3, 26, v3
	v_ashrrev_i32_e32 v4, 6, v4
	v_add_u32_e32 v7, v5, v3
	v_lshlrev_b32_e32 v8, 3, v4
	v_ashrrev_i32_e32 v3, 6, v7
	v_and_b32_e32 v8, -16, v8
	v_add_u32_e32 v8, v3, v8
	v_and_b32_e32 v9, 3, v3
	v_lshrrev_b32_e32 v10, 2, v8
	v_lshlrev_b32_e32 v11, 1, v8
	v_and_b32_e32 v7, 0xc0, v7
	v_writelane_b32 v250, s48, 32
	s_ashr_i32 s23, s22, 6
	v_and_or_b32 v9, v8, s0, v9
	v_and_b32_e32 v10, 4, v10
	v_and_b32_e32 v11, 24, v11
	v_sub_u32_e32 v5, v5, v7
	v_writelane_b32 v250, s49, 33
	s_ashr_i32 s24, s22, 8
	s_lshl_b32 s48, s23, 10
	v_or3_b32 v9, v9, v10, v11
	v_lshlrev_b32_e32 v10, 5, v4
	v_ashrrev_i16_sdwa v5, v205, sext(v5) dst_sel:DWORD dst_unused:UNUSED_PAD src0_sel:DWORD src1_sel:BYTE_0
	v_readlane_b32 s0, v251, 39
	v_and_b32_e32 v10, 32, v10
	v_bfe_i32 v5, v5, 0, 16
	v_readlane_b32 s1, v251, 40
	s_add_u32 s26, s46, s0
	v_add_lshl_u32 v7, v10, v5, 1
	s_addc_u32 s27, s47, s1
	s_add_i32 s49, s48, 0
	v_lshl_add_u32 v138, v9, 11, v7
	s_add_i32 m0, s49, 0x10000
	v_lshl_add_u32 v132, v8, 11, v7
	global_load_lds_dwordx4 v138, s[26:27]
	s_add_i32 m0, s49, 0x12000
	s_add_u32 s0, s26, 0x40000
	global_load_lds_dwordx4 v128, s[26:27]
	s_addc_u32 s1, s27, 0
	s_add_i32 m0, s49, 0x14000
	s_add_i32 s52, s49, 0x2000
	global_load_lds_dwordx4 v138, s[0:1]
	s_add_i32 m0, s49, 0x16000
	s_add_i32 s53, s49, 0x4000
	global_load_lds_dwordx4 v128, s[0:1]
	v_readlane_b32 s0, v251, 44
	s_mov_b32 m0, s49
	v_readlane_b32 s1, v251, 45
	s_add_i32 s54, s49, 0x6000
	s_cmp_eq_u32 s24, 1
	v_writelane_b32 v250, s95, 34
	s_nop 1
	global_load_lds_dwordx4 v132, s[0:1]
	s_mov_b32 m0, s52
	s_nop 0
	global_load_lds_dwordx4 v130, s[0:1]
	v_readlane_b32 s0, v251, 46
	s_mov_b32 m0, s53
	v_readlane_b32 s1, v251, 47
	s_nop 4
	global_load_lds_dwordx4 v132, s[0:1]
	s_mov_b32 m0, s54
	s_nop 0
	global_load_lds_dwordx4 v130, s[0:1]
	s_cselect_b64 s[0:1], -1, 0
	s_cmp_lg_u32 s24, 1
	s_cbranch_scc1 .LBB0_1142
	s_setprio 1
	s_barrier

; #define PG8_STAGE(bufoff, gbase, voff) do { _Pragma("unroll") for (int _i = 0; _i < 2; ++_i) \
;         __builtin_amdgcn_global_load_lds((const unsigned*)((const char*)(gbase) + (voff)[_i]), (PG8_LAS unsigned*)(lds + (bufoff) + ldsw + _i * 8192), 16, 0, 0); } while (0)
; #define PG8_LDA(dst, b, h) do { _Pragma("unroll") for (int m = 0; m < 4; ++m) _Pragma("unroll") for (int k = 0; k < 2; ++k) dst[m][k] = *(const PG8_LAS bf16x8*)(lds + PG8_SA(b, h) + aoff + m * 2048 + k * 1024); } while (0)
; #define PG8_LDB(dst, b, h) do { _Pragma("unroll") for (int n = 0; n < 2; ++n) _Pragma("unroll") for (int k = 0; k < 2; ++k) dst[n][k] = *(const PG8_LAS bf16x8*)(lds + PG8_SB(b, h) + boff + n * 2048 + k * 1024); } while (0)
; #define PG8_MMA(ai, bj, At, Bt) do { __builtin_amdgcn_s_setprio(1); _Pragma("unroll") for (int m = 0; m < 4; ++m) _Pragma("unroll") for (int n = 0; n < 2; ++n) _Pragma("unroll") for (int k = 0; k < 2; ++k) \
;         acc[ai][bj][m][n] = __builtin_amdgcn_mfma_f32_16x16x32_bf16(Bt[n][k], At[m][k], acc[ai][bj][m][n], 0, 0, 0); __builtin_amdgcn_s_setprio(0); } while (0)
; #define PG8_WAIT_V(n) asm volatile("s_waitcnt vmcnt(" #n ")" ::: "memory")
; #define PG8_BAR __builtin_amdgcn_s_barrier()
; template <class Epi, class Sched, bool ALIGN_EPI = false, bool SP2 = false>
; __device__ __forceinline__ void gemm_phase(PG8_LAS unsigned char* lds, const Gemm g, const Sched& S, const Epi& E) {
;     ...
;         for (int t = 0; t < nt; t += 2) {
;             const bool last = (t == nt - 2);
;             const char* a1 = cA + (size_t)(t + 1) * kstep;
;             const char* a2 = last ? nA : cA + (size_t)(t + 2) * kstep; const char* b2 = last ? nB : cB + (size_t)(t + 2) * kstep;
;             const char* a3 = a2 + kstep; const char* b3 = b2 + kstep;
;             if (last && has_next) S.a_ready(nxt);
;             if constexpr (SP2) {
;             PG8_LDB(B0, 0, 0); PG8_LDB(B1, 0, 1); PG8_SCHED; PG8_LDA(At, 0, 0); PG8_STAGE(PG8_SA(1, 1), a1 + hstep, voffA);
;             PG8_WAIT_V(8); PG8_WAIT_L(0); PG8_BAR; PG8_MMA(0, 0, At, B0); PG8_MMA(0, 1, At, B1); PG8_BAR; PG8_SCHED;
;             PG8_LDA(At, 0, 1); PG8_STAGE(PG8_SB(0, 0), b2, voffB); PG8_STAGE(PG8_SB(0, 1), b2 + hstep, voffB); PG8_STAGE(PG8_SA(0, 0), a2, voffA);
;             PG8_WAIT_V(8); PG8_WAIT_L(0); PG8_BAR; PG8_MMA(1, 0, At, B0); PG8_MMA(1, 1, At, B1); PG8_BAR; PG8_SCHED;
.LBB0_1152:
	s_add_u32 s26, s24, 0xfffc0080
	s_addc_u32 s27, s25, -1
	s_add_i32 s76, 0, 0x10000
	s_cmp_eq_u32 s93, 12
	s_cselect_b32 s43, s75, s27
	s_cselect_b32 s42, s89, s26
	s_cselect_b32 s27, s61, s37
	s_cselect_b32 s26, s92, s36
	s_add_i32 s77, 0, 0x14000
	v_add_u32_e32 v166, s76, v155
	v_add_u32_e32 v182, s77, v155
	ds_read_b128 v[150:153], v166
	ds_read_b128 v[158:161], v166 offset:1024
	ds_read_b128 v[162:165], v166 offset:2048
	ds_read_b128 v[166:169], v166 offset:3072
	ds_read_b128 v[170:173], v182
	ds_read_b128 v[174:177], v182 offset:1024
	ds_read_b128 v[178:181], v182 offset:2048
	ds_read_b128 v[182:185], v182 offset:3072
	v_lshl_add_u64 v[202:203], s[24:25], 0, v[134:135]
	s_add_i32 m0, s49, 0xc000
	ds_read_b128 v[186:189], v157
	ds_read_b128 v[190:193], v157 offset:1024
	ds_read_b128 v[194:197], v157 offset:2048
	ds_read_b128 v[198:201], v157 offset:3072
	ds_read_b128 v[208:211], v157 offset:4096
	ds_read_b128 v[212:215], v157 offset:5120
	ds_read_b128 v[216:219], v157 offset:6144
	ds_read_b128 v[220:223], v157 offset:7168
	global_load_lds_dwordx4 v[202:203], off
	v_lshl_add_u64 v[202:203], s[24:25], 0, v[148:149]
	s_add_i32 m0, s49, 0xe000
	s_nop 0
	global_load_lds_dwordx4 v[202:203], off
	s_waitcnt vmcnt(8)
	s_waitcnt lgkmcnt(0)
	s_barrier
	s_waitcnt lgkmcnt(0)
	v_mfma_f32_16x16x32_bf16 v[124:127], v[150:153], v[186:189], v[124:127]
	v_mfma_f32_16x16x32_bf16 v[120:123], v[162:165], v[186:189], v[120:123]
	v_mfma_f32_16x16x32_bf16 v[108:111], v[150:153], v[194:197], v[108:111]
	v_mfma_f32_16x16x32_bf16 v[104:107], v[162:165], v[194:197], v[104:107]
	v_mfma_f32_16x16x32_bf16 v[92:95], v[150:153], v[208:211], v[92:95]
	v_mfma_f32_16x16x32_bf16 v[88:91], v[162:165], v[208:211], v[88:91]
	v_mfma_f32_16x16x32_bf16 v[76:79], v[150:153], v[216:219], v[76:79]
	v_mfma_f32_16x16x32_bf16 v[72:75], v[162:165], v[216:219], v[72:75]
	v_mfma_f32_16x16x32_bf16 v[124:127], v[158:161], v[190:193], v[124:127]
	v_mfma_f32_16x16x32_bf16 v[120:123], v[166:169], v[190:193], v[120:123]
	v_mfma_f32_16x16x32_bf16 v[108:111], v[158:161], v[198:201], v[108:111]
	v_mfma_f32_16x16x32_bf16 v[104:107], v[166:169], v[198:201], v[104:107]
	v_mfma_f32_16x16x32_bf16 v[92:95], v[158:161], v[212:215], v[92:95]
	v_mfma_f32_16x16x32_bf16 v[88:91], v[166:169], v[212:215], v[88:91]
	v_mfma_f32_16x16x32_bf16 v[76:79], v[158:161], v[220:223], v[76:79]
	v_mfma_f32_16x16x32_bf16 v[72:75], v[166:169], v[220:223], v[72:75]
	v_mfma_f32_16x16x32_bf16 v[116:119], v[170:173], v[186:189], v[116:119]
	v_mfma_f32_16x16x32_bf16 v[112:115], v[178:181], v[186:189], v[112:115]
	v_mfma_f32_16x16x32_bf16 v[100:103], v[170:173], v[194:197], v[100:103]
	v_mfma_f32_16x16x32_bf16 v[96:99], v[178:181], v[194:197], v[96:99]
	v_mfma_f32_16x16x32_bf16 v[84:87], v[170:173], v[208:211], v[84:87]
	v_mfma_f32_16x16x32_bf16 v[80:83], v[178:181], v[208:211], v[80:83]
	v_mfma_f32_16x16x32_bf16 v[68:71], v[170:173], v[216:219], v[68:71]
	v_mfma_f32_16x16x32_bf16 v[64:67], v[178:181], v[216:219], v[64:67]
	v_mfma_f32_16x16x32_bf16 v[116:119], v[174:177], v[190:193], v[116:119]
	v_mfma_f32_16x16x32_bf16 v[112:115], v[182:185], v[190:193], v[112:115]
	v_mfma_f32_16x16x32_bf16 v[100:103], v[174:177], v[198:201], v[100:103]
	v_mfma_f32_16x16x32_bf16 v[96:99], v[182:185], v[198:201], v[96:99]
	v_mfma_f32_16x16x32_bf16 v[84:87], v[174:177], v[212:215], v[84:87]
	v_mfma_f32_16x16x32_bf16 v[80:83], v[182:185], v[212:215], v[80:83]
	v_mfma_f32_16x16x32_bf16 v[68:71], v[174:177], v[220:223], v[68:71]
	v_mfma_f32_16x16x32_bf16 v[64:67], v[182:185], v[220:223], v[64:67]
	s_barrier
	s_add_i32 s76, s76, s48
	v_lshl_add_u64 v[202:203], s[26:27], 0, v[138:139]
	s_mov_b32 m0, s76
	ds_read_b128 v[186:189], v157 offset:16384
	ds_read_b128 v[190:193], v157 offset:17408
	ds_read_b128 v[194:197], v157 offset:18432
	ds_read_b128 v[198:201], v157 offset:19456
	ds_read_b128 v[208:211], v157 offset:20480
	ds_read_b128 v[212:215], v157 offset:21504
	ds_read_b128 v[216:219], v157 offset:22528
	ds_read_b128 v[220:223], v157 offset:23552
	global_load_lds_dwordx4 v[202:203], off
	s_add_i32 m0, s76, 0x2000
	s_add_u32 s94, s26, 0x40000
	v_lshl_add_u64 v[224:225], s[26:27], 0, v[128:129]
	s_addc_u32 s95, s27, 0
	s_add_i32 s76, s77, s48
	global_load_lds_dwordx4 v[224:225], off
	v_lshl_add_u64 v[226:227], s[94:95], 0, v[138:139]
	s_mov_b32 m0, s76
	v_lshl_add_u64 v[228:229], s[42:43], 0, v[130:131]
	global_load_lds_dwordx4 v[226:227], off
	v_lshl_add_u64 v[226:227], s[94:95], 0, v[128:129]
	s_add_i32 m0, s76, 0x2000
	s_nop 0
	global_load_lds_dwordx4 v[226:227], off
	v_lshl_add_u64 v[226:227], s[42:43], 0, v[132:133]
	s_mov_b32 m0, s49
	s_nop 0
	global_load_lds_dwordx4 v[226:227], off
	s_mov_b32 m0, s52
	s_nop 0
	global_load_lds_dwordx4 v[228:229], off
	s_waitcnt vmcnt(8)
	s_waitcnt lgkmcnt(0)
	s_barrier
; #define PG8_STAGE(bufoff, gbase, voff) do { _Pragma("unroll") for (int _i = 0; _i < 2; ++_i) \
;         __builtin_amdgcn_global_load_lds((const unsigned*)((const char*)(gbase) + (voff)[_i]), (PG8_LAS unsigned*)(lds + (bufoff) + ldsw + _i * 8192), 16, 0, 0); } while (0)
; #define PG8_LDA(dst, b, h) do { _Pragma("unroll") for (int m = 0; m < 4; ++m) _Pragma("unroll") for (int k = 0; k < 2; ++k) dst[m][k] = *(const PG8_LAS bf16x8*)(lds + PG8_SA(b, h) + aoff + m * 2048 + k * 1024); } while (0)
; #define PG8_LDB(dst, b, h) do { _Pragma("unroll") for (int n = 0; n < 2; ++n) _Pragma("unroll") for (int k = 0; k < 2; ++k) dst[n][k] = *(const PG8_LAS bf16x8*)(lds + PG8_SB(b, h) + boff + n * 2048 + k * 1024); } while (0)
; #define PG8_MMA(ai, bj, At, Bt) do { __builtin_amdgcn_s_setprio(1); _Pragma("unroll") for (int m = 0; m < 4; ++m) _Pragma("unroll") for (int n = 0; n < 2; ++n) _Pragma("unroll") for (int k = 0; k < 2; ++k) \
;         acc[ai][bj][m][n] = __builtin_amdgcn_mfma_f32_16x16x32_bf16(Bt[n][k], At[m][k], acc[ai][bj][m][n], 0, 0, 0); __builtin_amdgcn_s_setprio(0); } while (0)
; #define PG8_WAIT_V(n) asm volatile("s_waitcnt vmcnt(" #n ")" ::: "memory")
; #define PG8_WAIT_L(n) asm volatile("s_waitcnt lgkmcnt(" #n ")" ::: "memory")
; #define PG8_BAR __builtin_amdgcn_s_barrier()
; #define PG8_SCHED __builtin_amdgcn_sched_barrier(0)
;     __device__ __forceinline__ void operator()(const f32x4 (&acc)[2][2][4][2], const Unit& u, int wr, int wc, int fr, int fq) const {
;     ...
;                 const f32x4* sp = (const f32x4*)(ss + (size_t)row * 16);
;                 const f32x4 a0 = sp[0], a1 = sp[1], a2 = sp[2], a3 = sp[3];
; template <class Epi, class Sched, bool ALIGN_EPI = false, bool SP2 = false>
; __device__ __forceinline__ void gemm_phase(PG8_LAS unsigned char* lds, const Gemm g, const Sched& S, const Epi& E) {
;     ...
;             PG8_WAIT_V(8); PG8_WAIT_L(0); PG8_BAR; PG8_MMA(1, 0, At, B0); PG8_MMA(1, 1, At, B1); PG8_BAR; PG8_SCHED;
;             PG8_LDB(B0, 1, 0); PG8_LDB(B1, 1, 1); PG8_SCHED; PG8_LDA(At, 1, 0); PG8_STAGE(PG8_SA(0, 1), a2 + hstep, voffA);
;             PG8_WAIT_V(8); PG8_WAIT_L(0); PG8_BAR; PG8_MMA(0, 0, At, B0); PG8_MMA(0, 1, At, B1); PG8_BAR; PG8_SCHED;
	s_waitcnt lgkmcnt(0)
	v_mfma_f32_16x16x32_bf16 v[60:63], v[150:153], v[186:189], v[60:63]
	v_mfma_f32_16x16x32_bf16 v[56:59], v[162:165], v[186:189], v[56:59]
	v_mfma_f32_16x16x32_bf16 v[44:47], v[150:153], v[194:197], v[44:47]
	v_mfma_f32_16x16x32_bf16 v[40:43], v[162:165], v[194:197], v[40:43]
	v_mfma_f32_16x16x32_bf16 v[28:31], v[150:153], v[208:211], v[28:31]
	v_mfma_f32_16x16x32_bf16 v[24:27], v[162:165], v[208:211], v[24:27]
	v_mfma_f32_16x16x32_bf16 v[12:15], v[150:153], v[216:219], v[12:15]
	v_mfma_f32_16x16x32_bf16 v[8:11], v[162:165], v[216:219], v[8:11]
	v_mfma_f32_16x16x32_bf16 v[60:63], v[158:161], v[190:193], v[60:63]
	v_mfma_f32_16x16x32_bf16 v[56:59], v[166:169], v[190:193], v[56:59]
	v_mfma_f32_16x16x32_bf16 v[44:47], v[158:161], v[198:201], v[44:47]
	v_mfma_f32_16x16x32_bf16 v[40:43], v[166:169], v[198:201], v[40:43]
	v_mfma_f32_16x16x32_bf16 v[28:31], v[158:161], v[212:215], v[28:31]
	v_mfma_f32_16x16x32_bf16 v[24:27], v[166:169], v[212:215], v[24:27]
	v_mfma_f32_16x16x32_bf16 v[12:15], v[158:161], v[220:223], v[12:15]
	v_mfma_f32_16x16x32_bf16 v[8:11], v[166:169], v[220:223], v[8:11]
	v_mfma_f32_16x16x32_bf16 v[52:55], v[170:173], v[186:189], v[52:55]
	v_mfma_f32_16x16x32_bf16 v[48:51], v[178:181], v[186:189], v[48:51]
	v_mfma_f32_16x16x32_bf16 v[36:39], v[170:173], v[194:197], v[36:39]
	v_mfma_f32_16x16x32_bf16 v[32:35], v[178:181], v[194:197], v[32:35]
	v_mfma_f32_16x16x32_bf16 v[20:23], v[170:173], v[208:211], v[20:23]
	v_mfma_f32_16x16x32_bf16 v[16:19], v[178:181], v[208:211], v[16:19]
	v_mfma_f32_16x16x32_bf16 v[4:7], v[170:173], v[216:219], v[4:7]
	v_mfma_f32_16x16x32_bf16 v[0:3], v[178:181], v[216:219], v[0:3]
	v_mfma_f32_16x16x32_bf16 v[52:55], v[174:177], v[190:193], v[52:55]
	v_mfma_f32_16x16x32_bf16 v[48:51], v[182:185], v[190:193], v[48:51]
	v_mfma_f32_16x16x32_bf16 v[36:39], v[174:177], v[198:201], v[36:39]
	v_mfma_f32_16x16x32_bf16 v[32:35], v[182:185], v[198:201], v[32:35]
	v_mfma_f32_16x16x32_bf16 v[20:23], v[174:177], v[212:215], v[20:23]
	v_mfma_f32_16x16x32_bf16 v[16:19], v[182:185], v[212:215], v[16:19]
	v_mfma_f32_16x16x32_bf16 v[4:7], v[174:177], v[220:223], v[4:7]
	v_mfma_f32_16x16x32_bf16 v[0:3], v[182:185], v[220:223], v[0:3]
	s_barrier
	s_add_i32 s76, 0, 0x18000
	s_add_i32 s77, 0, 0x1c000
	v_add_u32_e32 v166, s76, v155
	v_add_u32_e32 v182, s77, v155
	ds_read_b128 v[150:153], v166
	ds_read_b128 v[158:161], v166 offset:1024
	ds_read_b128 v[162:165], v166 offset:2048
	ds_read_b128 v[166:169], v166 offset:3072
	ds_read_b128 v[170:173], v182
	ds_read_b128 v[174:177], v182 offset:1024
	ds_read_b128 v[178:181], v182 offset:2048
	ds_read_b128 v[182:185], v182 offset:3072
	s_add_u32 s42, s42, 0x40000
	s_addc_u32 s43, s43, 0
	s_mov_b32 m0, s53
	v_lshl_add_u64 v[230:231], s[42:43], 0, v[132:133]
	ds_read_b128 v[186:189], v157 offset:32768
	ds_read_b128 v[190:193], v157 offset:33792
	ds_read_b128 v[194:197], v157 offset:34816
	ds_read_b128 v[198:201], v157 offset:35840
	ds_read_b128 v[208:211], v157 offset:36864
	ds_read_b128 v[212:215], v157 offset:37888
	ds_read_b128 v[216:219], v157 offset:38912
	ds_read_b128 v[220:223], v157 offset:39936
	global_load_lds_dwordx4 v[230:231], off
	v_lshl_add_u64 v[230:231], s[42:43], 0, v[130:131]
	s_mov_b32 m0, s54
	s_nop 0
	global_load_lds_dwordx4 v[230:231], off
	s_waitcnt vmcnt(8)
	s_waitcnt lgkmcnt(0)
	s_barrier
	s_waitcnt lgkmcnt(0)
	v_mfma_f32_16x16x32_bf16 v[124:127], v[150:153], v[186:189], v[124:127]
	v_mfma_f32_16x16x32_bf16 v[120:123], v[162:165], v[186:189], v[120:123]
	v_mfma_f32_16x16x32_bf16 v[108:111], v[150:153], v[194:197], v[108:111]
	v_mfma_f32_16x16x32_bf16 v[104:107], v[162:165], v[194:197], v[104:107]
	v_mfma_f32_16x16x32_bf16 v[92:95], v[150:153], v[208:211], v[92:95]
	v_mfma_f32_16x16x32_bf16 v[88:91], v[162:165], v[208:211], v[88:91]
	v_mfma_f32_16x16x32_bf16 v[76:79], v[150:153], v[216:219], v[76:79]
	v_mfma_f32_16x16x32_bf16 v[72:75], v[162:165], v[216:219], v[72:75]
	v_mfma_f32_16x16x32_bf16 v[124:127], v[158:161], v[190:193], v[124:127]
	v_mfma_f32_16x16x32_bf16 v[120:123], v[166:169], v[190:193], v[120:123]
	v_mfma_f32_16x16x32_bf16 v[108:111], v[158:161], v[198:201], v[108:111]
	v_mfma_f32_16x16x32_bf16 v[104:107], v[166:169], v[198:201], v[104:107]
	v_mfma_f32_16x16x32_bf16 v[92:95], v[158:161], v[212:215], v[92:95]
	v_mfma_f32_16x16x32_bf16 v[88:91], v[166:169], v[212:215], v[88:91]
	v_mfma_f32_16x16x32_bf16 v[76:79], v[158:161], v[220:223], v[76:79]
	v_mfma_f32_16x16x32_bf16 v[72:75], v[166:169], v[220:223], v[72:75]
	v_mfma_f32_16x16x32_bf16 v[116:119], v[170:173], v[186:189], v[116:119]
	v_mfma_f32_16x16x32_bf16 v[112:115], v[178:181], v[186:189], v[112:115]
	v_mfma_f32_16x16x32_bf16 v[100:103], v[170:173], v[194:197], v[100:103]
	v_mfma_f32_16x16x32_bf16 v[96:99], v[178:181], v[194:197], v[96:99]
	v_mfma_f32_16x16x32_bf16 v[84:87], v[170:173], v[208:211], v[84:87]
	v_mfma_f32_16x16x32_bf16 v[80:83], v[178:181], v[208:211], v[80:83]
	v_mfma_f32_16x16x32_bf16 v[68:71], v[170:173], v[216:219], v[68:71]
	v_mfma_f32_16x16x32_bf16 v[64:67], v[178:181], v[216:219], v[64:67]
	v_mfma_f32_16x16x32_bf16 v[116:119], v[174:177], v[190:193], v[116:119]
	v_mfma_f32_16x16x32_bf16 v[112:115], v[182:185], v[190:193], v[112:115]
	v_mfma_f32_16x16x32_bf16 v[100:103], v[174:177], v[198:201], v[100:103]
	v_mfma_f32_16x16x32_bf16 v[96:99], v[182:185], v[198:201], v[96:99]
	v_mfma_f32_16x16x32_bf16 v[84:87], v[174:177], v[212:215], v[84:87]
	v_mfma_f32_16x16x32_bf16 v[80:83], v[182:185], v[212:215], v[80:83]
	v_mfma_f32_16x16x32_bf16 v[68:71], v[174:177], v[220:223], v[68:71]
	v_mfma_f32_16x16x32_bf16 v[64:67], v[182:185], v[220:223], v[64:67]
	s_barrier
	s_cmp_eq_u32 s93, 12
	s_cbranch_scc0 .Lp4_noss
	v_lshl_add_u32 v248, s88, 8, v154
	v_ashrrev_i32_e32 v249, 31, v248
	v_lshlrev_b64 v[248:249], 6, v[248:249]
	v_and_or_b32 v248, v204, 48, v248
	v_lshl_add_u64 v[248:249], s[90:91], 0, v[248:249]
	global_load_dwordx4 v[232:235], v[248:249], off
	global_load_dwordx4 v[236:239], v[248:249], off offset:1024
	global_load_dwordx4 v[240:243], v[248:249], off offset:2048
	global_load_dwordx4 v[244:247], v[248:249], off offset:3072
; #define PG8_STAGE(bufoff, gbase, voff) do { _Pragma("unroll") for (int _i = 0; _i < 2; ++_i) \
;         __builtin_amdgcn_global_load_lds((const unsigned*)((const char*)(gbase) + (voff)[_i]), (PG8_LAS unsigned*)(lds + (bufoff) + ldsw + _i * 8192), 16, 0, 0); } while (0)
; #define PG8_LDA(dst, b, h) do { _Pragma("unroll") for (int m = 0; m < 4; ++m) _Pragma("unroll") for (int k = 0; k < 2; ++k) dst[m][k] = *(const PG8_LAS bf16x8*)(lds + PG8_SA(b, h) + aoff + m * 2048 + k * 1024); } while (0)
; #define PG8_MMA(ai, bj, At, Bt) do { __builtin_amdgcn_s_setprio(1); _Pragma("unroll") for (int m = 0; m < 4; ++m) _Pragma("unroll") for (int n = 0; n < 2; ++n) _Pragma("unroll") for (int k = 0; k < 2; ++k) \
;         acc[ai][bj][m][n] = __builtin_amdgcn_mfma_f32_16x16x32_bf16(Bt[n][k], At[m][k], acc[ai][bj][m][n], 0, 0, 0); __builtin_amdgcn_s_setprio(0); } while (0)
; #define PG8_WAIT_V(n) asm volatile("s_waitcnt vmcnt(" #n ")" ::: "memory")
; #define PG8_WAIT_L(n) asm volatile("s_waitcnt lgkmcnt(" #n ")" ::: "memory")
;     __device__ __forceinline__ void operator()(const f32x4 (&acc)[2][2][4][2], const Unit& u, int wr, int wc, int fr, int fq) const {
;         const int row0 = u.pm * BM + wr * 64 + fr, col0 = u.pn * BM + wc * 32 + 8 * fq;
; #pragma unroll
;         for (int ai = 0; ai < 2; ++ai)
; #pragma unroll
;             for (int m = 0; m < 4; ++m) {
;                 const int row = row0 + ai * HALF + m * 16;
;                 const f32x4* sp = (const f32x4*)(ss + (size_t)row * 16);
;                 const f32x4 a0 = sp[0], a1 = sp[1], a2 = sp[2], a3 = sp[3];
;                 const float tot = ((a0.x + a0.y) + (a0.z + a0.w)) + ((a1.x + a1.y) + (a1.z + a1.w)) + ((a2.x + a2.y) + (a2.z + a2.w)) + ((a3.x + a3.y) + (a3.z + a3.w));
;                 const float rs = rsqrtf(tot * (1.0f / 1024.0f) + 1e-6f);
; template <class Epi, class Sched, bool ALIGN_EPI = false, bool SP2 = false>
; __device__ __forceinline__ void gemm_phase(PG8_LAS unsigned char* lds, const Gemm g, const Sched& S, const Epi& E) {
;     ...
;             PG8_LDA(At, 1, 1); PG8_STAGE(PG8_SB(1, 0), b3, voffB); PG8_STAGE(PG8_SB(1, 1), b3 + hstep, voffB); PG8_STAGE(PG8_SA(1, 0), a3, voffA);
;             PG8_WAIT_V(8); PG8_WAIT_L(0); PG8_BAR; PG8_MMA(1, 0, At, B0); PG8_MMA(1, 1, At, B1); PG8_BAR; PG8_SCHED;
;     ...
;         if constexpr (ALIGN_EPI) { if (wr == 0) PG8_BAR; }
.Lp4_noss:
	s_add_i32 s42, s76, s48
	v_lshl_add_u64 v[202:203], v[202:203], 0, s[34:35]
	s_mov_b32 m0, s42
	ds_read_b128 v[186:189], v157 offset:49152
	ds_read_b128 v[190:193], v157 offset:50176
	ds_read_b128 v[194:197], v157 offset:51200
	ds_read_b128 v[198:201], v157 offset:52224
	ds_read_b128 v[208:211], v157 offset:53248
	ds_read_b128 v[212:215], v157 offset:54272
	ds_read_b128 v[216:219], v157 offset:55296
	ds_read_b128 v[220:223], v157 offset:56320
	global_load_lds_dwordx4 v[202:203], off
	s_add_i32 m0, s42, 0x2000
	s_add_u32 s26, s26, 0x40080
	v_lshl_add_u64 v[202:203], v[224:225], 0, s[34:35]
	s_addc_u32 s27, s27, 0
	s_add_i32 s42, s77, s48
	global_load_lds_dwordx4 v[202:203], off
	v_lshl_add_u64 v[202:203], s[26:27], 0, v[138:139]
	s_mov_b32 m0, s42
	s_nop 0
	global_load_lds_dwordx4 v[202:203], off
	v_lshl_add_u64 v[202:203], s[26:27], 0, v[128:129]
	s_add_i32 m0, s42, 0x2000
	s_nop 0
	global_load_lds_dwordx4 v[202:203], off
	v_lshl_add_u64 v[202:203], v[226:227], 0, s[34:35]
	s_mov_b32 m0, s55
	s_nop 0
	global_load_lds_dwordx4 v[202:203], off
	v_lshl_add_u64 v[202:203], v[228:229], 0, s[34:35]
	s_mov_b32 m0, s58
	s_nop 0
	global_load_lds_dwordx4 v[202:203], off
	s_waitcnt vmcnt(8)
	s_waitcnt lgkmcnt(0)
	s_barrier
	s_waitcnt lgkmcnt(0)
	v_mfma_f32_16x16x32_bf16 v[60:63], v[150:153], v[186:189], v[60:63]
	v_mfma_f32_16x16x32_bf16 v[56:59], v[162:165], v[186:189], v[56:59]
	v_mfma_f32_16x16x32_bf16 v[44:47], v[150:153], v[194:197], v[44:47]
	v_mfma_f32_16x16x32_bf16 v[40:43], v[162:165], v[194:197], v[40:43]
	v_mfma_f32_16x16x32_bf16 v[28:31], v[150:153], v[208:211], v[28:31]
	v_mfma_f32_16x16x32_bf16 v[24:27], v[162:165], v[208:211], v[24:27]
	v_mfma_f32_16x16x32_bf16 v[12:15], v[150:153], v[216:219], v[12:15]
	v_mfma_f32_16x16x32_bf16 v[8:11], v[162:165], v[216:219], v[8:11]
	v_mfma_f32_16x16x32_bf16 v[60:63], v[158:161], v[190:193], v[60:63]
	v_mfma_f32_16x16x32_bf16 v[56:59], v[166:169], v[190:193], v[56:59]
	v_mfma_f32_16x16x32_bf16 v[44:47], v[158:161], v[198:201], v[44:47]
	v_mfma_f32_16x16x32_bf16 v[40:43], v[166:169], v[198:201], v[40:43]
	v_mfma_f32_16x16x32_bf16 v[28:31], v[158:161], v[212:215], v[28:31]
	v_mfma_f32_16x16x32_bf16 v[24:27], v[166:169], v[212:215], v[24:27]
	v_mfma_f32_16x16x32_bf16 v[12:15], v[158:161], v[220:223], v[12:15]
	v_mfma_f32_16x16x32_bf16 v[8:11], v[166:169], v[220:223], v[8:11]
	v_mfma_f32_16x16x32_bf16 v[52:55], v[170:173], v[186:189], v[52:55]
	v_mfma_f32_16x16x32_bf16 v[48:51], v[178:181], v[186:189], v[48:51]
	v_mfma_f32_16x16x32_bf16 v[36:39], v[170:173], v[194:197], v[36:39]
	v_mfma_f32_16x16x32_bf16 v[32:35], v[178:181], v[194:197], v[32:35]
	v_mfma_f32_16x16x32_bf16 v[20:23], v[170:173], v[208:211], v[20:23]
	v_mfma_f32_16x16x32_bf16 v[16:19], v[178:181], v[208:211], v[16:19]
	v_mfma_f32_16x16x32_bf16 v[4:7], v[170:173], v[216:219], v[4:7]
	v_mfma_f32_16x16x32_bf16 v[0:3], v[178:181], v[216:219], v[0:3]
	v_mfma_f32_16x16x32_bf16 v[52:55], v[174:177], v[190:193], v[52:55]
	v_mfma_f32_16x16x32_bf16 v[48:51], v[182:185], v[190:193], v[48:51]
	v_mfma_f32_16x16x32_bf16 v[36:39], v[174:177], v[198:201], v[36:39]
	v_mfma_f32_16x16x32_bf16 v[32:35], v[182:185], v[198:201], v[32:35]
	v_mfma_f32_16x16x32_bf16 v[20:23], v[174:177], v[212:215], v[20:23]
	v_mfma_f32_16x16x32_bf16 v[16:19], v[182:185], v[212:215], v[16:19]
	v_mfma_f32_16x16x32_bf16 v[4:7], v[174:177], v[220:223], v[4:7]
	v_mfma_f32_16x16x32_bf16 v[0:3], v[182:185], v[220:223], v[0:3]
	s_barrier
	s_add_i32 s93, s93, 2
	s_add_u32 s24, s24, 0x100
	s_addc_u32 s25, s25, 0
	s_add_u32 s36, s36, 0x100
	s_addc_u32 s37, s37, 0
	s_cmp_gt_u32 s93, 13
	s_cbranch_scc0 .LBB0_1152
	v_readlane_b32 s76, v250, 21
	v_readlane_b32 s92, v250, 23
	s_and_b64 vcc, exec, s[40:41]
	v_readlane_b32 s77, v250, 22
	v_readlane_b32 s93, v250, 24
	s_cbranch_vccz .LBB0_1155
	s_barrier
.LBB0_1155:
	s_setprio 0
	v_lshl_add_u32 v152, s88, 8, v154
	v_ashrrev_i32_e32 v153, 31, v152
	v_lshlrev_b64 v[176:177], 6, v[152:153]
	v_and_or_b32 v176, v204, 48, v176
	v_lshl_add_u64 v[176:177], s[90:91], 0, v[176:177]
	v_mov_b32_e32 v178, 0x2000
	v_mov_b32_e32 v179, 0
	v_lshl_add_u64 v[178:179], v[176:177], 0, v[178:179]
	global_load_dwordx4 v[196:199], v[178:179], off
	global_load_dwordx4 v[208:211], v[178:179], off offset:1024
	global_load_dwordx4 v[212:215], v[178:179], off offset:2048
	global_load_dwordx4 v[216:219], v[178:179], off offset:3072
	v_bfe_u32 v228, v204, 2, 4
	v_and_b32_e32 v229, -16, v154
	v_or_b32_e32 v229, v229, v228
	v_lshl_add_u32 v152, s88, 8, v229
	v_ashrrev_i32_e32 v153, 31, v152
	v_and_b32_e32 v229, 3, v204
	v_lshlrev_b32_e32 v230, 3, v229
	v_and_b32_e32 v231, -32, v156
	v_or_b32_e32 v230, v230, v231
	v_lshl_add_u32 v228, v229, 4, v228
	v_lshlrev_b32_e32 v228, 2, v228
	v_lshl_or_b32 v150, s30, 8, v230
	v_ashrrev_i32_e32 v151, 31, v150
	v_lshlrev_b64 v[150:151], 1, v[150:151]
	s_mov_b64 s[24:25], -1
	v_lshlrev_b64 v[160:161], 13, v[152:153]
	v_lshl_add_u64 v[160:161], s[78:79], 0, v[160:161]
	v_lshl_add_u64 v[160:161], v[160:161], 0, v[150:151]
	s_waitcnt vmcnt(10)
; __device__ __forceinline__ unsigned cvt_pk_bf16(float lo, float hi) { unsigned r; asm volatile("v_cvt_pk_bf16_f32 %0, %1, %2" : "=v"(r) : "v"(lo), "v"(hi)); return r; }
;     __device__ __forceinline__ void operator()(const f32x4 (&acc)[2][2][4][2], const Unit& u, int wr, int wc, int fr, int fq) const {
;     ...
;                 const int row = row0 + ai * HALF + m * 16;
;                 const f32x4* sp = (const f32x4*)(ss + (size_t)row * 16);
;                 const f32x4 a0 = sp[0], a1 = sp[1], a2 = sp[2], a3 = sp[3];
;                 const float tot = ((a0.x + a0.y) + (a0.z + a0.w)) + ((a1.x + a1.y) + (a1.z + a1.w)) + ((a2.x + a2.y) + (a2.z + a2.w)) + ((a3.x + a3.y) + (a3.z + a3.w));
;                 const float rs = rsqrtf(tot * (1.0f / 1024.0f) + 1e-6f);
;                 bf16_t* rowp = O + (size_t)row * ldc + col0;
; #pragma unroll
;                 for (int bj = 0; bj < 2; ++bj) {
;                     f32x4 v0 = acc[ai][bj][m][0] * rs, v1 = acc[ai][bj][m][1] * rs;
;                     if (ACT == 1) {
; #pragma unroll
;                         for (int e = 0; e < 4; ++e) { float a = fmaxf(v0[e], 0.f); v0[e] = a * a; float b = fmaxf(v1[e], 0.f); v1[e] = b * b; }
;                     }
;                     u32x4 w; w.x = cvt_pk_bf16(v0[0], v0[1]); w.y = cvt_pk_bf16(v0[2], v0[3]); w.z = cvt_pk_bf16(v1[0], v1[1]); w.w = cvt_pk_bf16(v1[2], v1[3]);
;                     *(u32x4*)(rowp + bj * HALF) = w;
	v_mov_b32_e32 v180, v232
	v_mov_b32_e32 v181, v233
	v_mov_b32_e32 v182, v234
	v_mov_b32_e32 v183, v235
	v_mov_b32_e32 v184, v236
	v_mov_b32_e32 v185, v237
	v_mov_b32_e32 v186, v238
	v_mov_b32_e32 v187, v239
	v_mov_b32_e32 v188, v240
	v_mov_b32_e32 v189, v241
	v_mov_b32_e32 v190, v242
	v_mov_b32_e32 v191, v243
	v_mov_b32_e32 v192, v244
	v_mov_b32_e32 v193, v245
	v_mov_b32_e32 v194, v246
	v_mov_b32_e32 v195, v247
	v_add_f32_e32 v180, v180, v181
	v_add_f32_e32 v182, v182, v183
	v_add_f32_e32 v184, v184, v185
	v_add_f32_e32 v186, v186, v187
	v_add_f32_e32 v188, v188, v189
	v_add_f32_e32 v190, v190, v191
	v_add_f32_e32 v192, v192, v193
	v_add_f32_e32 v194, v194, v195
	v_add_f32_e32 v180, v180, v182
	v_add_f32_e32 v184, v184, v186
	v_add_f32_e32 v188, v188, v190
	v_add_f32_e32 v192, v192, v194
	v_mov_b32_e32 v181, v180
	v_mov_b32_e32 v185, v184
	v_mov_b32_e32 v189, v188
	v_mov_b32_e32 v193, v192
	s_nop 1
	v_permlane16_swap_b32_e32 v180, v181
	v_permlane16_swap_b32_e32 v184, v185
	v_permlane16_swap_b32_e32 v188, v189
	v_permlane16_swap_b32_e32 v192, v193
	v_add_f32_e32 v180, v180, v181
	v_add_f32_e32 v184, v184, v185
	v_add_f32_e32 v188, v188, v189
	v_add_f32_e32 v192, v192, v193
	v_mov_b32_e32 v181, v180
	v_mov_b32_e32 v185, v184
	v_mov_b32_e32 v189, v188
	v_mov_b32_e32 v193, v192
	s_nop 1
	v_permlane32_swap_b32_e32 v180, v181
	v_permlane32_swap_b32_e32 v184, v185
	v_permlane32_swap_b32_e32 v188, v189
	v_permlane32_swap_b32_e32 v192, v193
	v_add_f32_e32 v180, v180, v181
	v_add_f32_e32 v184, v184, v185
	v_add_f32_e32 v188, v188, v189
	v_add_f32_e32 v192, v192, v193
	v_fmamk_f32 v180, v180, 0x3a800000, v137
	v_cmp_gt_f32_e32 vcc, s4, v180
	v_mul_f32_e32 v181, 0x4b800000, v180
	s_nop 0
	v_cndmask_b32_e32 v180, v180, v181, vcc
	v_rsq_f32_e32 v180, v180
	s_nop 0
	v_mul_f32_e32 v181, 0x45800000, v180
	v_cndmask_b32_e32 v180, v180, v181, vcc
	v_fmamk_f32 v184, v184, 0x3a800000, v137
	v_cmp_gt_f32_e32 vcc, s4, v184
	v_mul_f32_e32 v185, 0x4b800000, v184
	s_nop 0
	v_cndmask_b32_e32 v184, v184, v185, vcc
	v_rsq_f32_e32 v184, v184
	s_nop 0
	v_mul_f32_e32 v185, 0x45800000, v184
	v_cndmask_b32_e32 v184, v184, v185, vcc
	v_fmamk_f32 v188, v188, 0x3a800000, v137
	v_cmp_gt_f32_e32 vcc, s4, v188
	v_mul_f32_e32 v189, 0x4b800000, v188
	s_nop 0
	v_cndmask_b32_e32 v188, v188, v189, vcc
	v_rsq_f32_e32 v188, v188
	s_nop 0
	v_mul_f32_e32 v189, 0x45800000, v188
	v_cndmask_b32_e32 v188, v188, v189, vcc
	v_fmamk_f32 v192, v192, 0x3a800000, v137
	v_cmp_gt_f32_e32 vcc, s4, v192
	v_mul_f32_e32 v193, 0x4b800000, v192
	s_nop 0
	v_cndmask_b32_e32 v192, v192, v193, vcc
	v_rsq_f32_e32 v192, v192
	s_nop 0
	v_mul_f32_e32 v193, 0x45800000, v192
	v_cndmask_b32_e32 v192, v192, v193, vcc
	v_mov_b32_e32 v158, v180
	v_pk_mul_f32 v[120:121], v[120:121], v[158:159] op_sel_hi:[1,0]
	v_pk_mul_f32 v[124:125], v[124:125], v[158:159] op_sel_hi:[1,0]
	v_pk_mul_f32 v[122:123], v[122:123], v[158:159] op_sel_hi:[1,0]
	v_max_f32_e32 v120, 0, v120
	v_pk_mul_f32 v[126:127], v[126:127], v[158:159] op_sel_hi:[1,0]
	v_mul_f32_e32 v153, v120, v120
	v_max_f32_e32 v120, 0, v125
	v_max_f32_e32 v121, 0, v121
	v_max_f32_e32 v122, 0, v122
	v_max_f32_e32 v124, 0, v124
	v_mul_f32_e32 v120, v120, v120
	v_mul_f32_e32 v125, v121, v121
	v_max_f32_e32 v121, 0, v126
	v_mul_f32_e32 v126, v122, v122
	v_max_f32_e32 v122, 0, v127
	v_max_f32_e32 v123, 0, v123
	v_pk_mul_f32 v[112:113], v[112:113], v[158:159] op_sel_hi:[1,0]
	v_mul_f32_e32 v124, v124, v124
	v_mul_f32_e32 v121, v121, v121
	v_mul_f32_e32 v122, v122, v122
	v_mul_f32_e32 v123, v123, v123
	v_cvt_pk_bf16_f32 v120, v124, v120
	v_pk_mul_f32 v[116:117], v[116:117], v[158:159] op_sel_hi:[1,0]
	v_pk_mul_f32 v[114:115], v[114:115], v[158:159] op_sel_hi:[1,0]
	v_max_f32_e32 v112, 0, v112
	v_cvt_pk_bf16_f32 v121, v121, v122
	v_cvt_pk_bf16_f32 v122, v153, v125
	v_cvt_pk_bf16_f32 v123, v126, v123
	ds_bpermute_b32 v220, v228, v120
	ds_bpermute_b32 v221, v228, v121
	ds_bpermute_b32 v222, v228, v122
	ds_bpermute_b32 v223, v228, v123
	v_pk_mul_f32 v[118:119], v[118:119], v[158:159] op_sel_hi:[1,0]
	v_max_f32_e32 v113, 0, v113
	v_mul_f32_e32 v120, v112, v112
	v_max_f32_e32 v112, 0, v117
	v_max_f32_e32 v114, 0, v114
	v_max_f32_e32 v116, 0, v116
	v_mul_f32_e32 v112, v112, v112
	v_mul_f32_e32 v117, v113, v113
	v_max_f32_e32 v113, 0, v118
	v_mul_f32_e32 v118, v114, v114
	v_max_f32_e32 v114, 0, v119
	v_max_f32_e32 v115, 0, v115
	v_mul_f32_e32 v116, v116, v116
	v_mul_f32_e32 v113, v113, v113
	v_mul_f32_e32 v114, v114, v114
	v_mul_f32_e32 v115, v115, v115
	v_cvt_pk_bf16_f32 v112, v116, v112
	v_cvt_pk_bf16_f32 v113, v113, v114
	v_cvt_pk_bf16_f32 v114, v120, v117
	v_cvt_pk_bf16_f32 v115, v118, v115
	ds_bpermute_b32 v224, v228, v112
	ds_bpermute_b32 v225, v228, v113
	ds_bpermute_b32 v226, v228, v114
	ds_bpermute_b32 v227, v228, v115
	s_waitcnt lgkmcnt(4)
	global_store_dwordx4 v[160:161], v[220:223], off
	s_waitcnt lgkmcnt(0)
; __device__ __forceinline__ unsigned cvt_pk_bf16(float lo, float hi) { unsigned r; asm volatile("v_cvt_pk_bf16_f32 %0, %1, %2" : "=v"(r) : "v"(lo), "v"(hi)); return r; }
;     __device__ __forceinline__ void operator()(const f32x4 (&acc)[2][2][4][2], const Unit& u, int wr, int wc, int fr, int fq) const {
;     ...
;                 bf16_t* rowp = O + (size_t)row * ldc + col0;
; #pragma unroll
;                 for (int bj = 0; bj < 2; ++bj) {
;                     f32x4 v0 = acc[ai][bj][m][0] * rs, v1 = acc[ai][bj][m][1] * rs;
;                     if (ACT == 1) {
; #pragma unroll
;                         for (int e = 0; e < 4; ++e) { float a = fmaxf(v0[e], 0.f); v0[e] = a * a; float b = fmaxf(v1[e], 0.f); v1[e] = b * b; }
;                     }
;                     u32x4 w; w.x = cvt_pk_bf16(v0[0], v0[1]); w.y = cvt_pk_bf16(v0[2], v0[3]); w.z = cvt_pk_bf16(v1[0], v1[1]); w.w = cvt_pk_bf16(v1[2], v1[3]);
;                     *(u32x4*)(rowp + bj * HALF) = w;
	global_store_dwordx4 v[160:161], v[224:227], off offset:256
	s_nop 1
	v_or_b32_e32 v112, 16, v152
	v_ashrrev_i32_e32 v113, 31, v112
	v_lshlrev_b64 v[112:113], 13, v[112:113]
	v_lshl_add_u64 v[112:113], s[78:79], 0, v[112:113]
	v_lshl_add_u64 v[112:113], v[112:113], 0, v[150:151]
	v_mov_b32_e32 v114, v184
	v_pk_mul_f32 v[104:105], v[104:105], v[114:115] op_sel_hi:[1,0]
	v_pk_mul_f32 v[108:109], v[108:109], v[114:115] op_sel_hi:[1,0]
	v_pk_mul_f32 v[106:107], v[106:107], v[114:115] op_sel_hi:[1,0]
	v_max_f32_e32 v104, 0, v104
	v_pk_mul_f32 v[110:111], v[110:111], v[114:115] op_sel_hi:[1,0]
	v_mul_f32_e32 v115, v104, v104
	v_max_f32_e32 v104, 0, v109
	v_max_f32_e32 v105, 0, v105
	v_max_f32_e32 v106, 0, v106
	v_max_f32_e32 v108, 0, v108
	v_mul_f32_e32 v104, v104, v104
	v_mul_f32_e32 v109, v105, v105
	v_max_f32_e32 v105, 0, v110
	v_mul_f32_e32 v110, v106, v106
	v_max_f32_e32 v106, 0, v111
	v_max_f32_e32 v107, 0, v107
	v_pk_mul_f32 v[96:97], v[96:97], v[114:115] op_sel_hi:[1,0]
	v_mul_f32_e32 v108, v108, v108
	v_mul_f32_e32 v105, v105, v105
	v_mul_f32_e32 v106, v106, v106
	v_mul_f32_e32 v107, v107, v107
	v_cvt_pk_bf16_f32 v104, v108, v104
	v_pk_mul_f32 v[100:101], v[100:101], v[114:115] op_sel_hi:[1,0]
	v_pk_mul_f32 v[98:99], v[98:99], v[114:115] op_sel_hi:[1,0]
	v_max_f32_e32 v96, 0, v96
	v_cvt_pk_bf16_f32 v105, v105, v106
	v_cvt_pk_bf16_f32 v106, v115, v109
	v_cvt_pk_bf16_f32 v107, v110, v107
	ds_bpermute_b32 v220, v228, v104
	ds_bpermute_b32 v221, v228, v105
	ds_bpermute_b32 v222, v228, v106
	ds_bpermute_b32 v223, v228, v107
	v_pk_mul_f32 v[102:103], v[102:103], v[114:115] op_sel_hi:[1,0]
	v_max_f32_e32 v97, 0, v97
	v_mul_f32_e32 v104, v96, v96
	v_max_f32_e32 v96, 0, v101
	v_max_f32_e32 v98, 0, v98
	v_max_f32_e32 v100, 0, v100
	v_mul_f32_e32 v96, v96, v96
	v_mul_f32_e32 v101, v97, v97
	v_max_f32_e32 v97, 0, v102
	v_mul_f32_e32 v102, v98, v98
	v_max_f32_e32 v98, 0, v103
	v_max_f32_e32 v99, 0, v99
	v_mul_f32_e32 v100, v100, v100
	v_mul_f32_e32 v97, v97, v97
	v_mul_f32_e32 v98, v98, v98
	v_mul_f32_e32 v99, v99, v99
	v_cvt_pk_bf16_f32 v96, v100, v96
	v_cvt_pk_bf16_f32 v97, v97, v98
	v_cvt_pk_bf16_f32 v98, v104, v101
	v_cvt_pk_bf16_f32 v99, v102, v99
	ds_bpermute_b32 v224, v228, v96
	ds_bpermute_b32 v225, v228, v97
	ds_bpermute_b32 v226, v228, v98
	ds_bpermute_b32 v227, v228, v99
	s_waitcnt lgkmcnt(4)
	global_store_dwordx4 v[112:113], v[220:223], off
	s_waitcnt lgkmcnt(0)
	global_store_dwordx4 v[112:113], v[224:227], off offset:256
	s_nop 1
	v_or_b32_e32 v96, 32, v152
	v_ashrrev_i32_e32 v97, 31, v96
	v_lshlrev_b64 v[96:97], 13, v[96:97]
	v_lshl_add_u64 v[96:97], s[78:79], 0, v[96:97]
	v_lshl_add_u64 v[96:97], v[96:97], 0, v[150:151]
	v_mov_b32_e32 v98, v188
	v_pk_mul_f32 v[88:89], v[88:89], v[98:99] op_sel_hi:[1,0]
	v_pk_mul_f32 v[92:93], v[92:93], v[98:99] op_sel_hi:[1,0]
	v_pk_mul_f32 v[90:91], v[90:91], v[98:99] op_sel_hi:[1,0]
	v_max_f32_e32 v88, 0, v88
	v_pk_mul_f32 v[94:95], v[94:95], v[98:99] op_sel_hi:[1,0]
	v_mul_f32_e32 v99, v88, v88
	v_max_f32_e32 v88, 0, v93
	v_max_f32_e32 v89, 0, v89
	v_max_f32_e32 v90, 0, v90
	v_max_f32_e32 v92, 0, v92
	v_mul_f32_e32 v88, v88, v88
	v_mul_f32_e32 v93, v89, v89
	v_max_f32_e32 v89, 0, v94
	v_mul_f32_e32 v94, v90, v90
	v_max_f32_e32 v90, 0, v95
	v_max_f32_e32 v91, 0, v91
	v_pk_mul_f32 v[80:81], v[80:81], v[98:99] op_sel_hi:[1,0]
	v_mul_f32_e32 v92, v92, v92
	v_mul_f32_e32 v89, v89, v89
	v_mul_f32_e32 v90, v90, v90
	v_mul_f32_e32 v91, v91, v91
	v_cvt_pk_bf16_f32 v88, v92, v88
	v_pk_mul_f32 v[84:85], v[84:85], v[98:99] op_sel_hi:[1,0]
	v_pk_mul_f32 v[82:83], v[82:83], v[98:99] op_sel_hi:[1,0]
	v_max_f32_e32 v80, 0, v80
	v_cvt_pk_bf16_f32 v89, v89, v90
	v_cvt_pk_bf16_f32 v90, v99, v93
	v_cvt_pk_bf16_f32 v91, v94, v91
	ds_bpermute_b32 v220, v228, v88
	ds_bpermute_b32 v221, v228, v89
	ds_bpermute_b32 v222, v228, v90
	ds_bpermute_b32 v223, v228, v91
	v_pk_mul_f32 v[86:87], v[86:87], v[98:99] op_sel_hi:[1,0]
	v_max_f32_e32 v81, 0, v81
	v_mul_f32_e32 v88, v80, v80
	v_max_f32_e32 v80, 0, v85
	v_max_f32_e32 v82, 0, v82
	v_max_f32_e32 v84, 0, v84
	v_mul_f32_e32 v80, v80, v80
	v_mul_f32_e32 v85, v81, v81
	v_max_f32_e32 v81, 0, v86
	v_mul_f32_e32 v86, v82, v82
	v_max_f32_e32 v82, 0, v87
	v_max_f32_e32 v83, 0, v83
	v_mul_f32_e32 v84, v84, v84
	v_mul_f32_e32 v81, v81, v81
	v_mul_f32_e32 v82, v82, v82
	v_mul_f32_e32 v83, v83, v83
	v_cvt_pk_bf16_f32 v80, v84, v80
	v_cvt_pk_bf16_f32 v81, v81, v82
	v_cvt_pk_bf16_f32 v82, v88, v85
	v_cvt_pk_bf16_f32 v83, v86, v83
	ds_bpermute_b32 v224, v228, v80
	ds_bpermute_b32 v225, v228, v81
	ds_bpermute_b32 v226, v228, v82
	ds_bpermute_b32 v227, v228, v83
	s_waitcnt lgkmcnt(4)
	global_store_dwordx4 v[96:97], v[220:223], off
	s_waitcnt lgkmcnt(0)
; __device__ __forceinline__ unsigned cvt_pk_bf16(float lo, float hi) { unsigned r; asm volatile("v_cvt_pk_bf16_f32 %0, %1, %2" : "=v"(r) : "v"(lo), "v"(hi)); return r; }
;     __device__ __forceinline__ void operator()(const f32x4 (&acc)[2][2][4][2], const Unit& u, int wr, int wc, int fr, int fq) const {
;     ...
;                 const int row = row0 + ai * HALF + m * 16;
;                 const f32x4* sp = (const f32x4*)(ss + (size_t)row * 16);
;                 const f32x4 a0 = sp[0], a1 = sp[1], a2 = sp[2], a3 = sp[3];
;                 const float tot = ((a0.x + a0.y) + (a0.z + a0.w)) + ((a1.x + a1.y) + (a1.z + a1.w)) + ((a2.x + a2.y) + (a2.z + a2.w)) + ((a3.x + a3.y) + (a3.z + a3.w));
;                 const float rs = rsqrtf(tot * (1.0f / 1024.0f) + 1e-6f);
;                 bf16_t* rowp = O + (size_t)row * ldc + col0;
; #pragma unroll
;                 for (int bj = 0; bj < 2; ++bj) {
;                     f32x4 v0 = acc[ai][bj][m][0] * rs, v1 = acc[ai][bj][m][1] * rs;
;                     if (ACT == 1) {
; #pragma unroll
;                         for (int e = 0; e < 4; ++e) { float a = fmaxf(v0[e], 0.f); v0[e] = a * a; float b = fmaxf(v1[e], 0.f); v1[e] = b * b; }
;                     }
;                     u32x4 w; w.x = cvt_pk_bf16(v0[0], v0[1]); w.y = cvt_pk_bf16(v0[2], v0[3]); w.z = cvt_pk_bf16(v1[0], v1[1]); w.w = cvt_pk_bf16(v1[2], v1[3]);
;                     *(u32x4*)(rowp + bj * HALF) = w;
	global_store_dwordx4 v[96:97], v[224:227], off offset:256
	s_nop 1
	v_or_b32_e32 v80, 48, v152
	v_ashrrev_i32_e32 v81, 31, v80
	v_lshlrev_b64 v[80:81], 13, v[80:81]
	v_lshl_add_u64 v[80:81], s[78:79], 0, v[80:81]
	v_lshl_add_u64 v[80:81], v[80:81], 0, v[150:151]
	v_mov_b32_e32 v82, v192
	v_pk_mul_f32 v[72:73], v[72:73], v[82:83] op_sel_hi:[1,0]
	v_pk_mul_f32 v[76:77], v[76:77], v[82:83] op_sel_hi:[1,0]
	v_pk_mul_f32 v[74:75], v[74:75], v[82:83] op_sel_hi:[1,0]
	v_max_f32_e32 v72, 0, v72
	v_pk_mul_f32 v[78:79], v[78:79], v[82:83] op_sel_hi:[1,0]
	v_mul_f32_e32 v83, v72, v72
	v_max_f32_e32 v72, 0, v77
	v_max_f32_e32 v73, 0, v73
	v_max_f32_e32 v74, 0, v74
	v_max_f32_e32 v76, 0, v76
	v_mul_f32_e32 v72, v72, v72
	v_mul_f32_e32 v77, v73, v73
	v_max_f32_e32 v73, 0, v78
	v_mul_f32_e32 v78, v74, v74
	v_max_f32_e32 v74, 0, v79
	v_max_f32_e32 v75, 0, v75
	v_pk_mul_f32 v[64:65], v[64:65], v[82:83] op_sel_hi:[1,0]
	v_mul_f32_e32 v76, v76, v76
	v_mul_f32_e32 v73, v73, v73
	v_mul_f32_e32 v74, v74, v74
	v_mul_f32_e32 v75, v75, v75
	v_cvt_pk_bf16_f32 v72, v76, v72
	v_pk_mul_f32 v[68:69], v[68:69], v[82:83] op_sel_hi:[1,0]
	v_pk_mul_f32 v[66:67], v[66:67], v[82:83] op_sel_hi:[1,0]
	v_max_f32_e32 v64, 0, v64
	v_cvt_pk_bf16_f32 v73, v73, v74
	v_cvt_pk_bf16_f32 v74, v83, v77
	v_cvt_pk_bf16_f32 v75, v78, v75
	ds_bpermute_b32 v220, v228, v72
	ds_bpermute_b32 v221, v228, v73
	ds_bpermute_b32 v222, v228, v74
	ds_bpermute_b32 v223, v228, v75
	v_pk_mul_f32 v[70:71], v[70:71], v[82:83] op_sel_hi:[1,0]
	v_max_f32_e32 v65, 0, v65
	v_mul_f32_e32 v72, v64, v64
	v_max_f32_e32 v64, 0, v69
	v_max_f32_e32 v66, 0, v66
	v_max_f32_e32 v68, 0, v68
	v_mul_f32_e32 v64, v64, v64
	v_mul_f32_e32 v69, v65, v65
	v_max_f32_e32 v65, 0, v70
	v_mul_f32_e32 v70, v66, v66
	v_max_f32_e32 v66, 0, v71
	v_max_f32_e32 v67, 0, v67
	v_mul_f32_e32 v68, v68, v68
	v_mul_f32_e32 v65, v65, v65
	v_mul_f32_e32 v66, v66, v66
	v_mul_f32_e32 v67, v67, v67
	v_cvt_pk_bf16_f32 v64, v68, v64
	v_cvt_pk_bf16_f32 v65, v65, v66
	v_cvt_pk_bf16_f32 v66, v72, v69
	v_cvt_pk_bf16_f32 v67, v70, v67
	ds_bpermute_b32 v224, v228, v64
	ds_bpermute_b32 v225, v228, v65
	ds_bpermute_b32 v226, v228, v66
	ds_bpermute_b32 v227, v228, v67
	s_waitcnt lgkmcnt(4)
	global_store_dwordx4 v[80:81], v[220:223], off
	s_waitcnt lgkmcnt(0)
	global_store_dwordx4 v[80:81], v[224:227], off offset:256
	s_nop 1
	v_add_u32_e32 v64, 0x80, v152
	v_ashrrev_i32_e32 v65, 31, v64
	v_lshlrev_b64 v[64:65], 13, v[64:65]
	v_lshl_add_u64 v[64:65], s[78:79], 0, v[64:65]
	v_lshl_add_u64 v[64:65], v[64:65], 0, v[150:151]
	s_waitcnt vmcnt(8)
	v_add_f32_e32 v196, v196, v197
	v_add_f32_e32 v198, v198, v199
	v_add_f32_e32 v208, v208, v209
	v_add_f32_e32 v210, v210, v211
	v_add_f32_e32 v212, v212, v213
	v_add_f32_e32 v214, v214, v215
	v_add_f32_e32 v216, v216, v217
	v_add_f32_e32 v218, v218, v219
	v_add_f32_e32 v196, v196, v198
	v_add_f32_e32 v208, v208, v210
	v_add_f32_e32 v212, v212, v214
	v_add_f32_e32 v216, v216, v218
	v_mov_b32_e32 v197, v196
	v_mov_b32_e32 v209, v208
	v_mov_b32_e32 v213, v212
	v_mov_b32_e32 v217, v216
	s_nop 1
	v_permlane16_swap_b32_e32 v196, v197
	v_permlane16_swap_b32_e32 v208, v209
	v_permlane16_swap_b32_e32 v212, v213
	v_permlane16_swap_b32_e32 v216, v217
	v_add_f32_e32 v196, v196, v197
	v_add_f32_e32 v208, v208, v209
	v_add_f32_e32 v212, v212, v213
	v_add_f32_e32 v216, v216, v217
	v_mov_b32_e32 v197, v196
	v_mov_b32_e32 v209, v208
	v_mov_b32_e32 v213, v212
	v_mov_b32_e32 v217, v216
	s_nop 1
	v_permlane32_swap_b32_e32 v196, v197
	v_permlane32_swap_b32_e32 v208, v209
	v_permlane32_swap_b32_e32 v212, v213
	v_permlane32_swap_b32_e32 v216, v217
	v_add_f32_e32 v196, v196, v197
	v_add_f32_e32 v208, v208, v209
	v_add_f32_e32 v212, v212, v213
	v_add_f32_e32 v216, v216, v217
	v_fmamk_f32 v196, v196, 0x3a800000, v137
	v_cmp_gt_f32_e32 vcc, s4, v196
	v_mul_f32_e32 v197, 0x4b800000, v196
	s_nop 0
	v_cndmask_b32_e32 v196, v196, v197, vcc
	v_rsq_f32_e32 v196, v196
	s_nop 0
	v_mul_f32_e32 v197, 0x45800000, v196
	v_cndmask_b32_e32 v196, v196, v197, vcc
	v_fmamk_f32 v208, v208, 0x3a800000, v137
	v_cmp_gt_f32_e32 vcc, s4, v208
	v_mul_f32_e32 v209, 0x4b800000, v208
	s_nop 0
	v_cndmask_b32_e32 v208, v208, v209, vcc
	v_rsq_f32_e32 v208, v208
	s_nop 0
	v_mul_f32_e32 v209, 0x45800000, v208
	v_cndmask_b32_e32 v208, v208, v209, vcc
	v_fmamk_f32 v212, v212, 0x3a800000, v137
	v_cmp_gt_f32_e32 vcc, s4, v212
	v_mul_f32_e32 v213, 0x4b800000, v212
	s_nop 0
	v_cndmask_b32_e32 v212, v212, v213, vcc
	v_rsq_f32_e32 v212, v212
	s_nop 0
	v_mul_f32_e32 v213, 0x45800000, v212
	v_cndmask_b32_e32 v212, v212, v213, vcc
	v_fmamk_f32 v216, v216, 0x3a800000, v137
	v_cmp_gt_f32_e32 vcc, s4, v216
	v_mul_f32_e32 v217, 0x4b800000, v216
	s_nop 0
	v_cndmask_b32_e32 v216, v216, v217, vcc
	v_rsq_f32_e32 v216, v216
	s_nop 0
	v_mul_f32_e32 v217, 0x45800000, v216
	v_cndmask_b32_e32 v216, v216, v217, vcc
	v_mov_b32_e32 v66, v196
	v_pk_mul_f32 v[56:57], v[56:57], v[66:67] op_sel_hi:[1,0]
	v_pk_mul_f32 v[60:61], v[60:61], v[66:67] op_sel_hi:[1,0]
	v_pk_mul_f32 v[58:59], v[58:59], v[66:67] op_sel_hi:[1,0]
	v_max_f32_e32 v56, 0, v56
	v_pk_mul_f32 v[62:63], v[62:63], v[66:67] op_sel_hi:[1,0]
	v_mul_f32_e32 v67, v56, v56
	v_max_f32_e32 v56, 0, v61
	v_max_f32_e32 v57, 0, v57
	v_max_f32_e32 v58, 0, v58
	v_max_f32_e32 v60, 0, v60
	v_mul_f32_e32 v56, v56, v56
	v_mul_f32_e32 v61, v57, v57
	v_max_f32_e32 v57, 0, v62
	v_mul_f32_e32 v62, v58, v58
	v_max_f32_e32 v58, 0, v63
	v_max_f32_e32 v59, 0, v59
	v_pk_mul_f32 v[48:49], v[48:49], v[66:67] op_sel_hi:[1,0]
	v_mul_f32_e32 v60, v60, v60
	v_mul_f32_e32 v57, v57, v57
	v_mul_f32_e32 v58, v58, v58
	v_mul_f32_e32 v59, v59, v59
	v_cvt_pk_bf16_f32 v56, v60, v56
	v_pk_mul_f32 v[52:53], v[52:53], v[66:67] op_sel_hi:[1,0]
	v_pk_mul_f32 v[50:51], v[50:51], v[66:67] op_sel_hi:[1,0]
	v_max_f32_e32 v48, 0, v48
	v_cvt_pk_bf16_f32 v57, v57, v58
	v_cvt_pk_bf16_f32 v58, v67, v61
	v_cvt_pk_bf16_f32 v59, v62, v59
	ds_bpermute_b32 v220, v228, v56
	ds_bpermute_b32 v221, v228, v57
	ds_bpermute_b32 v222, v228, v58
	ds_bpermute_b32 v223, v228, v59
	v_pk_mul_f32 v[54:55], v[54:55], v[66:67] op_sel_hi:[1,0]
	v_max_f32_e32 v49, 0, v49
	v_mul_f32_e32 v56, v48, v48
	v_max_f32_e32 v48, 0, v53
	v_max_f32_e32 v50, 0, v50
	v_max_f32_e32 v52, 0, v52
	v_mul_f32_e32 v48, v48, v48
	v_mul_f32_e32 v53, v49, v49
	v_max_f32_e32 v49, 0, v54
	v_mul_f32_e32 v54, v50, v50
	v_max_f32_e32 v50, 0, v55
	v_max_f32_e32 v51, 0, v51
	v_mul_f32_e32 v52, v52, v52
	v_mul_f32_e32 v49, v49, v49
	v_mul_f32_e32 v50, v50, v50
	v_mul_f32_e32 v51, v51, v51
	v_cvt_pk_bf16_f32 v48, v52, v48
	v_cvt_pk_bf16_f32 v49, v49, v50
	v_cvt_pk_bf16_f32 v50, v56, v53
	v_cvt_pk_bf16_f32 v51, v54, v51
	ds_bpermute_b32 v224, v228, v48
	ds_bpermute_b32 v225, v228, v49
	ds_bpermute_b32 v226, v228, v50
	ds_bpermute_b32 v227, v228, v51
	s_waitcnt lgkmcnt(4)
; __device__ __forceinline__ unsigned cvt_pk_bf16(float lo, float hi) { unsigned r; asm volatile("v_cvt_pk_bf16_f32 %0, %1, %2" : "=v"(r) : "v"(lo), "v"(hi)); return r; }
; #define PG8_BAR __builtin_amdgcn_s_barrier()
;     __device__ __forceinline__ void operator()(const f32x4 (&acc)[2][2][4][2], const Unit& u, int wr, int wc, int fr, int fq) const {
;     ...
;                 bf16_t* rowp = O + (size_t)row * ldc + col0;
; #pragma unroll
;                 for (int bj = 0; bj < 2; ++bj) {
;                     f32x4 v0 = acc[ai][bj][m][0] * rs, v1 = acc[ai][bj][m][1] * rs;
;                     if (ACT == 1) {
; #pragma unroll
;                         for (int e = 0; e < 4; ++e) { float a = fmaxf(v0[e], 0.f); v0[e] = a * a; float b = fmaxf(v1[e], 0.f); v1[e] = b * b; }
;                     }
;                     u32x4 w; w.x = cvt_pk_bf16(v0[0], v0[1]); w.y = cvt_pk_bf16(v0[2], v0[3]); w.z = cvt_pk_bf16(v1[0], v1[1]); w.w = cvt_pk_bf16(v1[2], v1[3]);
;                     *(u32x4*)(rowp + bj * HALF) = w;
; template <class Epi, class Sched, bool ALIGN_EPI = false, bool SP2 = false>
; __device__ __forceinline__ void gemm_phase(PG8_LAS unsigned char* lds, const Gemm g, const Sched& S, const Epi& E) {
;     ...
;         if (!has_next) break;
; #pragma unroll
;         for (int a = 0; a < 2; ++a)
; #pragma unroll
;             for (int b = 0; b < 2; ++b)
; #pragma unroll
;                 for (int m = 0; m < 4; ++m)
; #pragma unroll
;                     for (int n = 0; n < 2; ++n) acc[a][b][m][n] = (f32x4){0.f, 0.f, 0.f, 0.f};
;         cur = nxt; cA = nA; cB = nB; ++ui;
;         if constexpr (ALIGN_EPI) { if (wr == 1) PG8_BAR; }
	global_store_dwordx4 v[64:65], v[220:223], off
	s_waitcnt lgkmcnt(0)
	global_store_dwordx4 v[64:65], v[224:227], off offset:256
	s_nop 1
	v_add_u32_e32 v48, 0x90, v152
	v_ashrrev_i32_e32 v49, 31, v48
	v_lshlrev_b64 v[48:49], 13, v[48:49]
	v_lshl_add_u64 v[48:49], s[78:79], 0, v[48:49]
	v_lshl_add_u64 v[48:49], v[48:49], 0, v[150:151]
	v_mov_b32_e32 v50, v208
	v_pk_mul_f32 v[40:41], v[40:41], v[50:51] op_sel_hi:[1,0]
	v_pk_mul_f32 v[44:45], v[44:45], v[50:51] op_sel_hi:[1,0]
	v_pk_mul_f32 v[42:43], v[42:43], v[50:51] op_sel_hi:[1,0]
	v_max_f32_e32 v40, 0, v40
	v_pk_mul_f32 v[46:47], v[46:47], v[50:51] op_sel_hi:[1,0]
	v_mul_f32_e32 v51, v40, v40
	v_max_f32_e32 v40, 0, v45
	v_max_f32_e32 v41, 0, v41
	v_max_f32_e32 v42, 0, v42
	v_max_f32_e32 v44, 0, v44
	v_mul_f32_e32 v40, v40, v40
	v_mul_f32_e32 v45, v41, v41
	v_max_f32_e32 v41, 0, v46
	v_mul_f32_e32 v46, v42, v42
	v_max_f32_e32 v42, 0, v47
	v_max_f32_e32 v43, 0, v43
	v_pk_mul_f32 v[32:33], v[32:33], v[50:51] op_sel_hi:[1,0]
	v_mul_f32_e32 v44, v44, v44
	v_mul_f32_e32 v41, v41, v41
	v_mul_f32_e32 v42, v42, v42
	v_mul_f32_e32 v43, v43, v43
	v_cvt_pk_bf16_f32 v40, v44, v40
	v_pk_mul_f32 v[36:37], v[36:37], v[50:51] op_sel_hi:[1,0]
	v_pk_mul_f32 v[34:35], v[34:35], v[50:51] op_sel_hi:[1,0]
	v_max_f32_e32 v32, 0, v32
	v_cvt_pk_bf16_f32 v41, v41, v42
	v_cvt_pk_bf16_f32 v42, v51, v45
	v_cvt_pk_bf16_f32 v43, v46, v43
	ds_bpermute_b32 v220, v228, v40
	ds_bpermute_b32 v221, v228, v41
	ds_bpermute_b32 v222, v228, v42
	ds_bpermute_b32 v223, v228, v43
	v_pk_mul_f32 v[38:39], v[38:39], v[50:51] op_sel_hi:[1,0]
	v_max_f32_e32 v33, 0, v33
	v_mul_f32_e32 v40, v32, v32
	v_max_f32_e32 v32, 0, v37
	v_max_f32_e32 v34, 0, v34
	v_max_f32_e32 v36, 0, v36
	v_mul_f32_e32 v32, v32, v32
	v_mul_f32_e32 v37, v33, v33
	v_max_f32_e32 v33, 0, v38
	v_mul_f32_e32 v38, v34, v34
	v_max_f32_e32 v34, 0, v39
	v_max_f32_e32 v35, 0, v35
	v_mul_f32_e32 v36, v36, v36
	v_mul_f32_e32 v33, v33, v33
	v_mul_f32_e32 v34, v34, v34
	v_mul_f32_e32 v35, v35, v35
	v_cvt_pk_bf16_f32 v32, v36, v32
	v_cvt_pk_bf16_f32 v33, v33, v34
	v_cvt_pk_bf16_f32 v34, v40, v37
	v_cvt_pk_bf16_f32 v35, v38, v35
	ds_bpermute_b32 v224, v228, v32
	ds_bpermute_b32 v225, v228, v33
	ds_bpermute_b32 v226, v228, v34
	ds_bpermute_b32 v227, v228, v35
	s_waitcnt lgkmcnt(4)
	global_store_dwordx4 v[48:49], v[220:223], off
	s_waitcnt lgkmcnt(0)
	global_store_dwordx4 v[48:49], v[224:227], off offset:256
	s_nop 1
	v_add_u32_e32 v32, 0xa0, v152
	v_ashrrev_i32_e32 v33, 31, v32
	v_lshlrev_b64 v[32:33], 13, v[32:33]
	v_lshl_add_u64 v[32:33], s[78:79], 0, v[32:33]
	v_lshl_add_u64 v[32:33], v[32:33], 0, v[150:151]
	v_mov_b32_e32 v34, v212
	v_pk_mul_f32 v[24:25], v[24:25], v[34:35] op_sel_hi:[1,0]
	v_pk_mul_f32 v[28:29], v[28:29], v[34:35] op_sel_hi:[1,0]
	v_pk_mul_f32 v[26:27], v[26:27], v[34:35] op_sel_hi:[1,0]
	v_max_f32_e32 v24, 0, v24
	v_pk_mul_f32 v[30:31], v[30:31], v[34:35] op_sel_hi:[1,0]
	v_mul_f32_e32 v35, v24, v24
	v_max_f32_e32 v24, 0, v29
	v_max_f32_e32 v25, 0, v25
	v_max_f32_e32 v26, 0, v26
	v_max_f32_e32 v28, 0, v28
	v_mul_f32_e32 v24, v24, v24
	v_mul_f32_e32 v29, v25, v25
	v_max_f32_e32 v25, 0, v30
	v_mul_f32_e32 v30, v26, v26
	v_max_f32_e32 v26, 0, v31
	v_max_f32_e32 v27, 0, v27
	v_pk_mul_f32 v[16:17], v[16:17], v[34:35] op_sel_hi:[1,0]
	v_mul_f32_e32 v28, v28, v28
	v_mul_f32_e32 v25, v25, v25
	v_mul_f32_e32 v26, v26, v26
	v_mul_f32_e32 v27, v27, v27
	v_cvt_pk_bf16_f32 v24, v28, v24
	v_pk_mul_f32 v[20:21], v[20:21], v[34:35] op_sel_hi:[1,0]
	v_pk_mul_f32 v[18:19], v[18:19], v[34:35] op_sel_hi:[1,0]
	v_max_f32_e32 v16, 0, v16
	v_cvt_pk_bf16_f32 v25, v25, v26
	v_cvt_pk_bf16_f32 v26, v35, v29
	v_cvt_pk_bf16_f32 v27, v30, v27
	ds_bpermute_b32 v220, v228, v24
	ds_bpermute_b32 v221, v228, v25
	ds_bpermute_b32 v222, v228, v26
	ds_bpermute_b32 v223, v228, v27
	v_pk_mul_f32 v[22:23], v[22:23], v[34:35] op_sel_hi:[1,0]
	v_max_f32_e32 v17, 0, v17
	v_mul_f32_e32 v24, v16, v16
	v_max_f32_e32 v16, 0, v21
	v_max_f32_e32 v18, 0, v18
	v_max_f32_e32 v20, 0, v20
	v_mul_f32_e32 v16, v16, v16
	v_mul_f32_e32 v21, v17, v17
	v_max_f32_e32 v17, 0, v22
	v_mul_f32_e32 v22, v18, v18
	v_max_f32_e32 v18, 0, v23
	v_max_f32_e32 v19, 0, v19
	v_mul_f32_e32 v20, v20, v20
	v_mul_f32_e32 v17, v17, v17
	v_mul_f32_e32 v18, v18, v18
	v_mul_f32_e32 v19, v19, v19
	v_cvt_pk_bf16_f32 v16, v20, v16
	v_cvt_pk_bf16_f32 v17, v17, v18
	v_cvt_pk_bf16_f32 v18, v24, v21
	v_cvt_pk_bf16_f32 v19, v22, v19
	ds_bpermute_b32 v224, v228, v16
	ds_bpermute_b32 v225, v228, v17
	ds_bpermute_b32 v226, v228, v18
	ds_bpermute_b32 v227, v228, v19
	s_waitcnt lgkmcnt(4)
	global_store_dwordx4 v[32:33], v[220:223], off
	s_waitcnt lgkmcnt(0)
	global_store_dwordx4 v[32:33], v[224:227], off offset:256
	s_nop 1
	v_add_u32_e32 v16, 0xb0, v152
	v_ashrrev_i32_e32 v17, 31, v16
	v_lshlrev_b64 v[16:17], 13, v[16:17]
	v_lshl_add_u64 v[16:17], s[78:79], 0, v[16:17]
	v_lshl_add_u64 v[16:17], v[16:17], 0, v[150:151]
	v_mov_b32_e32 v18, v216
	v_pk_mul_f32 v[8:9], v[8:9], v[18:19] op_sel_hi:[1,0]
	v_pk_mul_f32 v[12:13], v[12:13], v[18:19] op_sel_hi:[1,0]
	v_pk_mul_f32 v[10:11], v[10:11], v[18:19] op_sel_hi:[1,0]
	v_max_f32_e32 v8, 0, v8
	v_pk_mul_f32 v[14:15], v[14:15], v[18:19] op_sel_hi:[1,0]
	v_mul_f32_e32 v19, v8, v8
	v_max_f32_e32 v8, 0, v13
	v_max_f32_e32 v9, 0, v9
	v_max_f32_e32 v10, 0, v10
	v_max_f32_e32 v12, 0, v12
	v_mul_f32_e32 v8, v8, v8
	v_mul_f32_e32 v13, v9, v9
	v_max_f32_e32 v9, 0, v14
	v_mul_f32_e32 v14, v10, v10
	v_max_f32_e32 v10, 0, v15
	v_max_f32_e32 v11, 0, v11
	v_pk_mul_f32 v[2:3], v[2:3], v[18:19] op_sel_hi:[1,0]
	v_pk_mul_f32 v[0:1], v[0:1], v[18:19] op_sel_hi:[1,0]
	v_mul_f32_e32 v12, v12, v12
	v_mul_f32_e32 v9, v9, v9
	v_mul_f32_e32 v10, v10, v10
	v_mul_f32_e32 v11, v11, v11
	v_cvt_pk_bf16_f32 v8, v12, v8
	v_pk_mul_f32 v[6:7], v[6:7], v[18:19] op_sel_hi:[1,0]
	v_pk_mul_f32 v[4:5], v[4:5], v[18:19] op_sel_hi:[1,0]
	v_max_f32_e32 v0, 0, v0
	v_max_f32_e32 v1, 0, v1
	v_max_f32_e32 v2, 0, v2
	v_cvt_pk_bf16_f32 v9, v9, v10
	v_cvt_pk_bf16_f32 v10, v19, v13
	v_cvt_pk_bf16_f32 v11, v14, v11
	ds_bpermute_b32 v220, v228, v8
	ds_bpermute_b32 v221, v228, v9
	ds_bpermute_b32 v222, v228, v10
	ds_bpermute_b32 v223, v228, v11
	v_max_f32_e32 v3, 0, v3
	v_max_f32_e32 v4, 0, v4
	v_mul_f32_e32 v8, v0, v0
	v_max_f32_e32 v0, 0, v5
	v_mul_f32_e32 v5, v1, v1
	v_max_f32_e32 v1, 0, v6
	v_mul_f32_e32 v6, v2, v2
	v_max_f32_e32 v2, 0, v7
	v_mul_f32_e32 v0, v0, v0
	v_mul_f32_e32 v1, v1, v1
	v_mul_f32_e32 v2, v2, v2
	v_mul_f32_e32 v3, v3, v3
	s_andn2_b64 vcc, exec, s[38:39]
	v_mul_f32_e32 v4, v4, v4
	v_cvt_pk_bf16_f32 v0, v4, v0
	v_cvt_pk_bf16_f32 v1, v1, v2
	v_cvt_pk_bf16_f32 v2, v8, v5
	v_cvt_pk_bf16_f32 v3, v6, v3
	ds_bpermute_b32 v224, v228, v0
	ds_bpermute_b32 v225, v228, v1
	ds_bpermute_b32 v226, v228, v2
	ds_bpermute_b32 v227, v228, v3
	s_waitcnt lgkmcnt(4)
	global_store_dwordx4 v[16:17], v[220:223], off
	s_waitcnt lgkmcnt(0)
	global_store_dwordx4 v[16:17], v[224:227], off offset:256
	s_cbranch_vccnz .LBB0_1144
	s_andn2_b64 vcc, exec, s[0:1]
	s_cbranch_vccnz .LBB0_1143
	s_setprio 1
	s_barrier
	s_branch .LBB0_1143

; #define PG8_STAGE(bufoff, gbase, voff) do { _Pragma("unroll") for (int _i = 0; _i < 2; ++_i) \
;         __builtin_amdgcn_global_load_lds((const unsigned*)((const char*)(gbase) + (voff)[_i]), (PG8_LAS unsigned*)(lds + (bufoff) + ldsw + _i * 8192), 16, 0, 0); } while (0)
; #define PG8_BAR __builtin_amdgcn_s_barrier()
; template <class Epi, class Sched, bool ALIGN_EPI = false, bool SP2 = false>
; __device__ __forceinline__ void gemm_phase(PG8_LAS unsigned char* lds, const Gemm g, const Sched& S, const Epi& E) {
;     ...
;     for (int i = 0; i < 2; ++i) { int R, C; stage_rc(tid * 16 + i * 8192, R, C); const int Rb = Epi::PERM ? ((R & ~31) + perm32(R & 31)) : R;
;         voffA[i] = (unsigned)(R * K + C) * 2u; voffB[i] = (unsigned)(Rb * K + C) * 2u; }
;     const size_t kstep = (size_t)(BK * 2);
;     const size_t hstep = (size_t)HALF * K * 2;
;     const size_t tstep = 2 * hstep;
;     const unsigned ldsw = (unsigned)wid * 1024u;
;     const int aoff = lds_byte(wr * 64 + fr, fq * 8), boff = lds_byte(wc * 32 + fr, fq * 8);
;     ...
;     const char* cA = (const char*)g.A + (size_t)cur.pm * tstep; const char* cB = (const char*)g.Bt + (size_t)cur.pn * tstep;
;     S.a_ready(cur);
;     if constexpr (SP2) {
;         PG8_STAGE(PG8_SB(0, 0), cB, voffB); PG8_STAGE(PG8_SB(0, 1), cB + hstep, voffB); PG8_STAGE(PG8_SA(0, 0), cA, voffA); PG8_STAGE(PG8_SA(0, 1), cA + hstep, voffA);
;         if (wr == 1) PG8_BAR;
.LBB0_1215:
	s_andn2_b64 vcc, exec, s[0:1]
	s_cbranch_vccnz .LBB0_413
	v_mov_b32_e32 v10, v204
	s_and_b64 vcc, exec, s[48:49]
	v_readfirstlane_b32 s24, v10
	s_cbranch_vccnz .LBB0_1284
	v_lshlrev_b32_e32 v0, 4, v10
	s_waitcnt lgkmcnt(0)
	v_add_u32_e32 v1, 0x2000, v0
	v_ashrrev_i32_e32 v2, 31, v1
	v_lshrrev_b32_e32 v2, 22, v2
	v_add_u32_e32 v2, v1, v2
	v_ashrrev_i32_e32 v4, 10, v2
	v_mul_i32_i24_e32 v2, 0x400, v4
	v_sub_u32_e32 v1, v1, v2
	v_lshrrev_b32_e32 v2, 4, v1
	v_bitop3_b32 v1, v2, v1, 32 bitop3:0x6c
	v_ashrrev_i32_e32 v2, 31, v1
	v_lshrrev_b32_e32 v2, 26, v2
	v_add_u32_e32 v2, v1, v2
	v_lshlrev_b32_e32 v3, 3, v4
	s_lshl_b32 s0, s45, 23
	v_readlane_b32 s1, v251, 32
	v_ashrrev_i32_e32 v5, 6, v2
	v_and_b32_e32 v3, -16, v3
	s_add_u32 s42, s1, s0
	v_readlane_b32 s0, v251, 33
	v_add_u32_e32 v3, v5, v3
	s_addc_u32 s43, s0, 0
	v_and_b32_e32 v6, 3, v5
	s_mov_b32 s0, 0x7ffe0
	v_lshrrev_b32_e32 v7, 2, v3
	v_lshlrev_b32_e32 v8, 1, v3
	v_and_b32_e32 v2, 0xc0, v2
	v_and_or_b32 v6, v3, s0, v6
	v_and_b32_e32 v7, 4, v7
	v_and_b32_e32 v8, 24, v8
	v_sub_u32_e32 v1, v1, v2
	v_or3_b32 v7, v6, v7, v8
	v_lshlrev_b32_e32 v6, 5, v4
	v_ashrrev_i16_sdwa v1, v205, sext(v1) dst_sel:DWORD dst_unused:UNUSED_PAD src0_sel:DWORD src1_sel:BYTE_0
	v_and_b32_e32 v8, 32, v6
	v_bfe_i32 v6, v1, 0, 16
	v_add_lshl_u32 v1, v8, v6, 1
	v_lshl_add_u32 v128, v7, 13, v1
	v_lshl_add_u32 v130, v3, 13, v1
	v_bfe_i32 v1, v10, 27, 1
	v_lshrrev_b32_e32 v1, 22, v1
	v_add_u32_e32 v1, v0, v1
	v_and_b32_e32 v1, 0xfffffc00, v1
	v_sub_u32_e32 v0, v0, v1
	v_lshrrev_b32_e32 v1, 4, v0
	v_ashrrev_i32_e32 v2, 31, v10
	v_bitop3_b32 v0, v1, v0, 32 bitop3:0x6c
	v_lshrrev_b32_e32 v2, 26, v2
	v_ashrrev_i32_e32 v1, 31, v0
	v_add_u32_e32 v2, v10, v2
	v_lshrrev_b32_e32 v1, 26, v1
	v_ashrrev_i32_e32 v8, 6, v2
	v_add_u32_e32 v1, v0, v1
	v_lshlrev_b32_e32 v2, 3, v8
	v_ashrrev_i32_e32 v7, 6, v1
	v_and_b32_e32 v2, -16, v2
	v_add_u32_e32 v2, v7, v2
	v_and_b32_e32 v3, 3, v7
	v_lshrrev_b32_e32 v9, 2, v2
	v_lshlrev_b32_e32 v11, 1, v2
	v_and_b32_e32 v1, 0xc0, v1
	s_ashr_i32 s25, s24, 6
	v_and_or_b32 v3, v2, s0, v3
	v_and_b32_e32 v9, 4, v9
	v_and_b32_e32 v11, 24, v11
	v_sub_u32_e32 v0, v0, v1
	s_ashr_i32 s1, s24, 8
	s_lshl_b32 s54, s25, 10
	v_or3_b32 v3, v3, v9, v11
	v_lshlrev_b32_e32 v9, 5, v8
	v_ashrrev_i16_sdwa v0, v205, sext(v0) dst_sel:DWORD dst_unused:UNUSED_PAD src0_sel:DWORD src1_sel:BYTE_0
	v_readlane_b32 s22, v251, 54
	v_and_b32_e32 v11, 32, v9
	v_bfe_i32 v9, v0, 0, 16
	v_readlane_b32 s23, v251, 55
	s_add_u32 s26, s42, s22
	v_add_lshl_u32 v0, v11, v9, 1
	s_addc_u32 s27, s43, s23
	s_add_i32 s55, s54, 0
	v_lshl_add_u32 v132, v3, 13, v0
	s_add_i32 m0, s55, 0x10000
	v_lshl_add_u32 v134, v2, 13, v0
	global_load_lds_dwordx4 v132, s[26:27]
	s_add_i32 m0, s55, 0x12000
	s_add_u32 s22, s26, 0x100000
	global_load_lds_dwordx4 v128, s[26:27]
	s_addc_u32 s23, s27, 0
	s_add_i32 m0, s55, 0x14000
	s_add_i32 s88, s55, 0x2000
	global_load_lds_dwordx4 v132, s[22:23]
	s_add_i32 m0, s55, 0x16000
	v_writelane_b32 v250, s95, 34
	global_load_lds_dwordx4 v128, s[22:23]
	v_readlane_b32 s22, v251, 62
	s_mov_b32 m0, s55
	v_readlane_b32 s23, v251, 63
	s_add_i32 s89, s55, 0x4000
	s_add_i32 s30, s55, 0x6000
	s_cmp_eq_u32 s1, 1
	v_mov_b32_e32 v133, v139
	v_mov_b32_e32 v129, v139
	global_load_lds_dwordx4 v134, s[22:23]
	s_mov_b32 m0, s88
	v_lshl_add_u64 v[0:1], s[26:27], 0, v[132:133]
	global_load_lds_dwordx4 v130, s[22:23]
	v_readlane_b32 s22, v250, 0
	s_mov_b32 m0, s89
	v_readlane_b32 s23, v250, 1
	v_lshl_add_u64 v[2:3], s[26:27], 0, v[128:129]
	s_nop 3
	global_load_lds_dwordx4 v134, s[22:23]
	s_mov_b32 m0, s30
	s_nop 0
	global_load_lds_dwordx4 v130, s[22:23]
	s_cselect_b64 s[22:23], -1, 0
	v_writelane_b32 v250, s22, 32
	s_cmp_lg_u32 s1, 1
	s_nop 0
	v_writelane_b32 v250, s23, 33
	s_cbranch_scc1 .LBB0_1219
	s_setprio 1
	s_barrier

; #define PG8_STAGE(bufoff, gbase, voff) do { _Pragma("unroll") for (int _i = 0; _i < 2; ++_i) \
;         __builtin_amdgcn_global_load_lds((const unsigned*)((const char*)(gbase) + (voff)[_i]), (PG8_LAS unsigned*)(lds + (bufoff) + ldsw + _i * 8192), 16, 0, 0); } while (0)
; #define PG8_LDA(dst, b, h) do { _Pragma("unroll") for (int m = 0; m < 4; ++m) _Pragma("unroll") for (int k = 0; k < 2; ++k) dst[m][k] = *(const PG8_LAS bf16x8*)(lds + PG8_SA(b, h) + aoff + m * 2048 + k * 1024); } while (0)
; #define PG8_LDB(dst, b, h) do { _Pragma("unroll") for (int n = 0; n < 2; ++n) _Pragma("unroll") for (int k = 0; k < 2; ++k) dst[n][k] = *(const PG8_LAS bf16x8*)(lds + PG8_SB(b, h) + boff + n * 2048 + k * 1024); } while (0)
; #define PG8_MMA(ai, bj, At, Bt) do { __builtin_amdgcn_s_setprio(1); _Pragma("unroll") for (int m = 0; m < 4; ++m) _Pragma("unroll") for (int n = 0; n < 2; ++n) _Pragma("unroll") for (int k = 0; k < 2; ++k) \
;         acc[ai][bj][m][n] = __builtin_amdgcn_mfma_f32_16x16x32_bf16(Bt[n][k], At[m][k], acc[ai][bj][m][n], 0, 0, 0); __builtin_amdgcn_s_setprio(0); } while (0)
; #define PG8_WAIT_V(n) asm volatile("s_waitcnt vmcnt(" #n ")" ::: "memory")
; #define PG8_BAR __builtin_amdgcn_s_barrier()
; template <class Epi, class Sched, bool ALIGN_EPI = false, bool SP2 = false>
; __device__ __forceinline__ void gemm_phase(PG8_LAS unsigned char* lds, const Gemm g, const Sched& S, const Epi& E) {
;     ...
;         for (int t = 0; t < nt; t += 2) {
;             const bool last = (t == nt - 2);
;             const char* a1 = cA + (size_t)(t + 1) * kstep;
;             const char* a2 = last ? nA : cA + (size_t)(t + 2) * kstep; const char* b2 = last ? nB : cB + (size_t)(t + 2) * kstep;
;             const char* a3 = a2 + kstep; const char* b3 = b2 + kstep;
;             if (last && has_next) S.a_ready(nxt);
;             if constexpr (SP2) {
;             PG8_LDB(B0, 0, 0); PG8_LDB(B1, 0, 1); PG8_SCHED; PG8_LDA(At, 0, 0); PG8_STAGE(PG8_SA(1, 1), a1 + hstep, voffA);
;             PG8_WAIT_V(8); PG8_WAIT_L(0); PG8_BAR; PG8_MMA(0, 0, At, B0); PG8_MMA(0, 1, At, B1); PG8_BAR; PG8_SCHED;
;             PG8_LDA(At, 0, 1); PG8_STAGE(PG8_SB(0, 0), b2, voffB); PG8_STAGE(PG8_SB(0, 1), b2 + hstep, voffB); PG8_STAGE(PG8_SA(0, 0), a2, voffA);
;             PG8_WAIT_V(8); PG8_WAIT_L(0); PG8_BAR; PG8_MMA(1, 0, At, B0); PG8_MMA(1, 1, At, B1); PG8_BAR; PG8_SCHED;
.LBB0_1229:
	s_add_u32 s26, s24, 0xfff00080
	s_addc_u32 s27, s25, -1
	s_add_i32 s76, 0, 0x10000
	s_cmp_eq_u32 s96, 60
	s_cselect_b32 s41, s59, s27
	s_cselect_b32 s40, vcc_lo, s26
	v_add_u32_e32 v138, s76, v157
	s_cselect_b32 s27, s75, s95
	s_cselect_b32 s26, vcc_hi, s94
	s_add_i32 s97, 0, 0x14000
	ds_read_b128 v[152:155], v138
	ds_read_b128 v[160:163], v138 offset:1024
	ds_read_b128 v[164:167], v138 offset:2048
	ds_read_b128 v[168:171], v138 offset:3072
	v_add_u32_e32 v138, s97, v157
	ds_read_b128 v[172:175], v138
	ds_read_b128 v[176:179], v138 offset:1024
	ds_read_b128 v[180:183], v138 offset:2048
	ds_read_b128 v[184:187], v138 offset:3072
	v_lshl_add_u64 v[224:225], s[24:25], 0, v[148:149]
	s_add_i32 m0, s55, 0xc000
	ds_read_b128 v[188:191], v159
	ds_read_b128 v[192:195], v159 offset:1024
	ds_read_b128 v[196:199], v159 offset:2048
	ds_read_b128 v[200:203], v159 offset:3072
	ds_read_b128 v[208:211], v159 offset:4096
	ds_read_b128 v[212:215], v159 offset:5120
	ds_read_b128 v[216:219], v159 offset:6144
	ds_read_b128 v[220:223], v159 offset:7168
	global_load_lds_dwordx4 v[224:225], off
	v_lshl_add_u64 v[224:225], s[24:25], 0, v[150:151]
	s_add_i32 m0, s55, 0xe000
	s_nop 0
	global_load_lds_dwordx4 v[224:225], off
	s_waitcnt vmcnt(8)
	s_waitcnt lgkmcnt(0)
	s_barrier
	s_waitcnt lgkmcnt(0)
	v_mfma_f32_16x16x32_bf16 v[124:127], v[152:155], v[188:191], v[124:127]
	v_mfma_f32_16x16x32_bf16 v[120:123], v[164:167], v[188:191], v[120:123]
	v_mfma_f32_16x16x32_bf16 v[108:111], v[152:155], v[196:199], v[108:111]
	v_mfma_f32_16x16x32_bf16 v[104:107], v[164:167], v[196:199], v[104:107]
	v_mfma_f32_16x16x32_bf16 v[92:95], v[152:155], v[208:211], v[92:95]
	v_mfma_f32_16x16x32_bf16 v[88:91], v[164:167], v[208:211], v[88:91]
	v_mfma_f32_16x16x32_bf16 v[76:79], v[152:155], v[216:219], v[76:79]
	v_mfma_f32_16x16x32_bf16 v[72:75], v[164:167], v[216:219], v[72:75]
	v_mfma_f32_16x16x32_bf16 v[124:127], v[160:163], v[192:195], v[124:127]
	v_mfma_f32_16x16x32_bf16 v[120:123], v[168:171], v[192:195], v[120:123]
	v_mfma_f32_16x16x32_bf16 v[108:111], v[160:163], v[200:203], v[108:111]
	v_mfma_f32_16x16x32_bf16 v[104:107], v[168:171], v[200:203], v[104:107]
	v_mfma_f32_16x16x32_bf16 v[92:95], v[160:163], v[212:215], v[92:95]
	v_mfma_f32_16x16x32_bf16 v[88:91], v[168:171], v[212:215], v[88:91]
	v_mfma_f32_16x16x32_bf16 v[76:79], v[160:163], v[220:223], v[76:79]
	v_mfma_f32_16x16x32_bf16 v[72:75], v[168:171], v[220:223], v[72:75]
	v_mfma_f32_16x16x32_bf16 v[116:119], v[172:175], v[188:191], v[116:119]
	v_mfma_f32_16x16x32_bf16 v[112:115], v[180:183], v[188:191], v[112:115]
	v_mfma_f32_16x16x32_bf16 v[100:103], v[172:175], v[196:199], v[100:103]
	v_mfma_f32_16x16x32_bf16 v[96:99], v[180:183], v[196:199], v[96:99]
	v_mfma_f32_16x16x32_bf16 v[84:87], v[172:175], v[208:211], v[84:87]
	v_mfma_f32_16x16x32_bf16 v[80:83], v[180:183], v[208:211], v[80:83]
	v_mfma_f32_16x16x32_bf16 v[68:71], v[172:175], v[216:219], v[68:71]
	v_mfma_f32_16x16x32_bf16 v[64:67], v[180:183], v[216:219], v[64:67]
	v_mfma_f32_16x16x32_bf16 v[116:119], v[176:179], v[192:195], v[116:119]
	v_mfma_f32_16x16x32_bf16 v[112:115], v[184:187], v[192:195], v[112:115]
	v_mfma_f32_16x16x32_bf16 v[100:103], v[176:179], v[200:203], v[100:103]
	v_mfma_f32_16x16x32_bf16 v[96:99], v[184:187], v[200:203], v[96:99]
	v_mfma_f32_16x16x32_bf16 v[84:87], v[176:179], v[212:215], v[84:87]
	v_mfma_f32_16x16x32_bf16 v[80:83], v[184:187], v[212:215], v[80:83]
	v_mfma_f32_16x16x32_bf16 v[68:71], v[176:179], v[220:223], v[68:71]
	v_mfma_f32_16x16x32_bf16 v[64:67], v[184:187], v[220:223], v[64:67]
	s_barrier
	s_add_i32 s76, s76, s54
	v_lshl_add_u64 v[224:225], s[26:27], 0, v[132:133]
	s_mov_b32 m0, s76
	ds_read_b128 v[188:191], v159 offset:16384
	ds_read_b128 v[192:195], v159 offset:17408
	ds_read_b128 v[196:199], v159 offset:18432
	ds_read_b128 v[200:203], v159 offset:19456
	ds_read_b128 v[208:211], v159 offset:20480
	ds_read_b128 v[212:215], v159 offset:21504
	ds_read_b128 v[216:219], v159 offset:22528
	ds_read_b128 v[220:223], v159 offset:23552
	global_load_lds_dwordx4 v[224:225], off
	s_add_i32 m0, s76, 0x2000
	s_add_u32 s76, s26, 0x100000
	v_lshl_add_u64 v[226:227], s[26:27], 0, v[128:129]
	s_addc_u32 s77, s27, 0
	s_add_i32 s97, s97, s54
	global_load_lds_dwordx4 v[226:227], off
	v_lshl_add_u64 v[228:229], s[76:77], 0, v[132:133]
	s_mov_b32 m0, s97
	v_lshl_add_u64 v[230:231], s[40:41], 0, v[130:131]
	global_load_lds_dwordx4 v[228:229], off
	v_lshl_add_u64 v[228:229], s[76:77], 0, v[128:129]
	s_add_i32 m0, s97, 0x2000
	s_nop 0
	global_load_lds_dwordx4 v[228:229], off
	v_lshl_add_u64 v[228:229], s[40:41], 0, v[134:135]
	s_mov_b32 m0, s55
	s_nop 0
	global_load_lds_dwordx4 v[228:229], off
	s_mov_b32 m0, s88
	s_nop 0
	global_load_lds_dwordx4 v[230:231], off
	s_waitcnt vmcnt(8)
	s_waitcnt lgkmcnt(0)
	s_barrier
; #define PG8_STAGE(bufoff, gbase, voff) do { _Pragma("unroll") for (int _i = 0; _i < 2; ++_i) \
;         __builtin_amdgcn_global_load_lds((const unsigned*)((const char*)(gbase) + (voff)[_i]), (PG8_LAS unsigned*)(lds + (bufoff) + ldsw + _i * 8192), 16, 0, 0); } while (0)
; #define PG8_LDA(dst, b, h) do { _Pragma("unroll") for (int m = 0; m < 4; ++m) _Pragma("unroll") for (int k = 0; k < 2; ++k) dst[m][k] = *(const PG8_LAS bf16x8*)(lds + PG8_SA(b, h) + aoff + m * 2048 + k * 1024); } while (0)
; #define PG8_LDB(dst, b, h) do { _Pragma("unroll") for (int n = 0; n < 2; ++n) _Pragma("unroll") for (int k = 0; k < 2; ++k) dst[n][k] = *(const PG8_LAS bf16x8*)(lds + PG8_SB(b, h) + boff + n * 2048 + k * 1024); } while (0)
; #define PG8_MMA(ai, bj, At, Bt) do { __builtin_amdgcn_s_setprio(1); _Pragma("unroll") for (int m = 0; m < 4; ++m) _Pragma("unroll") for (int n = 0; n < 2; ++n) _Pragma("unroll") for (int k = 0; k < 2; ++k) \
;         acc[ai][bj][m][n] = __builtin_amdgcn_mfma_f32_16x16x32_bf16(Bt[n][k], At[m][k], acc[ai][bj][m][n], 0, 0, 0); __builtin_amdgcn_s_setprio(0); } while (0)
; #define PG8_WAIT_V(n) asm volatile("s_waitcnt vmcnt(" #n ")" ::: "memory")
; #define PG8_WAIT_L(n) asm volatile("s_waitcnt lgkmcnt(" #n ")" ::: "memory")
; #define PG8_BAR __builtin_amdgcn_s_barrier()
; #define PG8_SCHED __builtin_amdgcn_sched_barrier(0)
; template <class Epi, class Sched, bool ALIGN_EPI = false, bool SP2 = false>
; __device__ __forceinline__ void gemm_phase(PG8_LAS unsigned char* lds, const Gemm g, const Sched& S, const Epi& E) {
;     ...
;             PG8_WAIT_V(8); PG8_WAIT_L(0); PG8_BAR; PG8_MMA(1, 0, At, B0); PG8_MMA(1, 1, At, B1); PG8_BAR; PG8_SCHED;
;             PG8_LDB(B0, 1, 0); PG8_LDB(B1, 1, 1); PG8_SCHED; PG8_LDA(At, 1, 0); PG8_STAGE(PG8_SA(0, 1), a2 + hstep, voffA);
;             PG8_WAIT_V(8); PG8_WAIT_L(0); PG8_BAR; PG8_MMA(0, 0, At, B0); PG8_MMA(0, 1, At, B1); PG8_BAR; PG8_SCHED;
	s_waitcnt lgkmcnt(0)
	v_mfma_f32_16x16x32_bf16 v[60:63], v[152:155], v[188:191], v[60:63]
	v_mfma_f32_16x16x32_bf16 v[56:59], v[164:167], v[188:191], v[56:59]
	v_mfma_f32_16x16x32_bf16 v[44:47], v[152:155], v[196:199], v[44:47]
	v_mfma_f32_16x16x32_bf16 v[40:43], v[164:167], v[196:199], v[40:43]
	v_mfma_f32_16x16x32_bf16 v[28:31], v[152:155], v[208:211], v[28:31]
	v_mfma_f32_16x16x32_bf16 v[24:27], v[164:167], v[208:211], v[24:27]
	v_mfma_f32_16x16x32_bf16 v[12:15], v[152:155], v[216:219], v[12:15]
	v_mfma_f32_16x16x32_bf16 v[8:11], v[164:167], v[216:219], v[8:11]
	v_mfma_f32_16x16x32_bf16 v[60:63], v[160:163], v[192:195], v[60:63]
	v_mfma_f32_16x16x32_bf16 v[56:59], v[168:171], v[192:195], v[56:59]
	v_mfma_f32_16x16x32_bf16 v[44:47], v[160:163], v[200:203], v[44:47]
	v_mfma_f32_16x16x32_bf16 v[40:43], v[168:171], v[200:203], v[40:43]
	v_mfma_f32_16x16x32_bf16 v[28:31], v[160:163], v[212:215], v[28:31]
	v_mfma_f32_16x16x32_bf16 v[24:27], v[168:171], v[212:215], v[24:27]
	v_mfma_f32_16x16x32_bf16 v[12:15], v[160:163], v[220:223], v[12:15]
	v_mfma_f32_16x16x32_bf16 v[8:11], v[168:171], v[220:223], v[8:11]
	v_mfma_f32_16x16x32_bf16 v[52:55], v[172:175], v[188:191], v[52:55]
	v_mfma_f32_16x16x32_bf16 v[48:51], v[180:183], v[188:191], v[48:51]
	v_mfma_f32_16x16x32_bf16 v[36:39], v[172:175], v[196:199], v[36:39]
	v_mfma_f32_16x16x32_bf16 v[32:35], v[180:183], v[196:199], v[32:35]
	v_mfma_f32_16x16x32_bf16 v[20:23], v[172:175], v[208:211], v[20:23]
	v_mfma_f32_16x16x32_bf16 v[16:19], v[180:183], v[208:211], v[16:19]
	v_mfma_f32_16x16x32_bf16 v[4:7], v[172:175], v[216:219], v[4:7]
	v_mfma_f32_16x16x32_bf16 v[0:3], v[180:183], v[216:219], v[0:3]
	v_mfma_f32_16x16x32_bf16 v[52:55], v[176:179], v[192:195], v[52:55]
	v_mfma_f32_16x16x32_bf16 v[48:51], v[184:187], v[192:195], v[48:51]
	v_mfma_f32_16x16x32_bf16 v[36:39], v[176:179], v[200:203], v[36:39]
	v_mfma_f32_16x16x32_bf16 v[32:35], v[184:187], v[200:203], v[32:35]
	v_mfma_f32_16x16x32_bf16 v[20:23], v[176:179], v[212:215], v[20:23]
	v_mfma_f32_16x16x32_bf16 v[16:19], v[184:187], v[212:215], v[16:19]
	v_mfma_f32_16x16x32_bf16 v[4:7], v[176:179], v[220:223], v[4:7]
	v_mfma_f32_16x16x32_bf16 v[0:3], v[184:187], v[220:223], v[0:3]
	s_barrier
	s_add_i32 s76, 0, 0x18000
	v_add_u32_e32 v138, s76, v157
	s_add_i32 s77, 0, 0x1c000
	ds_read_b128 v[152:155], v138
	ds_read_b128 v[160:163], v138 offset:1024
	ds_read_b128 v[164:167], v138 offset:2048
	ds_read_b128 v[168:171], v138 offset:3072
	v_add_u32_e32 v138, s77, v157
	ds_read_b128 v[172:175], v138
	ds_read_b128 v[176:179], v138 offset:1024
	ds_read_b128 v[180:183], v138 offset:2048
	ds_read_b128 v[184:187], v138 offset:3072
	s_add_u32 s40, s40, 0x100000
	s_addc_u32 s41, s41, 0
	s_mov_b32 m0, s89
	v_lshl_add_u64 v[232:233], s[40:41], 0, v[134:135]
	ds_read_b128 v[188:191], v159 offset:32768
	ds_read_b128 v[192:195], v159 offset:33792
	ds_read_b128 v[196:199], v159 offset:34816
	ds_read_b128 v[200:203], v159 offset:35840
	ds_read_b128 v[208:211], v159 offset:36864
	ds_read_b128 v[212:215], v159 offset:37888
	ds_read_b128 v[216:219], v159 offset:38912
	ds_read_b128 v[220:223], v159 offset:39936
	global_load_lds_dwordx4 v[232:233], off
	v_lshl_add_u64 v[232:233], s[40:41], 0, v[130:131]
	s_mov_b32 m0, s30
	s_nop 0
	global_load_lds_dwordx4 v[232:233], off
	s_waitcnt vmcnt(8)
	s_waitcnt lgkmcnt(0)
	s_barrier
	s_waitcnt lgkmcnt(0)
	v_mfma_f32_16x16x32_bf16 v[124:127], v[152:155], v[188:191], v[124:127]
	v_mfma_f32_16x16x32_bf16 v[120:123], v[164:167], v[188:191], v[120:123]
	v_mfma_f32_16x16x32_bf16 v[108:111], v[152:155], v[196:199], v[108:111]
	v_mfma_f32_16x16x32_bf16 v[104:107], v[164:167], v[196:199], v[104:107]
	v_mfma_f32_16x16x32_bf16 v[92:95], v[152:155], v[208:211], v[92:95]
	v_mfma_f32_16x16x32_bf16 v[88:91], v[164:167], v[208:211], v[88:91]
	v_mfma_f32_16x16x32_bf16 v[76:79], v[152:155], v[216:219], v[76:79]
	v_mfma_f32_16x16x32_bf16 v[72:75], v[164:167], v[216:219], v[72:75]
	v_mfma_f32_16x16x32_bf16 v[124:127], v[160:163], v[192:195], v[124:127]
	v_mfma_f32_16x16x32_bf16 v[120:123], v[168:171], v[192:195], v[120:123]
	v_mfma_f32_16x16x32_bf16 v[108:111], v[160:163], v[200:203], v[108:111]
	v_mfma_f32_16x16x32_bf16 v[104:107], v[168:171], v[200:203], v[104:107]
	v_mfma_f32_16x16x32_bf16 v[92:95], v[160:163], v[212:215], v[92:95]
	v_mfma_f32_16x16x32_bf16 v[88:91], v[168:171], v[212:215], v[88:91]
	v_mfma_f32_16x16x32_bf16 v[76:79], v[160:163], v[220:223], v[76:79]
	v_mfma_f32_16x16x32_bf16 v[72:75], v[168:171], v[220:223], v[72:75]
	v_mfma_f32_16x16x32_bf16 v[116:119], v[172:175], v[188:191], v[116:119]
	v_mfma_f32_16x16x32_bf16 v[112:115], v[180:183], v[188:191], v[112:115]
	v_mfma_f32_16x16x32_bf16 v[100:103], v[172:175], v[196:199], v[100:103]
	v_mfma_f32_16x16x32_bf16 v[96:99], v[180:183], v[196:199], v[96:99]
	v_mfma_f32_16x16x32_bf16 v[84:87], v[172:175], v[208:211], v[84:87]
	v_mfma_f32_16x16x32_bf16 v[80:83], v[180:183], v[208:211], v[80:83]
	v_mfma_f32_16x16x32_bf16 v[68:71], v[172:175], v[216:219], v[68:71]
	v_mfma_f32_16x16x32_bf16 v[64:67], v[180:183], v[216:219], v[64:67]
	v_mfma_f32_16x16x32_bf16 v[116:119], v[176:179], v[192:195], v[116:119]
	v_mfma_f32_16x16x32_bf16 v[112:115], v[184:187], v[192:195], v[112:115]
	v_mfma_f32_16x16x32_bf16 v[100:103], v[176:179], v[200:203], v[100:103]
	v_mfma_f32_16x16x32_bf16 v[96:99], v[184:187], v[200:203], v[96:99]
	v_mfma_f32_16x16x32_bf16 v[84:87], v[176:179], v[212:215], v[84:87]
	v_mfma_f32_16x16x32_bf16 v[80:83], v[184:187], v[212:215], v[80:83]
	v_mfma_f32_16x16x32_bf16 v[68:71], v[176:179], v[220:223], v[68:71]
	v_mfma_f32_16x16x32_bf16 v[64:67], v[184:187], v[220:223], v[64:67]
	s_barrier
; #define PG8_STAGE(bufoff, gbase, voff) do { _Pragma("unroll") for (int _i = 0; _i < 2; ++_i) \
;         __builtin_amdgcn_global_load_lds((const unsigned*)((const char*)(gbase) + (voff)[_i]), (PG8_LAS unsigned*)(lds + (bufoff) + ldsw + _i * 8192), 16, 0, 0); } while (0)
;     __device__ __forceinline__ void operator()(const f32x4 (&acc)[2][2][4][2], const Unit& u, int wr, int wc, int fr, int fq) const {
;         const unsigned row0 = u.pm * BM + wr * 64 + fr, col0 = u.pn * BM + wc * 32 + 8 * fq;
;         char* xo = (char*)xout; char* xbp = (char*)xb; char* ssp = (char*)ss;
;         const unsigned ssoff = (unsigned)(u.pn * 4 + wc) * 4u;
; #pragma unroll
;         for (int ai = 0; ai < 2; ++ai)
; #pragma unroll
;             for (int m = 0; m < 4; ++m) {
;                 const unsigned row = row0 + ai * HALF + m * 16;
;                 const unsigned hoff = (row * 1024u + col0) * 2u;
;                 float sq = 0.f;
; #pragma unroll
;                 for (int bj = 0; bj < 2; ++bj) {
;                     const u32x4 xw = *(const u32x4*)(xbp + hoff + bj * (HALF * 2));
;                     f32x4 v0, v1;
;                     v0[0] = __uint_as_float(xw.x << 16) + acc[ai][bj][m][0][0]; v0[1] = __uint_as_float(xw.x & 0xffff0000u) + acc[ai][bj][m][0][1];
;                     v0[2] = __uint_as_float(xw.y << 16) + acc[ai][bj][m][0][2]; v0[3] = __uint_as_float(xw.y & 0xffff0000u) + acc[ai][bj][m][0][3];
;                     v1[0] = __uint_as_float(xw.z << 16) + acc[ai][bj][m][1][0]; v1[1] = __uint_as_float(xw.z & 0xffff0000u) + acc[ai][bj][m][1][1];
;                     v1[2] = __uint_as_float(xw.w << 16) + acc[ai][bj][m][1][2]; v1[3] = __uint_as_float(xw.w & 0xffff0000u) + acc[ai][bj][m][1][3];
;                     if (xout) { *(f32x4*)(xo + 2u * hoff + bj * (HALF * 4)) = v0; *(f32x4*)(xo + 2u * hoff + bj * (HALF * 4) + 16) = v1; }
; template <class Epi, class Sched, bool ALIGN_EPI = false, bool SP2 = false>
; __device__ __forceinline__ void gemm_phase(PG8_LAS unsigned char* lds, const Gemm g, const Sched& S, const Epi& E) {
;     ...
;             PG8_LDA(At, 1, 1); PG8_STAGE(PG8_SB(1, 0), b3, voffB); PG8_STAGE(PG8_SB(1, 1), b3 + hstep, voffB); PG8_STAGE(PG8_SA(1, 0), a3, voffA);
;             PG8_WAIT_V(8); PG8_WAIT_L(0); PG8_BAR; PG8_MMA(1, 0, At, B0); PG8_MMA(1, 1, At, B1); PG8_BAR; PG8_SCHED;
;     ...
;         if constexpr (ALIGN_EPI) { if (wr == 0) PG8_BAR; }
	s_add_i32 s40, s76, s54
	v_lshl_add_u64 v[224:225], v[224:225], 0, s[34:35]
	s_mov_b32 m0, s40
	ds_read_b128 v[188:191], v159 offset:49152
	ds_read_b128 v[192:195], v159 offset:50176
	ds_read_b128 v[196:199], v159 offset:51200
	ds_read_b128 v[200:203], v159 offset:52224
	ds_read_b128 v[208:211], v159 offset:53248
	ds_read_b128 v[212:215], v159 offset:54272
	ds_read_b128 v[216:219], v159 offset:55296
	ds_read_b128 v[220:223], v159 offset:56320
	global_load_lds_dwordx4 v[224:225], off
	s_add_i32 m0, s40, 0x2000
	s_add_u32 s26, s26, 0x100080
	v_lshl_add_u64 v[224:225], v[226:227], 0, s[34:35]
	s_addc_u32 s27, s27, 0
	s_add_i32 s40, s77, s54
	global_load_lds_dwordx4 v[224:225], off
	v_lshl_add_u64 v[224:225], s[26:27], 0, v[132:133]
	s_mov_b32 m0, s40
	s_nop 0
	global_load_lds_dwordx4 v[224:225], off
	v_lshl_add_u64 v[224:225], s[26:27], 0, v[128:129]
	s_add_i32 m0, s40, 0x2000
	s_nop 0
	global_load_lds_dwordx4 v[224:225], off
	v_lshl_add_u64 v[224:225], v[228:229], 0, s[34:35]
	s_mov_b32 m0, s1
	s_nop 0
	global_load_lds_dwordx4 v[224:225], off
	v_lshl_add_u64 v[224:225], v[230:231], 0, s[34:35]
	s_mov_b32 m0, s92
	s_nop 0
	global_load_lds_dwordx4 v[224:225], off
	s_waitcnt vmcnt(8)
	s_waitcnt lgkmcnt(0)
	s_barrier
	s_waitcnt lgkmcnt(0)
	v_mfma_f32_16x16x32_bf16 v[60:63], v[152:155], v[188:191], v[60:63]
	v_mfma_f32_16x16x32_bf16 v[56:59], v[164:167], v[188:191], v[56:59]
	v_mfma_f32_16x16x32_bf16 v[44:47], v[152:155], v[196:199], v[44:47]
	v_mfma_f32_16x16x32_bf16 v[40:43], v[164:167], v[196:199], v[40:43]
	v_mfma_f32_16x16x32_bf16 v[28:31], v[152:155], v[208:211], v[28:31]
	v_mfma_f32_16x16x32_bf16 v[24:27], v[164:167], v[208:211], v[24:27]
	v_mfma_f32_16x16x32_bf16 v[12:15], v[152:155], v[216:219], v[12:15]
	v_mfma_f32_16x16x32_bf16 v[8:11], v[164:167], v[216:219], v[8:11]
	v_mfma_f32_16x16x32_bf16 v[60:63], v[160:163], v[192:195], v[60:63]
	v_mfma_f32_16x16x32_bf16 v[56:59], v[168:171], v[192:195], v[56:59]
	v_mfma_f32_16x16x32_bf16 v[44:47], v[160:163], v[200:203], v[44:47]
	v_mfma_f32_16x16x32_bf16 v[40:43], v[168:171], v[200:203], v[40:43]
	v_mfma_f32_16x16x32_bf16 v[28:31], v[160:163], v[212:215], v[28:31]
	v_mfma_f32_16x16x32_bf16 v[24:27], v[168:171], v[212:215], v[24:27]
	v_mfma_f32_16x16x32_bf16 v[12:15], v[160:163], v[220:223], v[12:15]
	v_mfma_f32_16x16x32_bf16 v[8:11], v[168:171], v[220:223], v[8:11]
	v_mfma_f32_16x16x32_bf16 v[52:55], v[172:175], v[188:191], v[52:55]
	v_mfma_f32_16x16x32_bf16 v[48:51], v[180:183], v[188:191], v[48:51]
	v_mfma_f32_16x16x32_bf16 v[36:39], v[172:175], v[196:199], v[36:39]
	v_mfma_f32_16x16x32_bf16 v[32:35], v[180:183], v[196:199], v[32:35]
	v_mfma_f32_16x16x32_bf16 v[20:23], v[172:175], v[208:211], v[20:23]
	v_mfma_f32_16x16x32_bf16 v[16:19], v[180:183], v[208:211], v[16:19]
	v_mfma_f32_16x16x32_bf16 v[4:7], v[172:175], v[216:219], v[4:7]
	v_mfma_f32_16x16x32_bf16 v[0:3], v[180:183], v[216:219], v[0:3]
	v_mfma_f32_16x16x32_bf16 v[52:55], v[176:179], v[192:195], v[52:55]
	v_mfma_f32_16x16x32_bf16 v[48:51], v[184:187], v[192:195], v[48:51]
	v_mfma_f32_16x16x32_bf16 v[36:39], v[176:179], v[200:203], v[36:39]
	v_mfma_f32_16x16x32_bf16 v[32:35], v[184:187], v[200:203], v[32:35]
	v_mfma_f32_16x16x32_bf16 v[20:23], v[176:179], v[212:215], v[20:23]
	v_mfma_f32_16x16x32_bf16 v[16:19], v[184:187], v[212:215], v[16:19]
	v_mfma_f32_16x16x32_bf16 v[4:7], v[176:179], v[220:223], v[4:7]
	v_mfma_f32_16x16x32_bf16 v[0:3], v[184:187], v[220:223], v[0:3]
	s_barrier
	s_add_i32 s96, s96, 2
	s_add_u32 s24, s24, 0x100
	s_addc_u32 s25, s25, 0
	s_add_u32 s94, s94, 0x100
	s_addc_u32 s95, s95, 0
	s_cmp_gt_u32 s96, 61
	s_cbranch_scc0 .LBB0_1229
	s_and_b64 vcc, exec, s[28:29]
	s_cbranch_vccz .LBB0_1232
	s_barrier
.LBB0_1232:
	s_setprio 0
	v_lshl_add_u32 v160, s53, 8, v156
	v_lshl_or_b32 v161, s52, 9, v158
	v_lshl_add_u32 v154, v160, 11, v161
	v_add_u32_e32 v240, 0x8000, v154
	v_add_u32_e32 v241, 0x10000, v154
	v_add_u32_e32 v242, 0x18000, v154
	v_add_u32_e32 v243, 0x40000, v154
	v_add_u32_e32 v244, 0x48000, v154
	v_add_u32_e32 v245, 0x50000, v154
	v_add_u32_e32 v246, 0x58000, v154
	global_load_dwordx4 v[172:175], v154, s[72:73]
	global_load_dwordx4 v[176:179], v154, s[72:73] offset:256
	global_load_dwordx4 v[180:183], v240, s[72:73]
	global_load_dwordx4 v[184:187], v240, s[72:73] offset:256
	global_load_dwordx4 v[188:191], v241, s[72:73]
	global_load_dwordx4 v[192:195], v241, s[72:73] offset:256
	global_load_dwordx4 v[196:199], v242, s[72:73]
	global_load_dwordx4 v[200:203], v242, s[72:73] offset:256
	global_load_dwordx4 v[208:211], v243, s[72:73]
	global_load_dwordx4 v[212:215], v243, s[72:73] offset:256
	global_load_dwordx4 v[216:219], v244, s[72:73]
	global_load_dwordx4 v[220:223], v244, s[72:73] offset:256
	global_load_dwordx4 v[224:227], v245, s[72:73]
	global_load_dwordx4 v[228:231], v245, s[72:73] offset:256
	global_load_dwordx4 v[232:235], v246, s[72:73]
	global_load_dwordx4 v[236:239], v246, s[72:73] offset:256
	v_lshlrev_b32_e32 v138, 1, v154
	v_lshl_add_u64 v[152:153], s[22:23], 0, v[138:139]
	v_cndmask_b32_e64 v138, 0, 1, s[60:61]
	v_readlane_b32 s96, v250, 25
	v_cmp_ne_u32_e64 s[40:41], 1, v138
	s_andn2_b64 vcc, exec, s[60:61]
	v_readlane_b32 s97, v250, 26
	s_waitcnt vmcnt(15)
	s_nop 1
	v_mov_b32_e32 v162, v172
	v_mov_b32_e32 v163, v173
	v_mov_b32_e32 v164, v174
	v_mov_b32_e32 v165, v175
	v_lshlrev_b32_e32 v166, 16, v162
	v_and_b32_e32 v167, 0xffff0000, v162
	v_lshlrev_b32_e32 v162, 16, v163
	v_and_b32_e32 v163, 0xffff0000, v163
	v_pk_add_f32 v[126:127], v[126:127], v[162:163]
	v_lshlrev_b32_e32 v162, 16, v164
	v_and_b32_e32 v163, 0xffff0000, v164
	v_pk_add_f32 v[120:121], v[120:121], v[162:163]
	v_lshlrev_b32_e32 v162, 16, v165
	v_and_b32_e32 v163, 0xffff0000, v165
	v_pk_add_f32 v[124:125], v[124:125], v[166:167]
	v_pk_add_f32 v[122:123], v[122:123], v[162:163]
	s_cbranch_vccnz .LBB0_1234
	global_store_dwordx4 v[152:153], v[124:127], off
	global_store_dwordx4 v[152:153], v[120:123], off offset:16

; #define PG8_BAR __builtin_amdgcn_s_barrier()
; template <class Epi, class Sched, bool ALIGN_EPI = false, bool SP2 = false>
; __device__ __forceinline__ void gemm_phase(PG8_LAS unsigned char* lds, const Gemm g, const Sched& S, const Epi& E) {
;     ...
;         if (!has_next) break;
; #pragma unroll
;         for (int a = 0; a < 2; ++a)
; #pragma unroll
;             for (int b = 0; b < 2; ++b)
; #pragma unroll
;                 for (int m = 0; m < 4; ++m)
; #pragma unroll
;                     for (int n = 0; n < 2; ++n) acc[a][b][m][n] = (f32x4){0.f, 0.f, 0.f, 0.f};
;         cur = nxt; cA = nA; cB = nB; ++ui;
;         if constexpr (ALIGN_EPI) { if (wr == 1) PG8_BAR; }
.LBB0_1280:
	s_or_b64 exec, exec, s[24:25]
	s_andn2_b64 vcc, exec, s[38:39]
	s_mov_b64 s[24:25], -1
	s_cbranch_vccnz .LBB0_1221
	v_readlane_b32 s24, v250, 32
	v_readlane_b32 s25, v250, 33
	s_andn2_b64 vcc, exec, s[24:25]
	s_cbranch_vccnz .LBB0_1220
	s_setprio 1
	s_barrier
	s_branch .LBB0_1220
